# three register staging sets (prefetch distance 3 k-tiles) in UP GEMM K loops (P4/P9)
# speedup vs baseline: 1.0009x; 1.0009x over previous
.LBB0_338:
	s_lshr_b32 s8, s13, 2
	s_and_b32 s10, s16, 56
	s_and_b32 s8, s8, 0x1ffffc0
	s_or_b32 s10, s10, s3
	s_or_b32 s8, s10, s8
	s_lshl_b32 s8, s8, 7
	s_lshl_b64 s[24:25], s[8:9], 11
	v_lshl_add_u64 v[78:79], v[68:69], 0, s[24:25]
	v_add_co_u32_e32 v80, vcc, s18, v78
	s_and_b32 s10, s14, 0xf80
	s_nop 0
	v_addc_co_u32_e32 v81, vcc, 0, v79, vcc
	s_lshl_b32 s26, s10, 11
	s_mov_b32 s27, s9
	v_add_co_u32_e32 v82, vcc, s19, v78
	v_lshl_add_u64 v[76:77], v[70:71], 0, s[26:27]
	s_nop 0
	v_addc_co_u32_e32 v83, vcc, 0, v79, vcc
	v_add_co_u32_e32 v84, vcc, s18, v76
	global_load_dwordx4 v[2:5], v[78:79], off
	global_load_dwordx4 v[6:9], v[80:81], off
	v_addc_co_u32_e32 v85, vcc, 0, v77, vcc
	v_add_co_u32_e32 v86, vcc, s19, v76
	global_load_dwordx4 v[10:13], v[82:83], off
	global_load_dwordx4 v[14:17], v[76:77], off
	v_addc_co_u32_e32 v87, vcc, 0, v77, vcc
	global_load_dwordx4 v[18:21], v[84:85], off
	global_load_dwordx4 v[22:25], v[86:87], off
	v_add_co_u32_e32 v88, vcc, s20, v76
	s_nop 1
	v_addc_co_u32_e32 v89, vcc, 0, v77, vcc
	global_load_dwordx4 v[26:29], v[88:89], off
	v_add_co_u32_e32 v90, vcc, s20, v78
	s_nop 1
	v_addc_co_u32_e32 v91, vcc, 0, v79, vcc
	global_load_dwordx4 v[30:33], v[90:91], off
	global_load_dwordx4 v[148:151], v[76:77], off offset:128
	global_load_dwordx4 v[152:155], v[84:85], off offset:128
	global_load_dwordx4 v[156:159], v[86:87], off offset:128
	global_load_dwordx4 v[160:163], v[88:89], off offset:128
	global_load_dwordx4 v[164:167], v[78:79], off offset:128
	global_load_dwordx4 v[168:171], v[80:81], off offset:128
	global_load_dwordx4 v[172:175], v[82:83], off offset:128
	global_load_dwordx4 v[176:179], v[90:91], off offset:128
	s_waitcnt vmcnt(12)
	ds_write_b128 v1, v[14:17] offset:36864
	s_waitcnt vmcnt(11)
	ds_write_b128 v1, v[18:21] offset:41472
	s_waitcnt vmcnt(10)
	ds_write_b128 v1, v[22:25] offset:46080
	s_waitcnt vmcnt(9)
	ds_write_b128 v1, v[26:29] offset:50688
	ds_write_b128 v1, v[2:5]
	ds_write_b128 v1, v[6:9] offset:4608
	ds_write_b128 v1, v[10:13] offset:9216
	s_waitcnt vmcnt(8)
	ds_write_b128 v1, v[30:33] offset:13824
	s_waitcnt lgkmcnt(0)
	s_barrier
	global_load_dwordx4 v[200:203], v[80:81], off offset:256
	global_load_dwordx4 v[204:207], v[82:83], off offset:256
	global_load_dwordx4 v[196:199], v[78:79], off offset:256
	global_load_dwordx4 v[180:183], v[76:77], off offset:256
	global_load_dwordx4 v[208:211], v[90:91], off offset:256
	global_load_dwordx4 v[184:187], v[84:85], off offset:256
	global_load_dwordx4 v[188:191], v[86:87], off offset:256
	global_load_dwordx4 v[192:195], v[88:89], off offset:256
	global_load_dwordx4 v[124:127], v[80:81], off offset:384
	global_load_dwordx4 v[128:131], v[82:83], off offset:384
	global_load_dwordx4 v[120:123], v[78:79], off offset:384
	global_load_dwordx4 v[104:107], v[76:77], off offset:384
	global_load_dwordx4 v[240:243], v[90:91], off offset:384
	global_load_dwordx4 v[108:111], v[84:85], off offset:384
	global_load_dwordx4 v[112:115], v[86:87], off offset:384
	global_load_dwordx4 v[116:119], v[88:89], off offset:384
	ds_read_b128 v[18:21], v72
	ds_read_b128 v[34:37], v73 offset:36864
	ds_read_b128 v[212:215], v72 offset:32
	ds_read_b128 v[216:219], v73 offset:36896
	ds_read_b128 v[50:53], v73 offset:41472
	ds_read_b128 v[220:223], v73 offset:41504
	ds_read_b128 v[54:57], v72 offset:4608
	ds_read_b128 v[224:227], v72 offset:4640
	s_waitcnt lgkmcnt(6)
	v_mfma_f32_32x32x16_bf16 v[2:17], v[18:21], v[34:37], 0
	s_waitcnt lgkmcnt(3)
	v_mfma_f32_32x32x16_bf16 v[18:33], v[18:21], v[50:53], 0
	s_waitcnt lgkmcnt(1)
	v_mfma_f32_32x32x16_bf16 v[34:49], v[54:57], v[34:37], 0
	v_mfma_f32_32x32x16_bf16 v[50:65], v[54:57], v[50:53], 0
	v_mfma_f32_32x32x16_bf16 v[2:17], v[212:215], v[216:219], v[2:17]
	v_mfma_f32_32x32x16_bf16 v[18:33], v[212:215], v[220:223], v[18:33]
	s_waitcnt lgkmcnt(0)
	v_mfma_f32_32x32x16_bf16 v[34:49], v[224:227], v[216:219], v[34:49]
	v_mfma_f32_32x32x16_bf16 v[50:65], v[224:227], v[220:223], v[50:65]
	ds_read_b128 v[212:215], v72 offset:64
	ds_read_b128 v[216:219], v73 offset:36928
	ds_read_b128 v[220:223], v72 offset:96
	ds_read_b128 v[224:227], v73 offset:36960
	ds_read_b128 v[228:231], v73 offset:41536
	ds_read_b128 v[232:235], v73 offset:41568
	s_waitcnt lgkmcnt(4)
	v_mfma_f32_32x32x16_bf16 v[2:17], v[212:215], v[216:219], v[2:17]
	s_waitcnt lgkmcnt(1)
	v_mfma_f32_32x32x16_bf16 v[18:33], v[212:215], v[228:231], v[18:33]
	ds_read_b128 v[212:215], v72 offset:4672
	ds_read_b128 v[236:239], v72 offset:4704
	s_waitcnt vmcnt(16)
	ds_write_b128 v1, v[164:167] offset:18432
	ds_write_b128 v1, v[168:171] offset:23040
	ds_write_b128 v1, v[172:175] offset:27648
	ds_write_b128 v1, v[176:179] offset:32256
	ds_write_b128 v1, v[148:151] offset:55296
	ds_write_b128 v1, v[152:155] offset:59904
	ds_write_b128 v1, v[156:159] offset:64512
	ds_write_b128 v92, v[160:163] offset:32256
	global_load_dwordx4 v[168:171], v[80:81], off offset:512
	global_load_dwordx4 v[172:175], v[82:83], off offset:512
	global_load_dwordx4 v[164:167], v[78:79], off offset:512
	global_load_dwordx4 v[148:151], v[76:77], off offset:512
	global_load_dwordx4 v[176:179], v[90:91], off offset:512
	global_load_dwordx4 v[152:155], v[84:85], off offset:512
	global_load_dwordx4 v[156:159], v[86:87], off offset:512
	global_load_dwordx4 v[160:163], v[88:89], off offset:512
	s_waitcnt lgkmcnt(0)
	s_barrier
	v_mfma_f32_32x32x16_bf16 v[34:49], v[212:215], v[216:219], v[34:49]
	v_mfma_f32_32x32x16_bf16 v[50:65], v[212:215], v[228:231], v[50:65]
	v_mfma_f32_32x32x16_bf16 v[2:17], v[220:223], v[224:227], v[2:17]
	v_mfma_f32_32x32x16_bf16 v[18:33], v[220:223], v[232:235], v[18:33]
	v_mfma_f32_32x32x16_bf16 v[34:49], v[236:239], v[224:227], v[34:49]
	v_mfma_f32_32x32x16_bf16 v[50:65], v[236:239], v[232:235], v[50:65]
	ds_read_b128 v[212:215], v72 offset:18432
	ds_read_b128 v[216:219], v73 offset:55296
	ds_read_b128 v[220:223], v72 offset:18464
	ds_read_b128 v[224:227], v73 offset:55328
	ds_read_b128 v[228:231], v73 offset:59904
	ds_read_b128 v[232:235], v73 offset:59936
	s_waitcnt lgkmcnt(4)
	v_mfma_f32_32x32x16_bf16 v[2:17], v[212:215], v[216:219], v[2:17]
	s_waitcnt lgkmcnt(1)
	v_mfma_f32_32x32x16_bf16 v[18:33], v[212:215], v[228:231], v[18:33]
	ds_read_b128 v[212:215], v72 offset:23040
	ds_read_b128 v[236:239], v72 offset:23072
	s_waitcnt lgkmcnt(1)
	v_mfma_f32_32x32x16_bf16 v[34:49], v[212:215], v[216:219], v[34:49]
	v_mfma_f32_32x32x16_bf16 v[50:65], v[212:215], v[228:231], v[50:65]
	v_mfma_f32_32x32x16_bf16 v[2:17], v[220:223], v[224:227], v[2:17]
	v_mfma_f32_32x32x16_bf16 v[18:33], v[220:223], v[232:235], v[18:33]
	s_waitcnt lgkmcnt(0)
	v_mfma_f32_32x32x16_bf16 v[34:49], v[236:239], v[224:227], v[34:49]
	ds_read_b128 v[212:215], v72 offset:18496
	ds_read_b128 v[216:219], v73 offset:55360
	ds_read_b128 v[220:223], v72 offset:18528
	ds_read_b128 v[224:227], v73 offset:55392
	v_mfma_f32_32x32x16_bf16 v[50:65], v[236:239], v[232:235], v[50:65]
	ds_read_b128 v[228:231], v73 offset:59968
	ds_read_b128 v[232:235], v73 offset:60000
	s_waitcnt lgkmcnt(4)
	v_mfma_f32_32x32x16_bf16 v[2:17], v[212:215], v[216:219], v[2:17]
	s_waitcnt lgkmcnt(1)
	v_mfma_f32_32x32x16_bf16 v[18:33], v[212:215], v[228:231], v[18:33]
	ds_read_b128 v[212:215], v72 offset:23104
	ds_read_b128 v[236:239], v72 offset:23136
	s_waitcnt vmcnt(16)
	ds_write_b128 v1, v[196:199]
	ds_write_b128 v1, v[200:203] offset:4608
	ds_write_b128 v1, v[204:207] offset:9216
	ds_write_b128 v1, v[208:211] offset:13824
	ds_write_b128 v1, v[180:183] offset:36864
	ds_write_b128 v1, v[184:187] offset:41472
	ds_write_b128 v1, v[188:191] offset:46080
	ds_write_b128 v1, v[192:195] offset:50688
	global_load_dwordx4 v[200:203], v[80:81], off offset:640
	global_load_dwordx4 v[204:207], v[82:83], off offset:640
	global_load_dwordx4 v[196:199], v[78:79], off offset:640
	global_load_dwordx4 v[180:183], v[76:77], off offset:640
	global_load_dwordx4 v[208:211], v[90:91], off offset:640
	global_load_dwordx4 v[184:187], v[84:85], off offset:640
	global_load_dwordx4 v[188:191], v[86:87], off offset:640
	global_load_dwordx4 v[192:195], v[88:89], off offset:640
	s_waitcnt lgkmcnt(0)
	s_barrier
	v_mfma_f32_32x32x16_bf16 v[34:49], v[212:215], v[216:219], v[34:49]
	v_mfma_f32_32x32x16_bf16 v[50:65], v[212:215], v[228:231], v[50:65]
	v_mfma_f32_32x32x16_bf16 v[2:17], v[220:223], v[224:227], v[2:17]
	v_mfma_f32_32x32x16_bf16 v[18:33], v[220:223], v[232:235], v[18:33]
	v_mfma_f32_32x32x16_bf16 v[34:49], v[236:239], v[224:227], v[34:49]
	v_mfma_f32_32x32x16_bf16 v[50:65], v[236:239], v[232:235], v[50:65]
	ds_read_b128 v[212:215], v72
	ds_read_b128 v[216:219], v73 offset:36864
	ds_read_b128 v[220:223], v72 offset:32
	ds_read_b128 v[224:227], v73 offset:36896
	ds_read_b128 v[228:231], v73 offset:41472
	ds_read_b128 v[232:235], v73 offset:41504
	s_waitcnt lgkmcnt(4)
	v_mfma_f32_32x32x16_bf16 v[2:17], v[212:215], v[216:219], v[2:17]
	s_waitcnt lgkmcnt(1)
	v_mfma_f32_32x32x16_bf16 v[18:33], v[212:215], v[228:231], v[18:33]
	ds_read_b128 v[212:215], v72 offset:4608
	ds_read_b128 v[236:239], v72 offset:4640
	s_waitcnt lgkmcnt(1)
	v_mfma_f32_32x32x16_bf16 v[34:49], v[212:215], v[216:219], v[34:49]
	v_mfma_f32_32x32x16_bf16 v[50:65], v[212:215], v[228:231], v[50:65]
	v_mfma_f32_32x32x16_bf16 v[2:17], v[220:223], v[224:227], v[2:17]
	v_mfma_f32_32x32x16_bf16 v[18:33], v[220:223], v[232:235], v[18:33]
	s_waitcnt lgkmcnt(0)
	v_mfma_f32_32x32x16_bf16 v[34:49], v[236:239], v[224:227], v[34:49]
	ds_read_b128 v[212:215], v72 offset:64
	ds_read_b128 v[216:219], v73 offset:36928
	ds_read_b128 v[220:223], v72 offset:96
	ds_read_b128 v[224:227], v73 offset:36960
	v_mfma_f32_32x32x16_bf16 v[50:65], v[236:239], v[232:235], v[50:65]
	ds_read_b128 v[228:231], v73 offset:41536
	ds_read_b128 v[232:235], v73 offset:41568
	s_waitcnt lgkmcnt(4)
	v_mfma_f32_32x32x16_bf16 v[2:17], v[212:215], v[216:219], v[2:17]
	s_waitcnt lgkmcnt(1)
	v_mfma_f32_32x32x16_bf16 v[18:33], v[212:215], v[228:231], v[18:33]
	ds_read_b128 v[212:215], v72 offset:4672
	ds_read_b128 v[236:239], v72 offset:4704
	s_waitcnt vmcnt(16)
	ds_write_b128 v1, v[120:123] offset:18432
	ds_write_b128 v1, v[124:127] offset:23040
	ds_write_b128 v1, v[128:131] offset:27648
	ds_write_b128 v1, v[240:243] offset:32256
	ds_write_b128 v1, v[104:107] offset:55296
	ds_write_b128 v1, v[108:111] offset:59904
	ds_write_b128 v1, v[112:115] offset:64512
	ds_write_b128 v92, v[116:119] offset:32256
	global_load_dwordx4 v[124:127], v[80:81], off offset:768
	global_load_dwordx4 v[128:131], v[82:83], off offset:768
	global_load_dwordx4 v[120:123], v[78:79], off offset:768
	global_load_dwordx4 v[104:107], v[76:77], off offset:768
	global_load_dwordx4 v[240:243], v[90:91], off offset:768
	global_load_dwordx4 v[108:111], v[84:85], off offset:768
	global_load_dwordx4 v[112:115], v[86:87], off offset:768
	global_load_dwordx4 v[116:119], v[88:89], off offset:768
	s_waitcnt lgkmcnt(0)
	s_barrier
	v_mfma_f32_32x32x16_bf16 v[34:49], v[212:215], v[216:219], v[34:49]
	v_mfma_f32_32x32x16_bf16 v[50:65], v[212:215], v[228:231], v[50:65]
	v_mfma_f32_32x32x16_bf16 v[2:17], v[220:223], v[224:227], v[2:17]
	v_mfma_f32_32x32x16_bf16 v[18:33], v[220:223], v[232:235], v[18:33]
	v_mfma_f32_32x32x16_bf16 v[34:49], v[236:239], v[224:227], v[34:49]
	v_mfma_f32_32x32x16_bf16 v[50:65], v[236:239], v[232:235], v[50:65]
	ds_read_b128 v[212:215], v72 offset:18432
	ds_read_b128 v[216:219], v73 offset:55296
	ds_read_b128 v[220:223], v72 offset:18464
	ds_read_b128 v[224:227], v73 offset:55328
	ds_read_b128 v[228:231], v73 offset:59904
	ds_read_b128 v[232:235], v73 offset:59936
	s_waitcnt lgkmcnt(4)
	v_mfma_f32_32x32x16_bf16 v[2:17], v[212:215], v[216:219], v[2:17]
	s_waitcnt lgkmcnt(1)
	v_mfma_f32_32x32x16_bf16 v[18:33], v[212:215], v[228:231], v[18:33]
	ds_read_b128 v[212:215], v72 offset:23040
	ds_read_b128 v[236:239], v72 offset:23072
	s_waitcnt lgkmcnt(1)
	v_mfma_f32_32x32x16_bf16 v[34:49], v[212:215], v[216:219], v[34:49]
	v_mfma_f32_32x32x16_bf16 v[50:65], v[212:215], v[228:231], v[50:65]
	v_mfma_f32_32x32x16_bf16 v[2:17], v[220:223], v[224:227], v[2:17]
	v_mfma_f32_32x32x16_bf16 v[18:33], v[220:223], v[232:235], v[18:33]
	s_waitcnt lgkmcnt(0)
	v_mfma_f32_32x32x16_bf16 v[34:49], v[236:239], v[224:227], v[34:49]
	ds_read_b128 v[212:215], v72 offset:18496
	ds_read_b128 v[216:219], v73 offset:55360
	ds_read_b128 v[220:223], v72 offset:18528
	ds_read_b128 v[224:227], v73 offset:55392
	v_mfma_f32_32x32x16_bf16 v[50:65], v[236:239], v[232:235], v[50:65]
	ds_read_b128 v[228:231], v73 offset:59968
	ds_read_b128 v[232:235], v73 offset:60000
	s_waitcnt lgkmcnt(4)
	v_mfma_f32_32x32x16_bf16 v[2:17], v[212:215], v[216:219], v[2:17]
	s_waitcnt lgkmcnt(1)
	v_mfma_f32_32x32x16_bf16 v[18:33], v[212:215], v[228:231], v[18:33]
	ds_read_b128 v[212:215], v72 offset:23104
	ds_read_b128 v[236:239], v72 offset:23136
	s_waitcnt vmcnt(16)
	ds_write_b128 v1, v[164:167]
	ds_write_b128 v1, v[168:171] offset:4608
	ds_write_b128 v1, v[172:175] offset:9216
	ds_write_b128 v1, v[176:179] offset:13824
	ds_write_b128 v1, v[148:151] offset:36864
	ds_write_b128 v1, v[152:155] offset:41472
	ds_write_b128 v1, v[156:159] offset:46080
	ds_write_b128 v1, v[160:163] offset:50688
	global_load_dwordx4 v[168:171], v[80:81], off offset:896
	global_load_dwordx4 v[172:175], v[82:83], off offset:896
	global_load_dwordx4 v[164:167], v[78:79], off offset:896
	global_load_dwordx4 v[148:151], v[76:77], off offset:896
	global_load_dwordx4 v[176:179], v[90:91], off offset:896
	global_load_dwordx4 v[152:155], v[84:85], off offset:896
	global_load_dwordx4 v[156:159], v[86:87], off offset:896
	global_load_dwordx4 v[160:163], v[88:89], off offset:896
	s_waitcnt lgkmcnt(0)
	s_barrier
	v_mfma_f32_32x32x16_bf16 v[34:49], v[212:215], v[216:219], v[34:49]
	v_mfma_f32_32x32x16_bf16 v[50:65], v[212:215], v[228:231], v[50:65]
	v_mfma_f32_32x32x16_bf16 v[2:17], v[220:223], v[224:227], v[2:17]
	v_mfma_f32_32x32x16_bf16 v[18:33], v[220:223], v[232:235], v[18:33]
	v_mfma_f32_32x32x16_bf16 v[34:49], v[236:239], v[224:227], v[34:49]
	v_mfma_f32_32x32x16_bf16 v[50:65], v[236:239], v[232:235], v[50:65]
	ds_read_b128 v[212:215], v72
	ds_read_b128 v[216:219], v73 offset:36864
	ds_read_b128 v[220:223], v72 offset:32
	ds_read_b128 v[224:227], v73 offset:36896
	ds_read_b128 v[228:231], v73 offset:41472
	ds_read_b128 v[232:235], v73 offset:41504
	s_waitcnt lgkmcnt(4)
	v_mfma_f32_32x32x16_bf16 v[2:17], v[212:215], v[216:219], v[2:17]
	s_waitcnt lgkmcnt(1)
	v_mfma_f32_32x32x16_bf16 v[18:33], v[212:215], v[228:231], v[18:33]
	ds_read_b128 v[212:215], v72 offset:4608
	ds_read_b128 v[236:239], v72 offset:4640
	s_waitcnt lgkmcnt(1)
	v_mfma_f32_32x32x16_bf16 v[34:49], v[212:215], v[216:219], v[34:49]
	v_mfma_f32_32x32x16_bf16 v[50:65], v[212:215], v[228:231], v[50:65]
	v_mfma_f32_32x32x16_bf16 v[2:17], v[220:223], v[224:227], v[2:17]
	v_mfma_f32_32x32x16_bf16 v[18:33], v[220:223], v[232:235], v[18:33]
	s_waitcnt lgkmcnt(0)
	v_mfma_f32_32x32x16_bf16 v[34:49], v[236:239], v[224:227], v[34:49]
	ds_read_b128 v[212:215], v72 offset:64
	ds_read_b128 v[216:219], v73 offset:36928
	ds_read_b128 v[220:223], v72 offset:96
	ds_read_b128 v[224:227], v73 offset:36960
	v_mfma_f32_32x32x16_bf16 v[50:65], v[236:239], v[232:235], v[50:65]
	ds_read_b128 v[228:231], v73 offset:41536
	ds_read_b128 v[232:235], v73 offset:41568
	s_waitcnt lgkmcnt(4)
	v_mfma_f32_32x32x16_bf16 v[2:17], v[212:215], v[216:219], v[2:17]
	s_waitcnt lgkmcnt(1)
	v_mfma_f32_32x32x16_bf16 v[18:33], v[212:215], v[228:231], v[18:33]
	ds_read_b128 v[212:215], v72 offset:4672
	ds_read_b128 v[236:239], v72 offset:4704
	s_waitcnt vmcnt(16)
	ds_write_b128 v1, v[196:199] offset:18432
	ds_write_b128 v1, v[200:203] offset:23040
	ds_write_b128 v1, v[204:207] offset:27648
	ds_write_b128 v1, v[208:211] offset:32256
	ds_write_b128 v1, v[180:183] offset:55296
	ds_write_b128 v1, v[184:187] offset:59904
	ds_write_b128 v1, v[188:191] offset:64512
	ds_write_b128 v92, v[192:195] offset:32256
	global_load_dwordx4 v[200:203], v[80:81], off offset:1024
	global_load_dwordx4 v[204:207], v[82:83], off offset:1024
	global_load_dwordx4 v[196:199], v[78:79], off offset:1024
	global_load_dwordx4 v[180:183], v[76:77], off offset:1024
	global_load_dwordx4 v[208:211], v[90:91], off offset:1024
	global_load_dwordx4 v[184:187], v[84:85], off offset:1024
	global_load_dwordx4 v[188:191], v[86:87], off offset:1024
	global_load_dwordx4 v[192:195], v[88:89], off offset:1024
	s_waitcnt lgkmcnt(0)
	s_barrier
	v_mfma_f32_32x32x16_bf16 v[34:49], v[212:215], v[216:219], v[34:49]
	v_mfma_f32_32x32x16_bf16 v[50:65], v[212:215], v[228:231], v[50:65]
	v_mfma_f32_32x32x16_bf16 v[2:17], v[220:223], v[224:227], v[2:17]
	v_mfma_f32_32x32x16_bf16 v[18:33], v[220:223], v[232:235], v[18:33]
	v_mfma_f32_32x32x16_bf16 v[34:49], v[236:239], v[224:227], v[34:49]
	v_mfma_f32_32x32x16_bf16 v[50:65], v[236:239], v[232:235], v[50:65]
	ds_read_b128 v[212:215], v72 offset:18432
	ds_read_b128 v[216:219], v73 offset:55296
	ds_read_b128 v[220:223], v72 offset:18464
	ds_read_b128 v[224:227], v73 offset:55328
	ds_read_b128 v[228:231], v73 offset:59904
	ds_read_b128 v[232:235], v73 offset:59936
	s_waitcnt lgkmcnt(4)
	v_mfma_f32_32x32x16_bf16 v[2:17], v[212:215], v[216:219], v[2:17]
	s_waitcnt lgkmcnt(1)
	v_mfma_f32_32x32x16_bf16 v[18:33], v[212:215], v[228:231], v[18:33]
	ds_read_b128 v[212:215], v72 offset:23040
	ds_read_b128 v[236:239], v72 offset:23072
	s_waitcnt lgkmcnt(1)
	v_mfma_f32_32x32x16_bf16 v[34:49], v[212:215], v[216:219], v[34:49]
	v_mfma_f32_32x32x16_bf16 v[50:65], v[212:215], v[228:231], v[50:65]
	v_mfma_f32_32x32x16_bf16 v[2:17], v[220:223], v[224:227], v[2:17]
	v_mfma_f32_32x32x16_bf16 v[18:33], v[220:223], v[232:235], v[18:33]
	s_waitcnt lgkmcnt(0)
	v_mfma_f32_32x32x16_bf16 v[34:49], v[236:239], v[224:227], v[34:49]
	ds_read_b128 v[212:215], v72 offset:18496
	ds_read_b128 v[216:219], v73 offset:55360
	ds_read_b128 v[220:223], v72 offset:18528
	ds_read_b128 v[224:227], v73 offset:55392
	v_mfma_f32_32x32x16_bf16 v[50:65], v[236:239], v[232:235], v[50:65]
	ds_read_b128 v[228:231], v73 offset:59968
	ds_read_b128 v[232:235], v73 offset:60000
	s_waitcnt lgkmcnt(4)
	v_mfma_f32_32x32x16_bf16 v[2:17], v[212:215], v[216:219], v[2:17]
	s_waitcnt lgkmcnt(1)
	v_mfma_f32_32x32x16_bf16 v[18:33], v[212:215], v[228:231], v[18:33]
	ds_read_b128 v[212:215], v72 offset:23104
	ds_read_b128 v[236:239], v72 offset:23136
	s_waitcnt vmcnt(16)
	ds_write_b128 v1, v[120:123]
	ds_write_b128 v1, v[124:127] offset:4608
	ds_write_b128 v1, v[128:131] offset:9216
	ds_write_b128 v1, v[240:243] offset:13824
	ds_write_b128 v1, v[104:107] offset:36864
	ds_write_b128 v1, v[108:111] offset:41472
	ds_write_b128 v1, v[112:115] offset:46080
	ds_write_b128 v1, v[116:119] offset:50688
	global_load_dwordx4 v[124:127], v[80:81], off offset:1152
	global_load_dwordx4 v[128:131], v[82:83], off offset:1152
	global_load_dwordx4 v[120:123], v[78:79], off offset:1152
	global_load_dwordx4 v[104:107], v[76:77], off offset:1152
	global_load_dwordx4 v[240:243], v[90:91], off offset:1152
	global_load_dwordx4 v[108:111], v[84:85], off offset:1152
	global_load_dwordx4 v[112:115], v[86:87], off offset:1152
	global_load_dwordx4 v[116:119], v[88:89], off offset:1152
	s_waitcnt lgkmcnt(0)
	s_barrier
	v_mfma_f32_32x32x16_bf16 v[34:49], v[212:215], v[216:219], v[34:49]
	v_mfma_f32_32x32x16_bf16 v[50:65], v[212:215], v[228:231], v[50:65]
	v_mfma_f32_32x32x16_bf16 v[2:17], v[220:223], v[224:227], v[2:17]
	v_mfma_f32_32x32x16_bf16 v[18:33], v[220:223], v[232:235], v[18:33]
	v_mfma_f32_32x32x16_bf16 v[34:49], v[236:239], v[224:227], v[34:49]
	v_mfma_f32_32x32x16_bf16 v[50:65], v[236:239], v[232:235], v[50:65]
	ds_read_b128 v[212:215], v72
	ds_read_b128 v[216:219], v73 offset:36864
	ds_read_b128 v[220:223], v72 offset:32
	ds_read_b128 v[224:227], v73 offset:36896
	ds_read_b128 v[228:231], v73 offset:41472
	ds_read_b128 v[232:235], v73 offset:41504
	s_waitcnt lgkmcnt(4)
	v_mfma_f32_32x32x16_bf16 v[2:17], v[212:215], v[216:219], v[2:17]
	s_waitcnt lgkmcnt(1)
	v_mfma_f32_32x32x16_bf16 v[18:33], v[212:215], v[228:231], v[18:33]
	ds_read_b128 v[212:215], v72 offset:4608
	ds_read_b128 v[236:239], v72 offset:4640
	s_waitcnt lgkmcnt(1)
	v_mfma_f32_32x32x16_bf16 v[34:49], v[212:215], v[216:219], v[34:49]
	v_mfma_f32_32x32x16_bf16 v[50:65], v[212:215], v[228:231], v[50:65]
	v_mfma_f32_32x32x16_bf16 v[2:17], v[220:223], v[224:227], v[2:17]
	v_mfma_f32_32x32x16_bf16 v[18:33], v[220:223], v[232:235], v[18:33]
	s_waitcnt lgkmcnt(0)
	v_mfma_f32_32x32x16_bf16 v[34:49], v[236:239], v[224:227], v[34:49]
	ds_read_b128 v[212:215], v72 offset:64
	ds_read_b128 v[216:219], v73 offset:36928
	ds_read_b128 v[220:223], v72 offset:96
	ds_read_b128 v[224:227], v73 offset:36960
	v_mfma_f32_32x32x16_bf16 v[50:65], v[236:239], v[232:235], v[50:65]
	ds_read_b128 v[228:231], v73 offset:41536
	ds_read_b128 v[232:235], v73 offset:41568
	s_waitcnt lgkmcnt(4)
	v_mfma_f32_32x32x16_bf16 v[2:17], v[212:215], v[216:219], v[2:17]
	s_waitcnt lgkmcnt(1)
	v_mfma_f32_32x32x16_bf16 v[18:33], v[212:215], v[228:231], v[18:33]
	ds_read_b128 v[212:215], v72 offset:4672
	ds_read_b128 v[236:239], v72 offset:4704
	s_waitcnt vmcnt(16)
	ds_write_b128 v1, v[164:167] offset:18432
	ds_write_b128 v1, v[168:171] offset:23040
	ds_write_b128 v1, v[172:175] offset:27648
	ds_write_b128 v1, v[176:179] offset:32256
	ds_write_b128 v1, v[148:151] offset:55296
	ds_write_b128 v1, v[152:155] offset:59904
	ds_write_b128 v1, v[156:159] offset:64512
	ds_write_b128 v92, v[160:163] offset:32256
	global_load_dwordx4 v[168:171], v[80:81], off offset:1280
	global_load_dwordx4 v[172:175], v[82:83], off offset:1280
	global_load_dwordx4 v[164:167], v[78:79], off offset:1280
	global_load_dwordx4 v[148:151], v[76:77], off offset:1280
	global_load_dwordx4 v[176:179], v[90:91], off offset:1280
	global_load_dwordx4 v[152:155], v[84:85], off offset:1280
	global_load_dwordx4 v[156:159], v[86:87], off offset:1280
	global_load_dwordx4 v[160:163], v[88:89], off offset:1280
	s_waitcnt lgkmcnt(0)
	s_barrier
	v_mfma_f32_32x32x16_bf16 v[34:49], v[212:215], v[216:219], v[34:49]
	v_mfma_f32_32x32x16_bf16 v[50:65], v[212:215], v[228:231], v[50:65]
	v_mfma_f32_32x32x16_bf16 v[2:17], v[220:223], v[224:227], v[2:17]
	v_mfma_f32_32x32x16_bf16 v[18:33], v[220:223], v[232:235], v[18:33]
	v_mfma_f32_32x32x16_bf16 v[34:49], v[236:239], v[224:227], v[34:49]
	v_mfma_f32_32x32x16_bf16 v[50:65], v[236:239], v[232:235], v[50:65]
	ds_read_b128 v[212:215], v72 offset:18432
	ds_read_b128 v[216:219], v73 offset:55296
	ds_read_b128 v[220:223], v72 offset:18464
	ds_read_b128 v[224:227], v73 offset:55328
	ds_read_b128 v[228:231], v73 offset:59904
	ds_read_b128 v[232:235], v73 offset:59936
	s_waitcnt lgkmcnt(4)
	v_mfma_f32_32x32x16_bf16 v[2:17], v[212:215], v[216:219], v[2:17]
	s_waitcnt lgkmcnt(1)
	v_mfma_f32_32x32x16_bf16 v[18:33], v[212:215], v[228:231], v[18:33]
	ds_read_b128 v[212:215], v72 offset:23040
	ds_read_b128 v[236:239], v72 offset:23072
	s_waitcnt lgkmcnt(1)
	v_mfma_f32_32x32x16_bf16 v[34:49], v[212:215], v[216:219], v[34:49]
	v_mfma_f32_32x32x16_bf16 v[50:65], v[212:215], v[228:231], v[50:65]
	v_mfma_f32_32x32x16_bf16 v[2:17], v[220:223], v[224:227], v[2:17]
	v_mfma_f32_32x32x16_bf16 v[18:33], v[220:223], v[232:235], v[18:33]
	s_waitcnt lgkmcnt(0)
	v_mfma_f32_32x32x16_bf16 v[34:49], v[236:239], v[224:227], v[34:49]
	ds_read_b128 v[212:215], v72 offset:18496
	ds_read_b128 v[216:219], v73 offset:55360
	ds_read_b128 v[220:223], v72 offset:18528
	ds_read_b128 v[224:227], v73 offset:55392
	v_mfma_f32_32x32x16_bf16 v[50:65], v[236:239], v[232:235], v[50:65]
	ds_read_b128 v[228:231], v73 offset:59968
	ds_read_b128 v[232:235], v73 offset:60000
	s_waitcnt lgkmcnt(4)
	v_mfma_f32_32x32x16_bf16 v[2:17], v[212:215], v[216:219], v[2:17]
	s_waitcnt lgkmcnt(1)
	v_mfma_f32_32x32x16_bf16 v[18:33], v[212:215], v[228:231], v[18:33]
	ds_read_b128 v[212:215], v72 offset:23104
	ds_read_b128 v[236:239], v72 offset:23136
	s_waitcnt vmcnt(16)
	ds_write_b128 v1, v[196:199]
	ds_write_b128 v1, v[200:203] offset:4608
	ds_write_b128 v1, v[204:207] offset:9216
	ds_write_b128 v1, v[208:211] offset:13824
	ds_write_b128 v1, v[180:183] offset:36864
	ds_write_b128 v1, v[184:187] offset:41472
	ds_write_b128 v1, v[188:191] offset:46080
	ds_write_b128 v1, v[192:195] offset:50688
	global_load_dwordx4 v[200:203], v[80:81], off offset:1408
	global_load_dwordx4 v[204:207], v[82:83], off offset:1408
	global_load_dwordx4 v[196:199], v[78:79], off offset:1408
	global_load_dwordx4 v[180:183], v[76:77], off offset:1408
	global_load_dwordx4 v[208:211], v[90:91], off offset:1408
	global_load_dwordx4 v[184:187], v[84:85], off offset:1408
	global_load_dwordx4 v[188:191], v[86:87], off offset:1408
	global_load_dwordx4 v[192:195], v[88:89], off offset:1408
	s_waitcnt lgkmcnt(0)
	s_barrier
	v_mfma_f32_32x32x16_bf16 v[34:49], v[212:215], v[216:219], v[34:49]
	v_mfma_f32_32x32x16_bf16 v[50:65], v[212:215], v[228:231], v[50:65]
	v_mfma_f32_32x32x16_bf16 v[2:17], v[220:223], v[224:227], v[2:17]
	v_mfma_f32_32x32x16_bf16 v[18:33], v[220:223], v[232:235], v[18:33]
	v_mfma_f32_32x32x16_bf16 v[34:49], v[236:239], v[224:227], v[34:49]
	v_mfma_f32_32x32x16_bf16 v[50:65], v[236:239], v[232:235], v[50:65]
	ds_read_b128 v[212:215], v72
	ds_read_b128 v[216:219], v73 offset:36864
	ds_read_b128 v[220:223], v72 offset:32
	ds_read_b128 v[224:227], v73 offset:36896
	ds_read_b128 v[228:231], v73 offset:41472
	ds_read_b128 v[232:235], v73 offset:41504
	s_waitcnt lgkmcnt(4)
	v_mfma_f32_32x32x16_bf16 v[2:17], v[212:215], v[216:219], v[2:17]
	s_waitcnt lgkmcnt(1)
	v_mfma_f32_32x32x16_bf16 v[18:33], v[212:215], v[228:231], v[18:33]
	ds_read_b128 v[212:215], v72 offset:4608
	ds_read_b128 v[236:239], v72 offset:4640
	s_waitcnt lgkmcnt(1)
	v_mfma_f32_32x32x16_bf16 v[34:49], v[212:215], v[216:219], v[34:49]
	v_mfma_f32_32x32x16_bf16 v[50:65], v[212:215], v[228:231], v[50:65]
	v_mfma_f32_32x32x16_bf16 v[2:17], v[220:223], v[224:227], v[2:17]
	v_mfma_f32_32x32x16_bf16 v[18:33], v[220:223], v[232:235], v[18:33]
	s_waitcnt lgkmcnt(0)
	v_mfma_f32_32x32x16_bf16 v[34:49], v[236:239], v[224:227], v[34:49]
	ds_read_b128 v[212:215], v72 offset:64
	ds_read_b128 v[216:219], v73 offset:36928
	ds_read_b128 v[220:223], v72 offset:96
	ds_read_b128 v[224:227], v73 offset:36960
	v_mfma_f32_32x32x16_bf16 v[50:65], v[236:239], v[232:235], v[50:65]
	ds_read_b128 v[228:231], v73 offset:41536
	ds_read_b128 v[232:235], v73 offset:41568
	s_waitcnt lgkmcnt(4)
	v_mfma_f32_32x32x16_bf16 v[2:17], v[212:215], v[216:219], v[2:17]
	s_waitcnt lgkmcnt(1)
	v_mfma_f32_32x32x16_bf16 v[18:33], v[212:215], v[228:231], v[18:33]
	ds_read_b128 v[212:215], v72 offset:4672
	ds_read_b128 v[236:239], v72 offset:4704
	s_waitcnt vmcnt(16)
	ds_write_b128 v1, v[120:123] offset:18432
	ds_write_b128 v1, v[124:127] offset:23040
	ds_write_b128 v1, v[128:131] offset:27648
	ds_write_b128 v1, v[240:243] offset:32256
	ds_write_b128 v1, v[104:107] offset:55296
	ds_write_b128 v1, v[108:111] offset:59904
	ds_write_b128 v1, v[112:115] offset:64512
	ds_write_b128 v92, v[116:119] offset:32256
	global_load_dwordx4 v[124:127], v[80:81], off offset:1536
	global_load_dwordx4 v[128:131], v[82:83], off offset:1536
	global_load_dwordx4 v[120:123], v[78:79], off offset:1536
	global_load_dwordx4 v[104:107], v[76:77], off offset:1536
	global_load_dwordx4 v[240:243], v[90:91], off offset:1536
	global_load_dwordx4 v[108:111], v[84:85], off offset:1536
	global_load_dwordx4 v[112:115], v[86:87], off offset:1536
	global_load_dwordx4 v[116:119], v[88:89], off offset:1536
	s_waitcnt lgkmcnt(0)
	s_barrier
	v_mfma_f32_32x32x16_bf16 v[34:49], v[212:215], v[216:219], v[34:49]
	v_mfma_f32_32x32x16_bf16 v[50:65], v[212:215], v[228:231], v[50:65]
	v_mfma_f32_32x32x16_bf16 v[2:17], v[220:223], v[224:227], v[2:17]
	v_mfma_f32_32x32x16_bf16 v[18:33], v[220:223], v[232:235], v[18:33]
	v_mfma_f32_32x32x16_bf16 v[34:49], v[236:239], v[224:227], v[34:49]
	v_mfma_f32_32x32x16_bf16 v[50:65], v[236:239], v[232:235], v[50:65]
	ds_read_b128 v[212:215], v72 offset:18432
	ds_read_b128 v[216:219], v73 offset:55296
	ds_read_b128 v[220:223], v72 offset:18464
	ds_read_b128 v[224:227], v73 offset:55328
	ds_read_b128 v[228:231], v73 offset:59904
	ds_read_b128 v[232:235], v73 offset:59936
	s_waitcnt lgkmcnt(4)
	v_mfma_f32_32x32x16_bf16 v[2:17], v[212:215], v[216:219], v[2:17]
	s_waitcnt lgkmcnt(1)
	v_mfma_f32_32x32x16_bf16 v[18:33], v[212:215], v[228:231], v[18:33]
	ds_read_b128 v[212:215], v72 offset:23040
	ds_read_b128 v[236:239], v72 offset:23072
	s_waitcnt lgkmcnt(1)
	v_mfma_f32_32x32x16_bf16 v[34:49], v[212:215], v[216:219], v[34:49]
	v_mfma_f32_32x32x16_bf16 v[50:65], v[212:215], v[228:231], v[50:65]
	v_mfma_f32_32x32x16_bf16 v[2:17], v[220:223], v[224:227], v[2:17]
	v_mfma_f32_32x32x16_bf16 v[18:33], v[220:223], v[232:235], v[18:33]
	s_waitcnt lgkmcnt(0)
	v_mfma_f32_32x32x16_bf16 v[34:49], v[236:239], v[224:227], v[34:49]
	ds_read_b128 v[212:215], v72 offset:18496
	ds_read_b128 v[216:219], v73 offset:55360
	ds_read_b128 v[220:223], v72 offset:18528
	ds_read_b128 v[224:227], v73 offset:55392
	v_mfma_f32_32x32x16_bf16 v[50:65], v[236:239], v[232:235], v[50:65]
	ds_read_b128 v[228:231], v73 offset:59968
	ds_read_b128 v[232:235], v73 offset:60000
	s_waitcnt lgkmcnt(4)
	v_mfma_f32_32x32x16_bf16 v[2:17], v[212:215], v[216:219], v[2:17]
	s_waitcnt lgkmcnt(1)
	v_mfma_f32_32x32x16_bf16 v[18:33], v[212:215], v[228:231], v[18:33]
	ds_read_b128 v[212:215], v72 offset:23104
	ds_read_b128 v[236:239], v72 offset:23136
	s_waitcnt vmcnt(16)
	ds_write_b128 v1, v[164:167]
	ds_write_b128 v1, v[168:171] offset:4608
	ds_write_b128 v1, v[172:175] offset:9216
	ds_write_b128 v1, v[176:179] offset:13824
	ds_write_b128 v1, v[148:151] offset:36864
	ds_write_b128 v1, v[152:155] offset:41472
	ds_write_b128 v1, v[156:159] offset:46080
	ds_write_b128 v1, v[160:163] offset:50688
	global_load_dwordx4 v[168:171], v[80:81], off offset:1664
	global_load_dwordx4 v[172:175], v[82:83], off offset:1664
	global_load_dwordx4 v[164:167], v[78:79], off offset:1664
	global_load_dwordx4 v[148:151], v[76:77], off offset:1664
	global_load_dwordx4 v[176:179], v[90:91], off offset:1664
	global_load_dwordx4 v[152:155], v[84:85], off offset:1664
	global_load_dwordx4 v[156:159], v[86:87], off offset:1664
	global_load_dwordx4 v[160:163], v[88:89], off offset:1664
	s_waitcnt lgkmcnt(0)
	s_barrier
	v_mfma_f32_32x32x16_bf16 v[34:49], v[212:215], v[216:219], v[34:49]
	v_mfma_f32_32x32x16_bf16 v[50:65], v[212:215], v[228:231], v[50:65]
	v_mfma_f32_32x32x16_bf16 v[2:17], v[220:223], v[224:227], v[2:17]
	v_mfma_f32_32x32x16_bf16 v[18:33], v[220:223], v[232:235], v[18:33]
	v_mfma_f32_32x32x16_bf16 v[34:49], v[236:239], v[224:227], v[34:49]
	v_mfma_f32_32x32x16_bf16 v[50:65], v[236:239], v[232:235], v[50:65]
	ds_read_b128 v[212:215], v72
	ds_read_b128 v[216:219], v73 offset:36864
	ds_read_b128 v[220:223], v72 offset:32
	ds_read_b128 v[224:227], v73 offset:36896
	ds_read_b128 v[228:231], v73 offset:41472
	ds_read_b128 v[232:235], v73 offset:41504
	s_waitcnt lgkmcnt(4)
	v_mfma_f32_32x32x16_bf16 v[2:17], v[212:215], v[216:219], v[2:17]
	s_waitcnt lgkmcnt(1)
	v_mfma_f32_32x32x16_bf16 v[18:33], v[212:215], v[228:231], v[18:33]
	ds_read_b128 v[212:215], v72 offset:4608
	ds_read_b128 v[236:239], v72 offset:4640
	s_waitcnt lgkmcnt(1)
	v_mfma_f32_32x32x16_bf16 v[34:49], v[212:215], v[216:219], v[34:49]
	v_mfma_f32_32x32x16_bf16 v[50:65], v[212:215], v[228:231], v[50:65]
	v_mfma_f32_32x32x16_bf16 v[2:17], v[220:223], v[224:227], v[2:17]
	v_mfma_f32_32x32x16_bf16 v[18:33], v[220:223], v[232:235], v[18:33]
	s_waitcnt lgkmcnt(0)
	v_mfma_f32_32x32x16_bf16 v[34:49], v[236:239], v[224:227], v[34:49]
	ds_read_b128 v[212:215], v72 offset:64
	ds_read_b128 v[216:219], v73 offset:36928
	ds_read_b128 v[220:223], v72 offset:96
	ds_read_b128 v[224:227], v73 offset:36960
	v_mfma_f32_32x32x16_bf16 v[50:65], v[236:239], v[232:235], v[50:65]
	ds_read_b128 v[228:231], v73 offset:41536
	ds_read_b128 v[232:235], v73 offset:41568
	s_waitcnt lgkmcnt(4)
	v_mfma_f32_32x32x16_bf16 v[2:17], v[212:215], v[216:219], v[2:17]
	s_waitcnt lgkmcnt(1)
	v_mfma_f32_32x32x16_bf16 v[18:33], v[212:215], v[228:231], v[18:33]
	ds_read_b128 v[212:215], v72 offset:4672
	ds_read_b128 v[236:239], v72 offset:4704
	s_waitcnt vmcnt(16)
	ds_write_b128 v1, v[196:199] offset:18432
	ds_write_b128 v1, v[200:203] offset:23040
	ds_write_b128 v1, v[204:207] offset:27648
	ds_write_b128 v1, v[208:211] offset:32256
	ds_write_b128 v1, v[180:183] offset:55296
	ds_write_b128 v1, v[184:187] offset:59904
	ds_write_b128 v1, v[188:191] offset:64512
	ds_write_b128 v92, v[192:195] offset:32256
	global_load_dwordx4 v[200:203], v[80:81], off offset:1792
	global_load_dwordx4 v[204:207], v[82:83], off offset:1792
	global_load_dwordx4 v[196:199], v[78:79], off offset:1792
	global_load_dwordx4 v[180:183], v[76:77], off offset:1792
	global_load_dwordx4 v[208:211], v[90:91], off offset:1792
	global_load_dwordx4 v[184:187], v[84:85], off offset:1792
	global_load_dwordx4 v[188:191], v[86:87], off offset:1792
	global_load_dwordx4 v[192:195], v[88:89], off offset:1792
	s_waitcnt lgkmcnt(0)
	s_barrier
	v_mfma_f32_32x32x16_bf16 v[34:49], v[212:215], v[216:219], v[34:49]
	v_mfma_f32_32x32x16_bf16 v[50:65], v[212:215], v[228:231], v[50:65]
	v_mfma_f32_32x32x16_bf16 v[2:17], v[220:223], v[224:227], v[2:17]
	v_mfma_f32_32x32x16_bf16 v[18:33], v[220:223], v[232:235], v[18:33]
	v_mfma_f32_32x32x16_bf16 v[34:49], v[236:239], v[224:227], v[34:49]
	v_mfma_f32_32x32x16_bf16 v[50:65], v[236:239], v[232:235], v[50:65]
	ds_read_b128 v[212:215], v72 offset:18432
	ds_read_b128 v[216:219], v73 offset:55296
	ds_read_b128 v[220:223], v72 offset:18464
	ds_read_b128 v[224:227], v73 offset:55328
	ds_read_b128 v[228:231], v73 offset:59904
	ds_read_b128 v[232:235], v73 offset:59936
	s_waitcnt lgkmcnt(4)
	v_mfma_f32_32x32x16_bf16 v[2:17], v[212:215], v[216:219], v[2:17]
	s_waitcnt lgkmcnt(1)
	v_mfma_f32_32x32x16_bf16 v[18:33], v[212:215], v[228:231], v[18:33]
	ds_read_b128 v[212:215], v72 offset:23040
	ds_read_b128 v[236:239], v72 offset:23072
	s_waitcnt lgkmcnt(1)
	v_mfma_f32_32x32x16_bf16 v[34:49], v[212:215], v[216:219], v[34:49]
	v_mfma_f32_32x32x16_bf16 v[50:65], v[212:215], v[228:231], v[50:65]
	v_mfma_f32_32x32x16_bf16 v[2:17], v[220:223], v[224:227], v[2:17]
	v_mfma_f32_32x32x16_bf16 v[18:33], v[220:223], v[232:235], v[18:33]
	s_waitcnt lgkmcnt(0)
	v_mfma_f32_32x32x16_bf16 v[34:49], v[236:239], v[224:227], v[34:49]
	ds_read_b128 v[212:215], v72 offset:18496
	ds_read_b128 v[216:219], v73 offset:55360
	ds_read_b128 v[220:223], v72 offset:18528
	ds_read_b128 v[224:227], v73 offset:55392
	v_mfma_f32_32x32x16_bf16 v[50:65], v[236:239], v[232:235], v[50:65]
	ds_read_b128 v[228:231], v73 offset:59968
	ds_read_b128 v[232:235], v73 offset:60000
	s_waitcnt lgkmcnt(4)
	v_mfma_f32_32x32x16_bf16 v[2:17], v[212:215], v[216:219], v[2:17]
	s_waitcnt lgkmcnt(1)
	v_mfma_f32_32x32x16_bf16 v[18:33], v[212:215], v[228:231], v[18:33]
	ds_read_b128 v[212:215], v72 offset:23104
	ds_read_b128 v[236:239], v72 offset:23136
	s_waitcnt vmcnt(16)
	ds_write_b128 v1, v[120:123]
	ds_write_b128 v1, v[124:127] offset:4608
	ds_write_b128 v1, v[128:131] offset:9216
	ds_write_b128 v1, v[240:243] offset:13824
	ds_write_b128 v1, v[104:107] offset:36864
	ds_write_b128 v1, v[108:111] offset:41472
	ds_write_b128 v1, v[112:115] offset:46080
	ds_write_b128 v1, v[116:119] offset:50688
	global_load_dwordx4 v[124:127], v[80:81], off offset:1920
	global_load_dwordx4 v[128:131], v[82:83], off offset:1920
	global_load_dwordx4 v[120:123], v[78:79], off offset:1920
	global_load_dwordx4 v[104:107], v[76:77], off offset:1920
	global_load_dwordx4 v[240:243], v[90:91], off offset:1920
	global_load_dwordx4 v[108:111], v[84:85], off offset:1920
	global_load_dwordx4 v[112:115], v[86:87], off offset:1920
	global_load_dwordx4 v[116:119], v[88:89], off offset:1920
	s_waitcnt lgkmcnt(0)
	s_barrier
	v_mfma_f32_32x32x16_bf16 v[34:49], v[212:215], v[216:219], v[34:49]
	v_mfma_f32_32x32x16_bf16 v[50:65], v[212:215], v[228:231], v[50:65]
	v_mfma_f32_32x32x16_bf16 v[2:17], v[220:223], v[224:227], v[2:17]
	v_mfma_f32_32x32x16_bf16 v[18:33], v[220:223], v[232:235], v[18:33]
	v_mfma_f32_32x32x16_bf16 v[34:49], v[236:239], v[224:227], v[34:49]
	v_mfma_f32_32x32x16_bf16 v[50:65], v[236:239], v[232:235], v[50:65]
	ds_read_b128 v[212:215], v72
	ds_read_b128 v[216:219], v73 offset:36864
	ds_read_b128 v[220:223], v72 offset:32
	ds_read_b128 v[224:227], v73 offset:36896
	ds_read_b128 v[228:231], v73 offset:41472
	ds_read_b128 v[232:235], v73 offset:41504
	s_waitcnt lgkmcnt(4)
	v_mfma_f32_32x32x16_bf16 v[2:17], v[212:215], v[216:219], v[2:17]
	s_waitcnt lgkmcnt(1)
	v_mfma_f32_32x32x16_bf16 v[18:33], v[212:215], v[228:231], v[18:33]
	ds_read_b128 v[212:215], v72 offset:4608
	ds_read_b128 v[236:239], v72 offset:4640
	s_waitcnt lgkmcnt(1)
	v_mfma_f32_32x32x16_bf16 v[34:49], v[212:215], v[216:219], v[34:49]
	v_mfma_f32_32x32x16_bf16 v[50:65], v[212:215], v[228:231], v[50:65]
	v_mfma_f32_32x32x16_bf16 v[2:17], v[220:223], v[224:227], v[2:17]
	v_mfma_f32_32x32x16_bf16 v[18:33], v[220:223], v[232:235], v[18:33]
	s_waitcnt lgkmcnt(0)
	v_mfma_f32_32x32x16_bf16 v[34:49], v[236:239], v[224:227], v[34:49]
	ds_read_b128 v[212:215], v72 offset:64
	ds_read_b128 v[216:219], v73 offset:36928
	ds_read_b128 v[220:223], v72 offset:96
	ds_read_b128 v[224:227], v73 offset:36960
	v_mfma_f32_32x32x16_bf16 v[50:65], v[236:239], v[232:235], v[50:65]
	ds_read_b128 v[228:231], v73 offset:41536
	ds_read_b128 v[232:235], v73 offset:41568
	s_waitcnt lgkmcnt(4)
	v_mfma_f32_32x32x16_bf16 v[2:17], v[212:215], v[216:219], v[2:17]
	s_waitcnt lgkmcnt(1)
	v_mfma_f32_32x32x16_bf16 v[18:33], v[212:215], v[228:231], v[18:33]
	ds_read_b128 v[212:215], v72 offset:4672
	ds_read_b128 v[236:239], v72 offset:4704
	s_waitcnt vmcnt(16)
	ds_write_b128 v1, v[164:167] offset:18432
	ds_write_b128 v1, v[168:171] offset:23040
	ds_write_b128 v1, v[172:175] offset:27648
	ds_write_b128 v1, v[176:179] offset:32256
	ds_write_b128 v1, v[148:151] offset:55296
	ds_write_b128 v1, v[152:155] offset:59904
	ds_write_b128 v1, v[156:159] offset:64512
	ds_write_b128 v92, v[160:163] offset:32256
	s_waitcnt lgkmcnt(0)
	s_barrier
	v_mfma_f32_32x32x16_bf16 v[34:49], v[212:215], v[216:219], v[34:49]
	v_mfma_f32_32x32x16_bf16 v[50:65], v[212:215], v[228:231], v[50:65]
	v_mfma_f32_32x32x16_bf16 v[2:17], v[220:223], v[224:227], v[2:17]
	v_mfma_f32_32x32x16_bf16 v[18:33], v[220:223], v[232:235], v[18:33]
	v_mfma_f32_32x32x16_bf16 v[34:49], v[236:239], v[224:227], v[34:49]
	v_mfma_f32_32x32x16_bf16 v[50:65], v[236:239], v[232:235], v[50:65]
	ds_read_b128 v[164:167], v72 offset:18432
	ds_read_b128 v[168:171], v73 offset:55296
	ds_read_b128 v[172:175], v72 offset:18464
	ds_read_b128 v[176:179], v73 offset:55328
	ds_read_b128 v[212:215], v73 offset:59904
	ds_read_b128 v[216:219], v73 offset:59936
	s_waitcnt lgkmcnt(4)
	v_mfma_f32_32x32x16_bf16 v[2:17], v[164:167], v[168:171], v[2:17]
	s_waitcnt lgkmcnt(1)
	v_mfma_f32_32x32x16_bf16 v[18:33], v[164:167], v[212:215], v[18:33]
	ds_read_b128 v[164:167], v72 offset:23040
	ds_read_b128 v[220:223], v72 offset:23072
	s_waitcnt lgkmcnt(1)
	v_mfma_f32_32x32x16_bf16 v[34:49], v[164:167], v[168:171], v[34:49]
	v_mfma_f32_32x32x16_bf16 v[50:65], v[164:167], v[212:215], v[50:65]
	v_mfma_f32_32x32x16_bf16 v[2:17], v[172:175], v[176:179], v[2:17]
	v_mfma_f32_32x32x16_bf16 v[18:33], v[172:175], v[216:219], v[18:33]
	s_waitcnt lgkmcnt(0)
	v_mfma_f32_32x32x16_bf16 v[34:49], v[220:223], v[176:179], v[34:49]
	ds_read_b128 v[164:167], v72 offset:18496
	ds_read_b128 v[168:171], v73 offset:55360
	ds_read_b128 v[172:175], v72 offset:18528
	ds_read_b128 v[176:179], v73 offset:55392
	v_mfma_f32_32x32x16_bf16 v[50:65], v[220:223], v[216:219], v[50:65]
	ds_read_b128 v[212:215], v73 offset:59968
	ds_read_b128 v[216:219], v73 offset:60000
	s_waitcnt lgkmcnt(4)
	v_mfma_f32_32x32x16_bf16 v[2:17], v[164:167], v[168:171], v[2:17]
	s_waitcnt lgkmcnt(1)
	v_mfma_f32_32x32x16_bf16 v[18:33], v[164:167], v[212:215], v[18:33]
	ds_read_b128 v[164:167], v72 offset:23104
	ds_read_b128 v[220:223], v72 offset:23136
	s_waitcnt vmcnt(8)
	ds_write_b128 v1, v[196:199]
	ds_write_b128 v1, v[200:203] offset:4608
	ds_write_b128 v1, v[204:207] offset:9216
	ds_write_b128 v1, v[208:211] offset:13824
	ds_write_b128 v1, v[180:183] offset:36864
	ds_write_b128 v1, v[184:187] offset:41472
	ds_write_b128 v1, v[188:191] offset:46080
	ds_write_b128 v1, v[192:195] offset:50688
	s_waitcnt lgkmcnt(0)
	s_barrier
	v_mfma_f32_32x32x16_bf16 v[34:49], v[164:167], v[168:171], v[34:49]
	v_mfma_f32_32x32x16_bf16 v[50:65], v[164:167], v[212:215], v[50:65]
	v_mfma_f32_32x32x16_bf16 v[2:17], v[172:175], v[176:179], v[2:17]
	v_mfma_f32_32x32x16_bf16 v[18:33], v[172:175], v[216:219], v[18:33]
	v_mfma_f32_32x32x16_bf16 v[34:49], v[220:223], v[176:179], v[34:49]
	v_mfma_f32_32x32x16_bf16 v[50:65], v[220:223], v[216:219], v[50:65]
	ds_read_b128 v[164:167], v72
	ds_read_b128 v[168:171], v73 offset:36864
	ds_read_b128 v[172:175], v72 offset:32
	ds_read_b128 v[176:179], v73 offset:36896
	ds_read_b128 v[180:183], v73 offset:41472
	ds_read_b128 v[184:187], v73 offset:41504
	s_waitcnt lgkmcnt(4)
	v_mfma_f32_32x32x16_bf16 v[2:17], v[164:167], v[168:171], v[2:17]
	s_waitcnt lgkmcnt(1)
	v_mfma_f32_32x32x16_bf16 v[18:33], v[164:167], v[180:183], v[18:33]
	ds_read_b128 v[164:167], v72 offset:4608
	ds_read_b128 v[188:191], v72 offset:4640
	s_waitcnt lgkmcnt(1)
	v_mfma_f32_32x32x16_bf16 v[34:49], v[164:167], v[168:171], v[34:49]
	v_mfma_f32_32x32x16_bf16 v[50:65], v[164:167], v[180:183], v[50:65]
	v_mfma_f32_32x32x16_bf16 v[2:17], v[172:175], v[176:179], v[2:17]
	v_mfma_f32_32x32x16_bf16 v[18:33], v[172:175], v[184:187], v[18:33]
	s_waitcnt lgkmcnt(0)
	v_mfma_f32_32x32x16_bf16 v[34:49], v[188:191], v[176:179], v[34:49]
	ds_read_b128 v[164:167], v72 offset:64
	ds_read_b128 v[168:171], v73 offset:36928
	ds_read_b128 v[172:175], v72 offset:96
	ds_read_b128 v[176:179], v73 offset:36960
	v_mfma_f32_32x32x16_bf16 v[50:65], v[188:191], v[184:187], v[50:65]
	ds_read_b128 v[180:183], v73 offset:41536
	ds_read_b128 v[184:187], v73 offset:41568
	s_waitcnt lgkmcnt(4)
	v_mfma_f32_32x32x16_bf16 v[2:17], v[164:167], v[168:171], v[2:17]
	s_waitcnt lgkmcnt(1)
	v_mfma_f32_32x32x16_bf16 v[18:33], v[164:167], v[180:183], v[18:33]
	ds_read_b128 v[164:167], v72 offset:4672
	ds_read_b128 v[188:191], v72 offset:4704
	s_waitcnt vmcnt(0)
	ds_write_b128 v1, v[120:123] offset:18432
	ds_write_b128 v1, v[124:127] offset:23040
	ds_write_b128 v1, v[128:131] offset:27648
	ds_write_b128 v1, v[240:243] offset:32256
	ds_write_b128 v1, v[104:107] offset:55296
	ds_write_b128 v1, v[108:111] offset:59904
	ds_write_b128 v1, v[112:115] offset:64512
	ds_write_b128 v92, v[116:119] offset:32256
	s_waitcnt lgkmcnt(0)
	s_barrier
	v_mfma_f32_32x32x16_bf16 v[34:49], v[164:167], v[168:171], v[34:49]
	v_mfma_f32_32x32x16_bf16 v[50:65], v[164:167], v[180:183], v[50:65]
	v_mfma_f32_32x32x16_bf16 v[2:17], v[172:175], v[176:179], v[2:17]
	v_mfma_f32_32x32x16_bf16 v[18:33], v[172:175], v[184:187], v[18:33]
	v_mfma_f32_32x32x16_bf16 v[34:49], v[188:191], v[176:179], v[34:49]
	v_mfma_f32_32x32x16_bf16 v[50:65], v[188:191], v[184:187], v[50:65]
	ds_read_b128 v[76:79], v72 offset:18432
	ds_read_b128 v[80:83], v73 offset:55296
	ds_read_b128 v[84:87], v72 offset:18464
	ds_read_b128 v[88:91], v73 offset:55328
	ds_read_b128 v[148:151], v73 offset:59904
	ds_read_b128 v[152:155], v73 offset:59936
	v_or_b32_e32 v66, s8, v93
	s_waitcnt lgkmcnt(4)
	v_mfma_f32_32x32x16_bf16 v[2:17], v[76:79], v[80:83], v[2:17]
	s_lshl_b32 s10, s10, 1
	s_mov_b32 s11, s9
	s_add_i32 s13, s13, s12
	s_add_i32 s14, s14, s15
	s_add_i32 s16, s16, s17
	s_cmpk_lt_u32 s13, 0x400
	s_waitcnt lgkmcnt(1)
	v_mfma_f32_32x32x16_bf16 v[18:33], v[76:79], v[148:151], v[18:33]
	ds_read_b128 v[76:79], v72 offset:23040
	ds_read_b128 v[156:159], v72 offset:23072
	s_waitcnt lgkmcnt(1)
	v_mfma_f32_32x32x16_bf16 v[34:49], v[76:79], v[80:83], v[34:49]
	v_mfma_f32_32x32x16_bf16 v[50:65], v[76:79], v[148:151], v[50:65]
	v_mfma_f32_32x32x16_bf16 v[2:17], v[84:87], v[88:91], v[2:17]
	v_mfma_f32_32x32x16_bf16 v[18:33], v[84:87], v[152:155], v[18:33]
	s_waitcnt lgkmcnt(0)
	v_mfma_f32_32x32x16_bf16 v[34:49], v[156:159], v[88:91], v[34:49]
	ds_read_b128 v[76:79], v72 offset:18496
	ds_read_b128 v[80:83], v73 offset:55360
	ds_read_b128 v[84:87], v72 offset:18528
	ds_read_b128 v[88:91], v73 offset:55392
	v_mfma_f32_32x32x16_bf16 v[50:65], v[156:159], v[152:155], v[50:65]
	ds_read_b128 v[148:151], v73 offset:59968
	ds_read_b128 v[152:155], v73 offset:60000
	s_waitcnt lgkmcnt(4)
	v_mfma_f32_32x32x16_bf16 v[2:17], v[76:79], v[80:83], v[2:17]
	s_waitcnt lgkmcnt(1)
	v_mfma_f32_32x32x16_bf16 v[18:33], v[76:79], v[148:151], v[18:33]
	ds_read_b128 v[76:79], v72 offset:23104
	ds_read_b128 v[156:159], v72 offset:23136
	s_waitcnt lgkmcnt(0)
	s_barrier
	v_mfma_f32_32x32x16_bf16 v[34:49], v[76:79], v[80:83], v[34:49]
	v_mfma_f32_32x32x16_bf16 v[50:65], v[76:79], v[148:151], v[50:65]
	v_mfma_f32_32x32x16_bf16 v[2:17], v[84:87], v[88:91], v[2:17]
	v_mfma_f32_32x32x16_bf16 v[18:33], v[84:87], v[152:155], v[18:33]
	v_mfma_f32_32x32x16_bf16 v[34:49], v[156:159], v[88:91], v[34:49]
	s_nop 10
	ds_write2_b32 v101, v2, v18 offset1:32
	v_mfma_f32_32x32x16_bf16 v[50:65], v[156:159], v[152:155], v[50:65]
	s_nop 11
	ds_write2_b32 v132, v34, v50 offset0:32 offset1:64
	ds_write2_b32 v101, v3, v19 offset0:129 offset1:161
	ds_write2_b32 v132, v35, v51 offset0:161 offset1:193
	ds_write2_b32 v133, v4, v20 offset0:2 offset1:34
	ds_write2_b32 v134, v36, v52 offset0:34 offset1:66
	ds_write2_b32 v133, v5, v21 offset0:131 offset1:163
	ds_write2_b32 v134, v37, v53 offset0:163 offset1:195
	ds_write2_b32 v135, v6, v22 offset0:8 offset1:40
	ds_write2_b32 v136, v38, v54 offset0:40 offset1:72
	ds_write2_b32 v135, v7, v23 offset0:137 offset1:169
	ds_write2_b32 v136, v39, v55 offset0:169 offset1:201
	ds_write2_b32 v137, v8, v24 offset0:10 offset1:42
	ds_write2_b32 v138, v40, v56 offset0:42 offset1:74
	ds_write2_b32 v137, v9, v25 offset0:139 offset1:171
	ds_write2_b32 v138, v41, v57 offset0:171 offset1:203
	ds_write2_b32 v139, v10, v26 offset0:16 offset1:48
	ds_write2_b32 v140, v42, v58 offset0:48 offset1:80
	ds_write2_b32 v139, v11, v27 offset0:145 offset1:177
	ds_write2_b32 v140, v43, v59 offset0:177 offset1:209
	ds_write2_b32 v141, v12, v28 offset0:18 offset1:50
	ds_write2_b32 v142, v44, v60 offset0:50 offset1:82
	ds_write2_b32 v141, v13, v29 offset0:147 offset1:179
	ds_write2_b32 v142, v45, v61 offset0:179 offset1:211
	ds_write2_b32 v143, v14, v30 offset0:24 offset1:56
	ds_write2_b32 v144, v46, v62 offset0:56 offset1:88
	ds_write2_b32 v143, v15, v31 offset0:153 offset1:185
	ds_write2_b32 v144, v47, v63 offset0:185 offset1:217
	ds_write2_b32 v145, v16, v32 offset0:26 offset1:58
	ds_write2_b32 v146, v48, v64 offset0:58 offset1:90
	ds_write2_b32 v145, v17, v33 offset0:155 offset1:187
	ds_write2_b32 v146, v49, v65 offset0:187 offset1:219
	v_lshl_add_u64 v[2:3], v[66:67], 2, s[6:7]
	s_waitcnt lgkmcnt(0)
	s_barrier
	v_mov_b32_e32 v2, v66
	v_lshlrev_b32_e32 v3, 2, v2
	global_load_dword v5, v3, s[6:7]
	global_load_dword v6, v3, s[6:7] offset:64
	global_load_dword v7, v3, s[6:7] offset:128
	global_load_dword v8, v3, s[6:7] offset:192
	global_load_dword v9, v3, s[6:7] offset:256
	global_load_dword v10, v3, s[6:7] offset:320
	global_load_dword v11, v3, s[6:7] offset:384
	global_load_dword v12, v3, s[6:7] offset:448
	v_lshlrev_b32_e32 v4, 13, v2
	v_add3_u32 v4, v4, v74, s10
	s_movk_i32 s24, 0x7fff
	v_mov_b32_e32 v59, 1
	v_mov_b32_e32 v13, 0x358637bd
	ds_read2_b32 v[14:15], v103 offset0:0 offset1:1
	ds_read2_b32 v[16:17], v103 offset0:2 offset1:3
	ds_read2_b32 v[18:19], v103 offset0:4 offset1:5
	ds_read2_b32 v[20:21], v103 offset0:6 offset1:7
	v_add_u32_e32 v56, 0x2040, v103
	ds_read2_b32 v[22:23], v56 offset0:0 offset1:1
	ds_read2_b32 v[24:25], v56 offset0:2 offset1:3
	ds_read2_b32 v[26:27], v56 offset0:4 offset1:5
	ds_read2_b32 v[28:29], v56 offset0:6 offset1:7
	s_waitcnt vmcnt(7) lgkmcnt(4)
	v_fmamk_f32 v54, v5, 0x3a800000, v13
	v_rsq_f32_e32 v54, v54
	s_nop 0
	v_mul_f32_e32 v14, v14, v54
	v_mul_f32_e32 v15, v15, v54
	v_mul_f32_e32 v16, v16, v54
	v_mul_f32_e32 v17, v17, v54
	v_mul_f32_e32 v18, v18, v54
	v_mul_f32_e32 v19, v19, v54
	v_mul_f32_e32 v20, v20, v54
	v_mul_f32_e32 v21, v21, v54
	v_max_f32_e32 v14, 0, v14
	v_max_f32_e32 v15, 0, v15
	v_max_f32_e32 v16, 0, v16
	v_max_f32_e32 v17, 0, v17
	v_max_f32_e32 v18, 0, v18
	v_max_f32_e32 v19, 0, v19
	v_max_f32_e32 v20, 0, v20
	v_max_f32_e32 v21, 0, v21
	v_pk_mul_f32 v[14:15], v[14:15], v[14:15]
	v_pk_mul_f32 v[16:17], v[16:17], v[16:17]
	v_pk_mul_f32 v[18:19], v[18:19], v[18:19]
	v_pk_mul_f32 v[20:21], v[20:21], v[20:21]
	v_and_b32_sdwa v46, v14, v59 dst_sel:DWORD dst_unused:UNUSED_PAD src0_sel:WORD_1 src1_sel:DWORD
	v_and_b32_sdwa v47, v15, v59 dst_sel:DWORD dst_unused:UNUSED_PAD src0_sel:WORD_1 src1_sel:DWORD
	v_and_b32_sdwa v48, v16, v59 dst_sel:DWORD dst_unused:UNUSED_PAD src0_sel:WORD_1 src1_sel:DWORD
	v_and_b32_sdwa v49, v17, v59 dst_sel:DWORD dst_unused:UNUSED_PAD src0_sel:WORD_1 src1_sel:DWORD
	v_and_b32_sdwa v50, v18, v59 dst_sel:DWORD dst_unused:UNUSED_PAD src0_sel:WORD_1 src1_sel:DWORD
	v_and_b32_sdwa v51, v19, v59 dst_sel:DWORD dst_unused:UNUSED_PAD src0_sel:WORD_1 src1_sel:DWORD
	v_and_b32_sdwa v52, v20, v59 dst_sel:DWORD dst_unused:UNUSED_PAD src0_sel:WORD_1 src1_sel:DWORD
	v_and_b32_sdwa v53, v21, v59 dst_sel:DWORD dst_unused:UNUSED_PAD src0_sel:WORD_1 src1_sel:DWORD
	v_add3_u32 v14, v14, v46, s24
	v_add3_u32 v15, v15, v47, s24
	v_add3_u32 v16, v16, v48, s24
	v_add3_u32 v17, v17, v49, s24
	v_add3_u32 v18, v18, v50, s24
	v_add3_u32 v19, v19, v51, s24
	v_add3_u32 v20, v20, v52, s24
	v_add3_u32 v21, v21, v53, s24
	v_and_b32_e32 v15, 0xffff0000, v15
	v_and_b32_e32 v17, 0xffff0000, v17
	v_and_b32_e32 v19, 0xffff0000, v19
	v_and_b32_e32 v21, 0xffff0000, v21
	v_or_b32_sdwa v60, v15, v14 dst_sel:DWORD dst_unused:UNUSED_PAD src0_sel:DWORD src1_sel:WORD_1
	v_or_b32_sdwa v61, v17, v16 dst_sel:DWORD dst_unused:UNUSED_PAD src0_sel:DWORD src1_sel:WORD_1
	v_or_b32_sdwa v62, v19, v18 dst_sel:DWORD dst_unused:UNUSED_PAD src0_sel:DWORD src1_sel:WORD_1
	v_or_b32_sdwa v63, v21, v20 dst_sel:DWORD dst_unused:UNUSED_PAD src0_sel:DWORD src1_sel:WORD_1
	global_store_dwordx4 v4, v[60:63], s[56:57]
	v_add_u32_e32 v55, 0x4080, v103
	ds_read2_b32 v[30:31], v55 offset0:0 offset1:1
	ds_read2_b32 v[32:33], v55 offset0:2 offset1:3
	ds_read2_b32 v[34:35], v55 offset0:4 offset1:5
	ds_read2_b32 v[36:37], v55 offset0:6 offset1:7
	v_add_u32_e32 v56, 0x60c0, v103
	ds_read2_b32 v[38:39], v56 offset0:0 offset1:1
	ds_read2_b32 v[40:41], v56 offset0:2 offset1:3
	ds_read2_b32 v[42:43], v56 offset0:4 offset1:5
	ds_read2_b32 v[44:45], v56 offset0:6 offset1:7
	s_waitcnt vmcnt(7) lgkmcnt(8)
	v_fmamk_f32 v54, v6, 0x3a800000, v13
	v_rsq_f32_e32 v54, v54
	v_add_u32_e32 v58, 0x20000, v4
	v_mul_f32_e32 v22, v22, v54
	v_mul_f32_e32 v23, v23, v54
	v_mul_f32_e32 v24, v24, v54
	v_mul_f32_e32 v25, v25, v54
	v_mul_f32_e32 v26, v26, v54
	v_mul_f32_e32 v27, v27, v54
	v_mul_f32_e32 v28, v28, v54
	v_mul_f32_e32 v29, v29, v54
	v_max_f32_e32 v22, 0, v22
	v_max_f32_e32 v23, 0, v23
	v_max_f32_e32 v24, 0, v24
	v_max_f32_e32 v25, 0, v25
	v_max_f32_e32 v26, 0, v26
	v_max_f32_e32 v27, 0, v27
	v_max_f32_e32 v28, 0, v28
	v_max_f32_e32 v29, 0, v29
	v_pk_mul_f32 v[22:23], v[22:23], v[22:23]
	v_pk_mul_f32 v[24:25], v[24:25], v[24:25]
	v_pk_mul_f32 v[26:27], v[26:27], v[26:27]
	v_pk_mul_f32 v[28:29], v[28:29], v[28:29]
	v_and_b32_sdwa v46, v22, v59 dst_sel:DWORD dst_unused:UNUSED_PAD src0_sel:WORD_1 src1_sel:DWORD
	v_and_b32_sdwa v47, v23, v59 dst_sel:DWORD dst_unused:UNUSED_PAD src0_sel:WORD_1 src1_sel:DWORD
	v_and_b32_sdwa v48, v24, v59 dst_sel:DWORD dst_unused:UNUSED_PAD src0_sel:WORD_1 src1_sel:DWORD
	v_and_b32_sdwa v49, v25, v59 dst_sel:DWORD dst_unused:UNUSED_PAD src0_sel:WORD_1 src1_sel:DWORD
	v_and_b32_sdwa v50, v26, v59 dst_sel:DWORD dst_unused:UNUSED_PAD src0_sel:WORD_1 src1_sel:DWORD
	v_and_b32_sdwa v51, v27, v59 dst_sel:DWORD dst_unused:UNUSED_PAD src0_sel:WORD_1 src1_sel:DWORD
	v_and_b32_sdwa v52, v28, v59 dst_sel:DWORD dst_unused:UNUSED_PAD src0_sel:WORD_1 src1_sel:DWORD
	v_and_b32_sdwa v53, v29, v59 dst_sel:DWORD dst_unused:UNUSED_PAD src0_sel:WORD_1 src1_sel:DWORD
	v_add3_u32 v22, v22, v46, s24
	v_add3_u32 v23, v23, v47, s24
	v_add3_u32 v24, v24, v48, s24
	v_add3_u32 v25, v25, v49, s24
	v_add3_u32 v26, v26, v50, s24
	v_add3_u32 v27, v27, v51, s24
	v_add3_u32 v28, v28, v52, s24
	v_add3_u32 v29, v29, v53, s24
	v_and_b32_e32 v23, 0xffff0000, v23
	v_and_b32_e32 v25, 0xffff0000, v25
	v_and_b32_e32 v27, 0xffff0000, v27
	v_and_b32_e32 v29, 0xffff0000, v29
	v_or_b32_sdwa v76, v23, v22 dst_sel:DWORD dst_unused:UNUSED_PAD src0_sel:DWORD src1_sel:WORD_1
	v_or_b32_sdwa v77, v25, v24 dst_sel:DWORD dst_unused:UNUSED_PAD src0_sel:DWORD src1_sel:WORD_1
	v_or_b32_sdwa v78, v27, v26 dst_sel:DWORD dst_unused:UNUSED_PAD src0_sel:DWORD src1_sel:WORD_1
	v_or_b32_sdwa v79, v29, v28 dst_sel:DWORD dst_unused:UNUSED_PAD src0_sel:DWORD src1_sel:WORD_1
	global_store_dwordx4 v58, v[76:79], s[56:57]
	s_waitcnt vmcnt(7) lgkmcnt(4)
	v_fmamk_f32 v54, v7, 0x3a800000, v13
	v_rsq_f32_e32 v54, v54
	v_add_u32_e32 v57, 0x40000, v4
	v_mul_f32_e32 v30, v30, v54
	v_mul_f32_e32 v31, v31, v54
	v_mul_f32_e32 v32, v32, v54
	v_mul_f32_e32 v33, v33, v54
	v_mul_f32_e32 v34, v34, v54
	v_mul_f32_e32 v35, v35, v54
	v_mul_f32_e32 v36, v36, v54
	v_mul_f32_e32 v37, v37, v54
	v_max_f32_e32 v30, 0, v30
	v_max_f32_e32 v31, 0, v31
	v_max_f32_e32 v32, 0, v32
	v_max_f32_e32 v33, 0, v33
	v_max_f32_e32 v34, 0, v34
	v_max_f32_e32 v35, 0, v35
	v_max_f32_e32 v36, 0, v36
	v_max_f32_e32 v37, 0, v37
	v_pk_mul_f32 v[30:31], v[30:31], v[30:31]
	v_pk_mul_f32 v[32:33], v[32:33], v[32:33]
	v_pk_mul_f32 v[34:35], v[34:35], v[34:35]
	v_pk_mul_f32 v[36:37], v[36:37], v[36:37]
	v_and_b32_sdwa v46, v30, v59 dst_sel:DWORD dst_unused:UNUSED_PAD src0_sel:WORD_1 src1_sel:DWORD
	v_and_b32_sdwa v47, v31, v59 dst_sel:DWORD dst_unused:UNUSED_PAD src0_sel:WORD_1 src1_sel:DWORD
	v_and_b32_sdwa v48, v32, v59 dst_sel:DWORD dst_unused:UNUSED_PAD src0_sel:WORD_1 src1_sel:DWORD
	v_and_b32_sdwa v49, v33, v59 dst_sel:DWORD dst_unused:UNUSED_PAD src0_sel:WORD_1 src1_sel:DWORD
	v_and_b32_sdwa v50, v34, v59 dst_sel:DWORD dst_unused:UNUSED_PAD src0_sel:WORD_1 src1_sel:DWORD
	v_and_b32_sdwa v51, v35, v59 dst_sel:DWORD dst_unused:UNUSED_PAD src0_sel:WORD_1 src1_sel:DWORD
	v_and_b32_sdwa v52, v36, v59 dst_sel:DWORD dst_unused:UNUSED_PAD src0_sel:WORD_1 src1_sel:DWORD
	v_and_b32_sdwa v53, v37, v59 dst_sel:DWORD dst_unused:UNUSED_PAD src0_sel:WORD_1 src1_sel:DWORD
	v_add3_u32 v30, v30, v46, s24
	v_add3_u32 v31, v31, v47, s24
	v_add3_u32 v32, v32, v48, s24
	v_add3_u32 v33, v33, v49, s24
	v_add3_u32 v34, v34, v50, s24
	v_add3_u32 v35, v35, v51, s24
	v_add3_u32 v36, v36, v52, s24
	v_add3_u32 v37, v37, v53, s24
	v_and_b32_e32 v31, 0xffff0000, v31
	v_and_b32_e32 v33, 0xffff0000, v33
	v_and_b32_e32 v35, 0xffff0000, v35
	v_and_b32_e32 v37, 0xffff0000, v37
	v_or_b32_sdwa v60, v31, v30 dst_sel:DWORD dst_unused:UNUSED_PAD src0_sel:DWORD src1_sel:WORD_1
	v_or_b32_sdwa v61, v33, v32 dst_sel:DWORD dst_unused:UNUSED_PAD src0_sel:DWORD src1_sel:WORD_1
	v_or_b32_sdwa v62, v35, v34 dst_sel:DWORD dst_unused:UNUSED_PAD src0_sel:DWORD src1_sel:WORD_1
	v_or_b32_sdwa v63, v37, v36 dst_sel:DWORD dst_unused:UNUSED_PAD src0_sel:DWORD src1_sel:WORD_1
	global_store_dwordx4 v57, v[60:63], s[56:57]
	v_add_u32_e32 v55, 0x8100, v103
	ds_read2_b32 v[14:15], v55 offset0:0 offset1:1
	ds_read2_b32 v[16:17], v55 offset0:2 offset1:3
	ds_read2_b32 v[18:19], v55 offset0:4 offset1:5
	ds_read2_b32 v[20:21], v55 offset0:6 offset1:7
	v_add_u32_e32 v56, 0xa140, v103
	ds_read2_b32 v[22:23], v56 offset0:0 offset1:1
	ds_read2_b32 v[24:25], v56 offset0:2 offset1:3
	ds_read2_b32 v[26:27], v56 offset0:4 offset1:5
	ds_read2_b32 v[28:29], v56 offset0:6 offset1:7
	s_waitcnt vmcnt(7) lgkmcnt(8)
	v_fmamk_f32 v54, v8, 0x3a800000, v13
	v_rsq_f32_e32 v54, v54
	v_add_u32_e32 v58, 0x60000, v4
	v_mul_f32_e32 v38, v38, v54
	v_mul_f32_e32 v39, v39, v54
	v_mul_f32_e32 v40, v40, v54
	v_mul_f32_e32 v41, v41, v54
	v_mul_f32_e32 v42, v42, v54
	v_mul_f32_e32 v43, v43, v54
	v_mul_f32_e32 v44, v44, v54
	v_mul_f32_e32 v45, v45, v54
	v_max_f32_e32 v38, 0, v38
	v_max_f32_e32 v39, 0, v39
	v_max_f32_e32 v40, 0, v40
	v_max_f32_e32 v41, 0, v41
	v_max_f32_e32 v42, 0, v42
	v_max_f32_e32 v43, 0, v43
	v_max_f32_e32 v44, 0, v44
	v_max_f32_e32 v45, 0, v45
	v_pk_mul_f32 v[38:39], v[38:39], v[38:39]
	v_pk_mul_f32 v[40:41], v[40:41], v[40:41]
	v_pk_mul_f32 v[42:43], v[42:43], v[42:43]
	v_pk_mul_f32 v[44:45], v[44:45], v[44:45]
	v_and_b32_sdwa v46, v38, v59 dst_sel:DWORD dst_unused:UNUSED_PAD src0_sel:WORD_1 src1_sel:DWORD
	v_and_b32_sdwa v47, v39, v59 dst_sel:DWORD dst_unused:UNUSED_PAD src0_sel:WORD_1 src1_sel:DWORD
	v_and_b32_sdwa v48, v40, v59 dst_sel:DWORD dst_unused:UNUSED_PAD src0_sel:WORD_1 src1_sel:DWORD
	v_and_b32_sdwa v49, v41, v59 dst_sel:DWORD dst_unused:UNUSED_PAD src0_sel:WORD_1 src1_sel:DWORD
	v_and_b32_sdwa v50, v42, v59 dst_sel:DWORD dst_unused:UNUSED_PAD src0_sel:WORD_1 src1_sel:DWORD
	v_and_b32_sdwa v51, v43, v59 dst_sel:DWORD dst_unused:UNUSED_PAD src0_sel:WORD_1 src1_sel:DWORD
	v_and_b32_sdwa v52, v44, v59 dst_sel:DWORD dst_unused:UNUSED_PAD src0_sel:WORD_1 src1_sel:DWORD
	v_and_b32_sdwa v53, v45, v59 dst_sel:DWORD dst_unused:UNUSED_PAD src0_sel:WORD_1 src1_sel:DWORD
	v_add3_u32 v38, v38, v46, s24
	v_add3_u32 v39, v39, v47, s24
	v_add3_u32 v40, v40, v48, s24
	v_add3_u32 v41, v41, v49, s24
	v_add3_u32 v42, v42, v50, s24
	v_add3_u32 v43, v43, v51, s24
	v_add3_u32 v44, v44, v52, s24
	v_add3_u32 v45, v45, v53, s24
	v_and_b32_e32 v39, 0xffff0000, v39
	v_and_b32_e32 v41, 0xffff0000, v41
	v_and_b32_e32 v43, 0xffff0000, v43
	v_and_b32_e32 v45, 0xffff0000, v45
	v_or_b32_sdwa v76, v39, v38 dst_sel:DWORD dst_unused:UNUSED_PAD src0_sel:DWORD src1_sel:WORD_1
	v_or_b32_sdwa v77, v41, v40 dst_sel:DWORD dst_unused:UNUSED_PAD src0_sel:DWORD src1_sel:WORD_1
	v_or_b32_sdwa v78, v43, v42 dst_sel:DWORD dst_unused:UNUSED_PAD src0_sel:DWORD src1_sel:WORD_1
	v_or_b32_sdwa v79, v45, v44 dst_sel:DWORD dst_unused:UNUSED_PAD src0_sel:DWORD src1_sel:WORD_1
	global_store_dwordx4 v58, v[76:79], s[56:57]
	s_waitcnt vmcnt(7) lgkmcnt(4)
	v_fmamk_f32 v54, v9, 0x3a800000, v13
	v_rsq_f32_e32 v54, v54
	v_add_u32_e32 v57, 0x80000, v4
	v_mul_f32_e32 v14, v14, v54
	v_mul_f32_e32 v15, v15, v54
	v_mul_f32_e32 v16, v16, v54
	v_mul_f32_e32 v17, v17, v54
	v_mul_f32_e32 v18, v18, v54
	v_mul_f32_e32 v19, v19, v54
	v_mul_f32_e32 v20, v20, v54
	v_mul_f32_e32 v21, v21, v54
	v_max_f32_e32 v14, 0, v14
	v_max_f32_e32 v15, 0, v15
	v_max_f32_e32 v16, 0, v16
	v_max_f32_e32 v17, 0, v17
	v_max_f32_e32 v18, 0, v18
	v_max_f32_e32 v19, 0, v19
	v_max_f32_e32 v20, 0, v20
	v_max_f32_e32 v21, 0, v21
	v_pk_mul_f32 v[14:15], v[14:15], v[14:15]
	v_pk_mul_f32 v[16:17], v[16:17], v[16:17]
	v_pk_mul_f32 v[18:19], v[18:19], v[18:19]
	v_pk_mul_f32 v[20:21], v[20:21], v[20:21]
	v_and_b32_sdwa v46, v14, v59 dst_sel:DWORD dst_unused:UNUSED_PAD src0_sel:WORD_1 src1_sel:DWORD
	v_and_b32_sdwa v47, v15, v59 dst_sel:DWORD dst_unused:UNUSED_PAD src0_sel:WORD_1 src1_sel:DWORD
	v_and_b32_sdwa v48, v16, v59 dst_sel:DWORD dst_unused:UNUSED_PAD src0_sel:WORD_1 src1_sel:DWORD
	v_and_b32_sdwa v49, v17, v59 dst_sel:DWORD dst_unused:UNUSED_PAD src0_sel:WORD_1 src1_sel:DWORD
	v_and_b32_sdwa v50, v18, v59 dst_sel:DWORD dst_unused:UNUSED_PAD src0_sel:WORD_1 src1_sel:DWORD
	v_and_b32_sdwa v51, v19, v59 dst_sel:DWORD dst_unused:UNUSED_PAD src0_sel:WORD_1 src1_sel:DWORD
	v_and_b32_sdwa v52, v20, v59 dst_sel:DWORD dst_unused:UNUSED_PAD src0_sel:WORD_1 src1_sel:DWORD
	v_and_b32_sdwa v53, v21, v59 dst_sel:DWORD dst_unused:UNUSED_PAD src0_sel:WORD_1 src1_sel:DWORD
	v_add3_u32 v14, v14, v46, s24
	v_add3_u32 v15, v15, v47, s24
	v_add3_u32 v16, v16, v48, s24
	v_add3_u32 v17, v17, v49, s24
	v_add3_u32 v18, v18, v50, s24
	v_add3_u32 v19, v19, v51, s24
	v_add3_u32 v20, v20, v52, s24
	v_add3_u32 v21, v21, v53, s24
	v_and_b32_e32 v15, 0xffff0000, v15
	v_and_b32_e32 v17, 0xffff0000, v17
	v_and_b32_e32 v19, 0xffff0000, v19
	v_and_b32_e32 v21, 0xffff0000, v21
	v_or_b32_sdwa v60, v15, v14 dst_sel:DWORD dst_unused:UNUSED_PAD src0_sel:DWORD src1_sel:WORD_1
	v_or_b32_sdwa v61, v17, v16 dst_sel:DWORD dst_unused:UNUSED_PAD src0_sel:DWORD src1_sel:WORD_1
	v_or_b32_sdwa v62, v19, v18 dst_sel:DWORD dst_unused:UNUSED_PAD src0_sel:DWORD src1_sel:WORD_1
	v_or_b32_sdwa v63, v21, v20 dst_sel:DWORD dst_unused:UNUSED_PAD src0_sel:DWORD src1_sel:WORD_1
	global_store_dwordx4 v57, v[60:63], s[56:57]
	v_add_u32_e32 v55, 0xc180, v103
	ds_read2_b32 v[30:31], v55 offset0:0 offset1:1
	ds_read2_b32 v[32:33], v55 offset0:2 offset1:3
	ds_read2_b32 v[34:35], v55 offset0:4 offset1:5
	ds_read2_b32 v[36:37], v55 offset0:6 offset1:7
	v_add_u32_e32 v56, 0xe1c0, v103
	ds_read2_b32 v[38:39], v56 offset0:0 offset1:1
	ds_read2_b32 v[40:41], v56 offset0:2 offset1:3
	ds_read2_b32 v[42:43], v56 offset0:4 offset1:5
	ds_read2_b32 v[44:45], v56 offset0:6 offset1:7
	s_waitcnt vmcnt(7) lgkmcnt(8)
	v_fmamk_f32 v54, v10, 0x3a800000, v13
	v_rsq_f32_e32 v54, v54
	v_add_u32_e32 v58, 0xa0000, v4
	v_mul_f32_e32 v22, v22, v54
	v_mul_f32_e32 v23, v23, v54
	v_mul_f32_e32 v24, v24, v54
	v_mul_f32_e32 v25, v25, v54
	v_mul_f32_e32 v26, v26, v54
	v_mul_f32_e32 v27, v27, v54
	v_mul_f32_e32 v28, v28, v54
	v_mul_f32_e32 v29, v29, v54
	v_max_f32_e32 v22, 0, v22
	v_max_f32_e32 v23, 0, v23
	v_max_f32_e32 v24, 0, v24
	v_max_f32_e32 v25, 0, v25
	v_max_f32_e32 v26, 0, v26
	v_max_f32_e32 v27, 0, v27
	v_max_f32_e32 v28, 0, v28
	v_max_f32_e32 v29, 0, v29
	v_pk_mul_f32 v[22:23], v[22:23], v[22:23]
	v_pk_mul_f32 v[24:25], v[24:25], v[24:25]
	v_pk_mul_f32 v[26:27], v[26:27], v[26:27]
	v_pk_mul_f32 v[28:29], v[28:29], v[28:29]
	v_and_b32_sdwa v46, v22, v59 dst_sel:DWORD dst_unused:UNUSED_PAD src0_sel:WORD_1 src1_sel:DWORD
	v_and_b32_sdwa v47, v23, v59 dst_sel:DWORD dst_unused:UNUSED_PAD src0_sel:WORD_1 src1_sel:DWORD
	v_and_b32_sdwa v48, v24, v59 dst_sel:DWORD dst_unused:UNUSED_PAD src0_sel:WORD_1 src1_sel:DWORD
	v_and_b32_sdwa v49, v25, v59 dst_sel:DWORD dst_unused:UNUSED_PAD src0_sel:WORD_1 src1_sel:DWORD
	v_and_b32_sdwa v50, v26, v59 dst_sel:DWORD dst_unused:UNUSED_PAD src0_sel:WORD_1 src1_sel:DWORD
	v_and_b32_sdwa v51, v27, v59 dst_sel:DWORD dst_unused:UNUSED_PAD src0_sel:WORD_1 src1_sel:DWORD
	v_and_b32_sdwa v52, v28, v59 dst_sel:DWORD dst_unused:UNUSED_PAD src0_sel:WORD_1 src1_sel:DWORD
	v_and_b32_sdwa v53, v29, v59 dst_sel:DWORD dst_unused:UNUSED_PAD src0_sel:WORD_1 src1_sel:DWORD
	v_add3_u32 v22, v22, v46, s24
	v_add3_u32 v23, v23, v47, s24
	v_add3_u32 v24, v24, v48, s24
	v_add3_u32 v25, v25, v49, s24
	v_add3_u32 v26, v26, v50, s24
	v_add3_u32 v27, v27, v51, s24
	v_add3_u32 v28, v28, v52, s24
	v_add3_u32 v29, v29, v53, s24
	v_and_b32_e32 v23, 0xffff0000, v23
	v_and_b32_e32 v25, 0xffff0000, v25
	v_and_b32_e32 v27, 0xffff0000, v27
	v_and_b32_e32 v29, 0xffff0000, v29
	v_or_b32_sdwa v76, v23, v22 dst_sel:DWORD dst_unused:UNUSED_PAD src0_sel:DWORD src1_sel:WORD_1
	v_or_b32_sdwa v77, v25, v24 dst_sel:DWORD dst_unused:UNUSED_PAD src0_sel:DWORD src1_sel:WORD_1
	v_or_b32_sdwa v78, v27, v26 dst_sel:DWORD dst_unused:UNUSED_PAD src0_sel:DWORD src1_sel:WORD_1
	v_or_b32_sdwa v79, v29, v28 dst_sel:DWORD dst_unused:UNUSED_PAD src0_sel:DWORD src1_sel:WORD_1
	global_store_dwordx4 v58, v[76:79], s[56:57]
	s_waitcnt vmcnt(7) lgkmcnt(4)
	v_fmamk_f32 v54, v11, 0x3a800000, v13
	v_rsq_f32_e32 v54, v54
	v_add_u32_e32 v57, 0xc0000, v4
	v_mul_f32_e32 v30, v30, v54
	v_mul_f32_e32 v31, v31, v54
	v_mul_f32_e32 v32, v32, v54
	v_mul_f32_e32 v33, v33, v54
	v_mul_f32_e32 v34, v34, v54
	v_mul_f32_e32 v35, v35, v54
	v_mul_f32_e32 v36, v36, v54
	v_mul_f32_e32 v37, v37, v54
	v_max_f32_e32 v30, 0, v30
	v_max_f32_e32 v31, 0, v31
	v_max_f32_e32 v32, 0, v32
	v_max_f32_e32 v33, 0, v33
	v_max_f32_e32 v34, 0, v34
	v_max_f32_e32 v35, 0, v35
	v_max_f32_e32 v36, 0, v36
	v_max_f32_e32 v37, 0, v37
	v_pk_mul_f32 v[30:31], v[30:31], v[30:31]
	v_pk_mul_f32 v[32:33], v[32:33], v[32:33]
	v_pk_mul_f32 v[34:35], v[34:35], v[34:35]
	v_pk_mul_f32 v[36:37], v[36:37], v[36:37]
	v_and_b32_sdwa v46, v30, v59 dst_sel:DWORD dst_unused:UNUSED_PAD src0_sel:WORD_1 src1_sel:DWORD
	v_and_b32_sdwa v47, v31, v59 dst_sel:DWORD dst_unused:UNUSED_PAD src0_sel:WORD_1 src1_sel:DWORD
	v_and_b32_sdwa v48, v32, v59 dst_sel:DWORD dst_unused:UNUSED_PAD src0_sel:WORD_1 src1_sel:DWORD
	v_and_b32_sdwa v49, v33, v59 dst_sel:DWORD dst_unused:UNUSED_PAD src0_sel:WORD_1 src1_sel:DWORD
	v_and_b32_sdwa v50, v34, v59 dst_sel:DWORD dst_unused:UNUSED_PAD src0_sel:WORD_1 src1_sel:DWORD
	v_and_b32_sdwa v51, v35, v59 dst_sel:DWORD dst_unused:UNUSED_PAD src0_sel:WORD_1 src1_sel:DWORD
	v_and_b32_sdwa v52, v36, v59 dst_sel:DWORD dst_unused:UNUSED_PAD src0_sel:WORD_1 src1_sel:DWORD
	v_and_b32_sdwa v53, v37, v59 dst_sel:DWORD dst_unused:UNUSED_PAD src0_sel:WORD_1 src1_sel:DWORD
	v_add3_u32 v30, v30, v46, s24
	v_add3_u32 v31, v31, v47, s24
	v_add3_u32 v32, v32, v48, s24
	v_add3_u32 v33, v33, v49, s24
	v_add3_u32 v34, v34, v50, s24
	v_add3_u32 v35, v35, v51, s24
	v_add3_u32 v36, v36, v52, s24
	v_add3_u32 v37, v37, v53, s24
	v_and_b32_e32 v31, 0xffff0000, v31
	v_and_b32_e32 v33, 0xffff0000, v33
	v_and_b32_e32 v35, 0xffff0000, v35
	v_and_b32_e32 v37, 0xffff0000, v37
	v_or_b32_sdwa v60, v31, v30 dst_sel:DWORD dst_unused:UNUSED_PAD src0_sel:DWORD src1_sel:WORD_1
	v_or_b32_sdwa v61, v33, v32 dst_sel:DWORD dst_unused:UNUSED_PAD src0_sel:DWORD src1_sel:WORD_1
	v_or_b32_sdwa v62, v35, v34 dst_sel:DWORD dst_unused:UNUSED_PAD src0_sel:DWORD src1_sel:WORD_1
	v_or_b32_sdwa v63, v37, v36 dst_sel:DWORD dst_unused:UNUSED_PAD src0_sel:DWORD src1_sel:WORD_1
	global_store_dwordx4 v57, v[60:63], s[56:57]
	s_waitcnt vmcnt(7) lgkmcnt(0)
	v_fmamk_f32 v54, v12, 0x3a800000, v13
	v_rsq_f32_e32 v54, v54
	v_add_u32_e32 v58, 0xe0000, v4
	v_mul_f32_e32 v38, v38, v54
	v_mul_f32_e32 v39, v39, v54
	v_mul_f32_e32 v40, v40, v54
	v_mul_f32_e32 v41, v41, v54
	v_mul_f32_e32 v42, v42, v54
	v_mul_f32_e32 v43, v43, v54
	v_mul_f32_e32 v44, v44, v54
	v_mul_f32_e32 v45, v45, v54
	v_max_f32_e32 v38, 0, v38
	v_max_f32_e32 v39, 0, v39
	v_max_f32_e32 v40, 0, v40
	v_max_f32_e32 v41, 0, v41
	v_max_f32_e32 v42, 0, v42
	v_max_f32_e32 v43, 0, v43
	v_max_f32_e32 v44, 0, v44
	v_max_f32_e32 v45, 0, v45
	v_pk_mul_f32 v[38:39], v[38:39], v[38:39]
	v_pk_mul_f32 v[40:41], v[40:41], v[40:41]
	v_pk_mul_f32 v[42:43], v[42:43], v[42:43]
	v_pk_mul_f32 v[44:45], v[44:45], v[44:45]
	v_and_b32_sdwa v46, v38, v59 dst_sel:DWORD dst_unused:UNUSED_PAD src0_sel:WORD_1 src1_sel:DWORD
	v_and_b32_sdwa v47, v39, v59 dst_sel:DWORD dst_unused:UNUSED_PAD src0_sel:WORD_1 src1_sel:DWORD
	v_and_b32_sdwa v48, v40, v59 dst_sel:DWORD dst_unused:UNUSED_PAD src0_sel:WORD_1 src1_sel:DWORD
	v_and_b32_sdwa v49, v41, v59 dst_sel:DWORD dst_unused:UNUSED_PAD src0_sel:WORD_1 src1_sel:DWORD
	v_and_b32_sdwa v50, v42, v59 dst_sel:DWORD dst_unused:UNUSED_PAD src0_sel:WORD_1 src1_sel:DWORD
	v_and_b32_sdwa v51, v43, v59 dst_sel:DWORD dst_unused:UNUSED_PAD src0_sel:WORD_1 src1_sel:DWORD
	v_and_b32_sdwa v52, v44, v59 dst_sel:DWORD dst_unused:UNUSED_PAD src0_sel:WORD_1 src1_sel:DWORD
	v_and_b32_sdwa v53, v45, v59 dst_sel:DWORD dst_unused:UNUSED_PAD src0_sel:WORD_1 src1_sel:DWORD
	v_add3_u32 v38, v38, v46, s24
	v_add3_u32 v39, v39, v47, s24
	v_add3_u32 v40, v40, v48, s24
	v_add3_u32 v41, v41, v49, s24
	v_add3_u32 v42, v42, v50, s24
	v_add3_u32 v43, v43, v51, s24
	v_add3_u32 v44, v44, v52, s24
	v_add3_u32 v45, v45, v53, s24
	v_and_b32_e32 v39, 0xffff0000, v39
	v_and_b32_e32 v41, 0xffff0000, v41
	v_and_b32_e32 v43, 0xffff0000, v43
	v_and_b32_e32 v45, 0xffff0000, v45
	v_or_b32_sdwa v76, v39, v38 dst_sel:DWORD dst_unused:UNUSED_PAD src0_sel:DWORD src1_sel:WORD_1
	v_or_b32_sdwa v77, v41, v40 dst_sel:DWORD dst_unused:UNUSED_PAD src0_sel:DWORD src1_sel:WORD_1
	v_or_b32_sdwa v78, v43, v42 dst_sel:DWORD dst_unused:UNUSED_PAD src0_sel:DWORD src1_sel:WORD_1
	v_or_b32_sdwa v79, v45, v44 dst_sel:DWORD dst_unused:UNUSED_PAD src0_sel:DWORD src1_sel:WORD_1
	global_store_dwordx4 v58, v[76:79], s[56:57]
	s_cmpk_lt_u32 s13, 0x400
	s_barrier
	s_cbranch_scc1 .LBB0_338

.LBB0_590:
	s_lshr_b32 s8, s12, 2
	s_and_b32 s10, s16, 56
	s_and_b32 s8, s8, 0x1ffffc0
	s_or_b32 s10, s10, s3
	s_or_b32 s8, s10, s8
	s_lshl_b32 s8, s8, 7
	s_lshl_b64 s[24:25], s[8:9], 11
	v_lshl_add_u64 v[78:79], v[70:71], 0, s[24:25]
	v_add_co_u32_e32 v80, vcc, s18, v78
	s_and_b32 s10, s14, 0xf80
	s_nop 0
	v_addc_co_u32_e32 v81, vcc, 0, v79, vcc
	s_lshl_b32 s26, s10, 11
	s_mov_b32 s27, s9
	v_add_co_u32_e32 v82, vcc, s19, v78
	v_lshl_add_u64 v[76:77], v[72:73], 0, s[26:27]
	s_nop 0
	v_addc_co_u32_e32 v83, vcc, 0, v79, vcc
	v_add_co_u32_e32 v84, vcc, s18, v76
	global_load_dwordx4 v[2:5], v[78:79], off
	global_load_dwordx4 v[6:9], v[80:81], off
	v_addc_co_u32_e32 v85, vcc, 0, v77, vcc
	v_add_co_u32_e32 v86, vcc, s19, v76
	global_load_dwordx4 v[10:13], v[82:83], off
	global_load_dwordx4 v[14:17], v[76:77], off
	v_addc_co_u32_e32 v87, vcc, 0, v77, vcc
	global_load_dwordx4 v[18:21], v[84:85], off
	global_load_dwordx4 v[22:25], v[86:87], off
	v_add_co_u32_e32 v88, vcc, s20, v76
	s_nop 1
	v_addc_co_u32_e32 v89, vcc, 0, v77, vcc
	global_load_dwordx4 v[26:29], v[88:89], off
	v_add_co_u32_e32 v90, vcc, s20, v78
	s_nop 1
	v_addc_co_u32_e32 v91, vcc, 0, v79, vcc
	global_load_dwordx4 v[30:33], v[90:91], off
	global_load_dwordx4 v[148:151], v[76:77], off offset:128
	global_load_dwordx4 v[152:155], v[84:85], off offset:128
	global_load_dwordx4 v[156:159], v[86:87], off offset:128
	global_load_dwordx4 v[160:163], v[88:89], off offset:128
	global_load_dwordx4 v[164:167], v[78:79], off offset:128
	global_load_dwordx4 v[168:171], v[80:81], off offset:128
	global_load_dwordx4 v[172:175], v[82:83], off offset:128
	global_load_dwordx4 v[176:179], v[90:91], off offset:128
	s_waitcnt vmcnt(12)
	ds_write_b128 v1, v[14:17] offset:36864
	s_waitcnt vmcnt(11)
	ds_write_b128 v1, v[18:21] offset:41472
	s_waitcnt vmcnt(10)
	ds_write_b128 v1, v[22:25] offset:46080
	s_waitcnt vmcnt(9)
	ds_write_b128 v1, v[26:29] offset:50688
	ds_write_b128 v1, v[2:5]
	ds_write_b128 v1, v[6:9] offset:4608
	ds_write_b128 v1, v[10:13] offset:9216
	s_waitcnt vmcnt(8)
	ds_write_b128 v1, v[30:33] offset:13824
	s_waitcnt lgkmcnt(0)
	s_barrier
	global_load_dwordx4 v[200:203], v[80:81], off offset:256
	global_load_dwordx4 v[204:207], v[82:83], off offset:256
	global_load_dwordx4 v[196:199], v[78:79], off offset:256
	global_load_dwordx4 v[180:183], v[76:77], off offset:256
	global_load_dwordx4 v[208:211], v[90:91], off offset:256
	global_load_dwordx4 v[184:187], v[84:85], off offset:256
	global_load_dwordx4 v[188:191], v[86:87], off offset:256
	global_load_dwordx4 v[192:195], v[88:89], off offset:256
	global_load_dwordx4 v[124:127], v[80:81], off offset:384
	global_load_dwordx4 v[128:131], v[82:83], off offset:384
	global_load_dwordx4 v[120:123], v[78:79], off offset:384
	global_load_dwordx4 v[104:107], v[76:77], off offset:384
	global_load_dwordx4 v[240:243], v[90:91], off offset:384
	global_load_dwordx4 v[108:111], v[84:85], off offset:384
	global_load_dwordx4 v[112:115], v[86:87], off offset:384
	global_load_dwordx4 v[116:119], v[88:89], off offset:384
	ds_read_b128 v[18:21], v66
	ds_read_b128 v[34:37], v67 offset:36864
	ds_read_b128 v[212:215], v66 offset:32
	ds_read_b128 v[216:219], v67 offset:36896
	ds_read_b128 v[50:53], v67 offset:41472
	ds_read_b128 v[220:223], v67 offset:41504
	ds_read_b128 v[54:57], v66 offset:4608
	ds_read_b128 v[224:227], v66 offset:4640
	s_waitcnt lgkmcnt(6)
	v_mfma_f32_32x32x16_bf16 v[2:17], v[18:21], v[34:37], 0
	s_waitcnt lgkmcnt(3)
	v_mfma_f32_32x32x16_bf16 v[18:33], v[18:21], v[50:53], 0
	s_waitcnt lgkmcnt(1)
	v_mfma_f32_32x32x16_bf16 v[34:49], v[54:57], v[34:37], 0
	v_mfma_f32_32x32x16_bf16 v[50:65], v[54:57], v[50:53], 0
	v_mfma_f32_32x32x16_bf16 v[2:17], v[212:215], v[216:219], v[2:17]
	v_mfma_f32_32x32x16_bf16 v[18:33], v[212:215], v[220:223], v[18:33]
	s_waitcnt lgkmcnt(0)
	v_mfma_f32_32x32x16_bf16 v[34:49], v[224:227], v[216:219], v[34:49]
	v_mfma_f32_32x32x16_bf16 v[50:65], v[224:227], v[220:223], v[50:65]
	ds_read_b128 v[212:215], v66 offset:64
	ds_read_b128 v[216:219], v67 offset:36928
	ds_read_b128 v[220:223], v66 offset:96
	ds_read_b128 v[224:227], v67 offset:36960
	ds_read_b128 v[228:231], v67 offset:41536
	ds_read_b128 v[232:235], v67 offset:41568
	s_waitcnt lgkmcnt(4)
	v_mfma_f32_32x32x16_bf16 v[2:17], v[212:215], v[216:219], v[2:17]
	s_waitcnt lgkmcnt(1)
	v_mfma_f32_32x32x16_bf16 v[18:33], v[212:215], v[228:231], v[18:33]
	ds_read_b128 v[212:215], v66 offset:4672
	ds_read_b128 v[236:239], v66 offset:4704
	s_waitcnt vmcnt(16)
	ds_write_b128 v1, v[164:167] offset:18432
	ds_write_b128 v1, v[168:171] offset:23040
	ds_write_b128 v1, v[172:175] offset:27648
	ds_write_b128 v1, v[176:179] offset:32256
	ds_write_b128 v1, v[148:151] offset:55296
	ds_write_b128 v1, v[152:155] offset:59904
	ds_write_b128 v1, v[156:159] offset:64512
	ds_write_b128 v92, v[160:163] offset:32256
	global_load_dwordx4 v[168:171], v[80:81], off offset:512
	global_load_dwordx4 v[172:175], v[82:83], off offset:512
	global_load_dwordx4 v[164:167], v[78:79], off offset:512
	global_load_dwordx4 v[148:151], v[76:77], off offset:512
	global_load_dwordx4 v[176:179], v[90:91], off offset:512
	global_load_dwordx4 v[152:155], v[84:85], off offset:512
	global_load_dwordx4 v[156:159], v[86:87], off offset:512
	global_load_dwordx4 v[160:163], v[88:89], off offset:512
	s_waitcnt lgkmcnt(0)
	s_barrier
	v_mfma_f32_32x32x16_bf16 v[34:49], v[212:215], v[216:219], v[34:49]
	v_mfma_f32_32x32x16_bf16 v[50:65], v[212:215], v[228:231], v[50:65]
	v_mfma_f32_32x32x16_bf16 v[2:17], v[220:223], v[224:227], v[2:17]
	v_mfma_f32_32x32x16_bf16 v[18:33], v[220:223], v[232:235], v[18:33]
	v_mfma_f32_32x32x16_bf16 v[34:49], v[236:239], v[224:227], v[34:49]
	v_mfma_f32_32x32x16_bf16 v[50:65], v[236:239], v[232:235], v[50:65]
	ds_read_b128 v[212:215], v66 offset:18432
	ds_read_b128 v[216:219], v67 offset:55296
	ds_read_b128 v[220:223], v66 offset:18464
	ds_read_b128 v[224:227], v67 offset:55328
	ds_read_b128 v[228:231], v67 offset:59904
	ds_read_b128 v[232:235], v67 offset:59936
	s_waitcnt lgkmcnt(4)
	v_mfma_f32_32x32x16_bf16 v[2:17], v[212:215], v[216:219], v[2:17]
	s_waitcnt lgkmcnt(1)
	v_mfma_f32_32x32x16_bf16 v[18:33], v[212:215], v[228:231], v[18:33]
	ds_read_b128 v[212:215], v66 offset:23040
	ds_read_b128 v[236:239], v66 offset:23072
	s_waitcnt lgkmcnt(1)
	v_mfma_f32_32x32x16_bf16 v[34:49], v[212:215], v[216:219], v[34:49]
	v_mfma_f32_32x32x16_bf16 v[50:65], v[212:215], v[228:231], v[50:65]
	v_mfma_f32_32x32x16_bf16 v[2:17], v[220:223], v[224:227], v[2:17]
	v_mfma_f32_32x32x16_bf16 v[18:33], v[220:223], v[232:235], v[18:33]
	s_waitcnt lgkmcnt(0)
	v_mfma_f32_32x32x16_bf16 v[34:49], v[236:239], v[224:227], v[34:49]
	ds_read_b128 v[212:215], v66 offset:18496
	ds_read_b128 v[216:219], v67 offset:55360
	ds_read_b128 v[220:223], v66 offset:18528
	ds_read_b128 v[224:227], v67 offset:55392
	v_mfma_f32_32x32x16_bf16 v[50:65], v[236:239], v[232:235], v[50:65]
	ds_read_b128 v[228:231], v67 offset:59968
	ds_read_b128 v[232:235], v67 offset:60000
	s_waitcnt lgkmcnt(4)
	v_mfma_f32_32x32x16_bf16 v[2:17], v[212:215], v[216:219], v[2:17]
	s_waitcnt lgkmcnt(1)
	v_mfma_f32_32x32x16_bf16 v[18:33], v[212:215], v[228:231], v[18:33]
	ds_read_b128 v[212:215], v66 offset:23104
	ds_read_b128 v[236:239], v66 offset:23136
	s_waitcnt vmcnt(16)
	ds_write_b128 v1, v[196:199]
	ds_write_b128 v1, v[200:203] offset:4608
	ds_write_b128 v1, v[204:207] offset:9216
	ds_write_b128 v1, v[208:211] offset:13824
	ds_write_b128 v1, v[180:183] offset:36864
	ds_write_b128 v1, v[184:187] offset:41472
	ds_write_b128 v1, v[188:191] offset:46080
	ds_write_b128 v1, v[192:195] offset:50688
	global_load_dwordx4 v[200:203], v[80:81], off offset:640
	global_load_dwordx4 v[204:207], v[82:83], off offset:640
	global_load_dwordx4 v[196:199], v[78:79], off offset:640
	global_load_dwordx4 v[180:183], v[76:77], off offset:640
	global_load_dwordx4 v[208:211], v[90:91], off offset:640
	global_load_dwordx4 v[184:187], v[84:85], off offset:640
	global_load_dwordx4 v[188:191], v[86:87], off offset:640
	global_load_dwordx4 v[192:195], v[88:89], off offset:640
	s_waitcnt lgkmcnt(0)
	s_barrier
	v_mfma_f32_32x32x16_bf16 v[34:49], v[212:215], v[216:219], v[34:49]
	v_mfma_f32_32x32x16_bf16 v[50:65], v[212:215], v[228:231], v[50:65]
	v_mfma_f32_32x32x16_bf16 v[2:17], v[220:223], v[224:227], v[2:17]
	v_mfma_f32_32x32x16_bf16 v[18:33], v[220:223], v[232:235], v[18:33]
	v_mfma_f32_32x32x16_bf16 v[34:49], v[236:239], v[224:227], v[34:49]
	v_mfma_f32_32x32x16_bf16 v[50:65], v[236:239], v[232:235], v[50:65]
	ds_read_b128 v[212:215], v66
	ds_read_b128 v[216:219], v67 offset:36864
	ds_read_b128 v[220:223], v66 offset:32
	ds_read_b128 v[224:227], v67 offset:36896
	ds_read_b128 v[228:231], v67 offset:41472
	ds_read_b128 v[232:235], v67 offset:41504
	s_waitcnt lgkmcnt(4)
	v_mfma_f32_32x32x16_bf16 v[2:17], v[212:215], v[216:219], v[2:17]
	s_waitcnt lgkmcnt(1)
	v_mfma_f32_32x32x16_bf16 v[18:33], v[212:215], v[228:231], v[18:33]
	ds_read_b128 v[212:215], v66 offset:4608
	ds_read_b128 v[236:239], v66 offset:4640
	s_waitcnt lgkmcnt(1)
	v_mfma_f32_32x32x16_bf16 v[34:49], v[212:215], v[216:219], v[34:49]
	v_mfma_f32_32x32x16_bf16 v[50:65], v[212:215], v[228:231], v[50:65]
	v_mfma_f32_32x32x16_bf16 v[2:17], v[220:223], v[224:227], v[2:17]
	v_mfma_f32_32x32x16_bf16 v[18:33], v[220:223], v[232:235], v[18:33]
	s_waitcnt lgkmcnt(0)
	v_mfma_f32_32x32x16_bf16 v[34:49], v[236:239], v[224:227], v[34:49]
	ds_read_b128 v[212:215], v66 offset:64
	ds_read_b128 v[216:219], v67 offset:36928
	ds_read_b128 v[220:223], v66 offset:96
	ds_read_b128 v[224:227], v67 offset:36960
	v_mfma_f32_32x32x16_bf16 v[50:65], v[236:239], v[232:235], v[50:65]
	ds_read_b128 v[228:231], v67 offset:41536
	ds_read_b128 v[232:235], v67 offset:41568
	s_waitcnt lgkmcnt(4)
	v_mfma_f32_32x32x16_bf16 v[2:17], v[212:215], v[216:219], v[2:17]
	s_waitcnt lgkmcnt(1)
	v_mfma_f32_32x32x16_bf16 v[18:33], v[212:215], v[228:231], v[18:33]
	ds_read_b128 v[212:215], v66 offset:4672
	ds_read_b128 v[236:239], v66 offset:4704
	s_waitcnt vmcnt(16)
	ds_write_b128 v1, v[120:123] offset:18432
	ds_write_b128 v1, v[124:127] offset:23040
	ds_write_b128 v1, v[128:131] offset:27648
	ds_write_b128 v1, v[240:243] offset:32256
	ds_write_b128 v1, v[104:107] offset:55296
	ds_write_b128 v1, v[108:111] offset:59904
	ds_write_b128 v1, v[112:115] offset:64512
	ds_write_b128 v92, v[116:119] offset:32256
	global_load_dwordx4 v[124:127], v[80:81], off offset:768
	global_load_dwordx4 v[128:131], v[82:83], off offset:768
	global_load_dwordx4 v[120:123], v[78:79], off offset:768
	global_load_dwordx4 v[104:107], v[76:77], off offset:768
	global_load_dwordx4 v[240:243], v[90:91], off offset:768
	global_load_dwordx4 v[108:111], v[84:85], off offset:768
	global_load_dwordx4 v[112:115], v[86:87], off offset:768
	global_load_dwordx4 v[116:119], v[88:89], off offset:768
	s_waitcnt lgkmcnt(0)
	s_barrier
	v_mfma_f32_32x32x16_bf16 v[34:49], v[212:215], v[216:219], v[34:49]
	v_mfma_f32_32x32x16_bf16 v[50:65], v[212:215], v[228:231], v[50:65]
	v_mfma_f32_32x32x16_bf16 v[2:17], v[220:223], v[224:227], v[2:17]
	v_mfma_f32_32x32x16_bf16 v[18:33], v[220:223], v[232:235], v[18:33]
	v_mfma_f32_32x32x16_bf16 v[34:49], v[236:239], v[224:227], v[34:49]
	v_mfma_f32_32x32x16_bf16 v[50:65], v[236:239], v[232:235], v[50:65]
	ds_read_b128 v[212:215], v66 offset:18432
	ds_read_b128 v[216:219], v67 offset:55296
	ds_read_b128 v[220:223], v66 offset:18464
	ds_read_b128 v[224:227], v67 offset:55328
	ds_read_b128 v[228:231], v67 offset:59904
	ds_read_b128 v[232:235], v67 offset:59936
	s_waitcnt lgkmcnt(4)
	v_mfma_f32_32x32x16_bf16 v[2:17], v[212:215], v[216:219], v[2:17]
	s_waitcnt lgkmcnt(1)
	v_mfma_f32_32x32x16_bf16 v[18:33], v[212:215], v[228:231], v[18:33]
	ds_read_b128 v[212:215], v66 offset:23040
	ds_read_b128 v[236:239], v66 offset:23072
	s_waitcnt lgkmcnt(1)
	v_mfma_f32_32x32x16_bf16 v[34:49], v[212:215], v[216:219], v[34:49]
	v_mfma_f32_32x32x16_bf16 v[50:65], v[212:215], v[228:231], v[50:65]
	v_mfma_f32_32x32x16_bf16 v[2:17], v[220:223], v[224:227], v[2:17]
	v_mfma_f32_32x32x16_bf16 v[18:33], v[220:223], v[232:235], v[18:33]
	s_waitcnt lgkmcnt(0)
	v_mfma_f32_32x32x16_bf16 v[34:49], v[236:239], v[224:227], v[34:49]
	ds_read_b128 v[212:215], v66 offset:18496
	ds_read_b128 v[216:219], v67 offset:55360
	ds_read_b128 v[220:223], v66 offset:18528
	ds_read_b128 v[224:227], v67 offset:55392
	v_mfma_f32_32x32x16_bf16 v[50:65], v[236:239], v[232:235], v[50:65]
	ds_read_b128 v[228:231], v67 offset:59968
	ds_read_b128 v[232:235], v67 offset:60000
	s_waitcnt lgkmcnt(4)
	v_mfma_f32_32x32x16_bf16 v[2:17], v[212:215], v[216:219], v[2:17]
	s_waitcnt lgkmcnt(1)
	v_mfma_f32_32x32x16_bf16 v[18:33], v[212:215], v[228:231], v[18:33]
	ds_read_b128 v[212:215], v66 offset:23104
	ds_read_b128 v[236:239], v66 offset:23136
	s_waitcnt vmcnt(16)
	ds_write_b128 v1, v[164:167]
	ds_write_b128 v1, v[168:171] offset:4608
	ds_write_b128 v1, v[172:175] offset:9216
	ds_write_b128 v1, v[176:179] offset:13824
	ds_write_b128 v1, v[148:151] offset:36864
	ds_write_b128 v1, v[152:155] offset:41472
	ds_write_b128 v1, v[156:159] offset:46080
	ds_write_b128 v1, v[160:163] offset:50688
	global_load_dwordx4 v[168:171], v[80:81], off offset:896
	global_load_dwordx4 v[172:175], v[82:83], off offset:896
	global_load_dwordx4 v[164:167], v[78:79], off offset:896
	global_load_dwordx4 v[148:151], v[76:77], off offset:896
	global_load_dwordx4 v[176:179], v[90:91], off offset:896
	global_load_dwordx4 v[152:155], v[84:85], off offset:896
	global_load_dwordx4 v[156:159], v[86:87], off offset:896
	global_load_dwordx4 v[160:163], v[88:89], off offset:896
	s_waitcnt lgkmcnt(0)
	s_barrier
	v_mfma_f32_32x32x16_bf16 v[34:49], v[212:215], v[216:219], v[34:49]
	v_mfma_f32_32x32x16_bf16 v[50:65], v[212:215], v[228:231], v[50:65]
	v_mfma_f32_32x32x16_bf16 v[2:17], v[220:223], v[224:227], v[2:17]
	v_mfma_f32_32x32x16_bf16 v[18:33], v[220:223], v[232:235], v[18:33]
	v_mfma_f32_32x32x16_bf16 v[34:49], v[236:239], v[224:227], v[34:49]
	v_mfma_f32_32x32x16_bf16 v[50:65], v[236:239], v[232:235], v[50:65]
	ds_read_b128 v[212:215], v66
	ds_read_b128 v[216:219], v67 offset:36864
	ds_read_b128 v[220:223], v66 offset:32
	ds_read_b128 v[224:227], v67 offset:36896
	ds_read_b128 v[228:231], v67 offset:41472
	ds_read_b128 v[232:235], v67 offset:41504
	s_waitcnt lgkmcnt(4)
	v_mfma_f32_32x32x16_bf16 v[2:17], v[212:215], v[216:219], v[2:17]
	s_waitcnt lgkmcnt(1)
	v_mfma_f32_32x32x16_bf16 v[18:33], v[212:215], v[228:231], v[18:33]
	ds_read_b128 v[212:215], v66 offset:4608
	ds_read_b128 v[236:239], v66 offset:4640
	s_waitcnt lgkmcnt(1)
	v_mfma_f32_32x32x16_bf16 v[34:49], v[212:215], v[216:219], v[34:49]
	v_mfma_f32_32x32x16_bf16 v[50:65], v[212:215], v[228:231], v[50:65]
	v_mfma_f32_32x32x16_bf16 v[2:17], v[220:223], v[224:227], v[2:17]
	v_mfma_f32_32x32x16_bf16 v[18:33], v[220:223], v[232:235], v[18:33]
	s_waitcnt lgkmcnt(0)
	v_mfma_f32_32x32x16_bf16 v[34:49], v[236:239], v[224:227], v[34:49]
	ds_read_b128 v[212:215], v66 offset:64
	ds_read_b128 v[216:219], v67 offset:36928
	ds_read_b128 v[220:223], v66 offset:96
	ds_read_b128 v[224:227], v67 offset:36960
	v_mfma_f32_32x32x16_bf16 v[50:65], v[236:239], v[232:235], v[50:65]
	ds_read_b128 v[228:231], v67 offset:41536
	ds_read_b128 v[232:235], v67 offset:41568
	s_waitcnt lgkmcnt(4)
	v_mfma_f32_32x32x16_bf16 v[2:17], v[212:215], v[216:219], v[2:17]
	s_waitcnt lgkmcnt(1)
	v_mfma_f32_32x32x16_bf16 v[18:33], v[212:215], v[228:231], v[18:33]
	ds_read_b128 v[212:215], v66 offset:4672
	ds_read_b128 v[236:239], v66 offset:4704
	s_waitcnt vmcnt(16)
	ds_write_b128 v1, v[196:199] offset:18432
	ds_write_b128 v1, v[200:203] offset:23040
	ds_write_b128 v1, v[204:207] offset:27648
	ds_write_b128 v1, v[208:211] offset:32256
	ds_write_b128 v1, v[180:183] offset:55296
	ds_write_b128 v1, v[184:187] offset:59904
	ds_write_b128 v1, v[188:191] offset:64512
	ds_write_b128 v92, v[192:195] offset:32256
	global_load_dwordx4 v[200:203], v[80:81], off offset:1024
	global_load_dwordx4 v[204:207], v[82:83], off offset:1024
	global_load_dwordx4 v[196:199], v[78:79], off offset:1024
	global_load_dwordx4 v[180:183], v[76:77], off offset:1024
	global_load_dwordx4 v[208:211], v[90:91], off offset:1024
	global_load_dwordx4 v[184:187], v[84:85], off offset:1024
	global_load_dwordx4 v[188:191], v[86:87], off offset:1024
	global_load_dwordx4 v[192:195], v[88:89], off offset:1024
	s_waitcnt lgkmcnt(0)
	s_barrier
	v_mfma_f32_32x32x16_bf16 v[34:49], v[212:215], v[216:219], v[34:49]
	v_mfma_f32_32x32x16_bf16 v[50:65], v[212:215], v[228:231], v[50:65]
	v_mfma_f32_32x32x16_bf16 v[2:17], v[220:223], v[224:227], v[2:17]
	v_mfma_f32_32x32x16_bf16 v[18:33], v[220:223], v[232:235], v[18:33]
	v_mfma_f32_32x32x16_bf16 v[34:49], v[236:239], v[224:227], v[34:49]
	v_mfma_f32_32x32x16_bf16 v[50:65], v[236:239], v[232:235], v[50:65]
	ds_read_b128 v[212:215], v66 offset:18432
	ds_read_b128 v[216:219], v67 offset:55296
	ds_read_b128 v[220:223], v66 offset:18464
	ds_read_b128 v[224:227], v67 offset:55328
	ds_read_b128 v[228:231], v67 offset:59904
	ds_read_b128 v[232:235], v67 offset:59936
	s_waitcnt lgkmcnt(4)
	v_mfma_f32_32x32x16_bf16 v[2:17], v[212:215], v[216:219], v[2:17]
	s_waitcnt lgkmcnt(1)
	v_mfma_f32_32x32x16_bf16 v[18:33], v[212:215], v[228:231], v[18:33]
	ds_read_b128 v[212:215], v66 offset:23040
	ds_read_b128 v[236:239], v66 offset:23072
	s_waitcnt lgkmcnt(1)
	v_mfma_f32_32x32x16_bf16 v[34:49], v[212:215], v[216:219], v[34:49]
	v_mfma_f32_32x32x16_bf16 v[50:65], v[212:215], v[228:231], v[50:65]
	v_mfma_f32_32x32x16_bf16 v[2:17], v[220:223], v[224:227], v[2:17]
	v_mfma_f32_32x32x16_bf16 v[18:33], v[220:223], v[232:235], v[18:33]
	s_waitcnt lgkmcnt(0)
	v_mfma_f32_32x32x16_bf16 v[34:49], v[236:239], v[224:227], v[34:49]
	ds_read_b128 v[212:215], v66 offset:18496
	ds_read_b128 v[216:219], v67 offset:55360
	ds_read_b128 v[220:223], v66 offset:18528
	ds_read_b128 v[224:227], v67 offset:55392
	v_mfma_f32_32x32x16_bf16 v[50:65], v[236:239], v[232:235], v[50:65]
	ds_read_b128 v[228:231], v67 offset:59968
	ds_read_b128 v[232:235], v67 offset:60000
	s_waitcnt lgkmcnt(4)
	v_mfma_f32_32x32x16_bf16 v[2:17], v[212:215], v[216:219], v[2:17]
	s_waitcnt lgkmcnt(1)
	v_mfma_f32_32x32x16_bf16 v[18:33], v[212:215], v[228:231], v[18:33]
	ds_read_b128 v[212:215], v66 offset:23104
	ds_read_b128 v[236:239], v66 offset:23136
	s_waitcnt vmcnt(16)
	ds_write_b128 v1, v[120:123]
	ds_write_b128 v1, v[124:127] offset:4608
	ds_write_b128 v1, v[128:131] offset:9216
	ds_write_b128 v1, v[240:243] offset:13824
	ds_write_b128 v1, v[104:107] offset:36864
	ds_write_b128 v1, v[108:111] offset:41472
	ds_write_b128 v1, v[112:115] offset:46080
	ds_write_b128 v1, v[116:119] offset:50688
	global_load_dwordx4 v[124:127], v[80:81], off offset:1152
	global_load_dwordx4 v[128:131], v[82:83], off offset:1152
	global_load_dwordx4 v[120:123], v[78:79], off offset:1152
	global_load_dwordx4 v[104:107], v[76:77], off offset:1152
	global_load_dwordx4 v[240:243], v[90:91], off offset:1152
	global_load_dwordx4 v[108:111], v[84:85], off offset:1152
	global_load_dwordx4 v[112:115], v[86:87], off offset:1152
	global_load_dwordx4 v[116:119], v[88:89], off offset:1152
	s_waitcnt lgkmcnt(0)
	s_barrier
	v_mfma_f32_32x32x16_bf16 v[34:49], v[212:215], v[216:219], v[34:49]
	v_mfma_f32_32x32x16_bf16 v[50:65], v[212:215], v[228:231], v[50:65]
	v_mfma_f32_32x32x16_bf16 v[2:17], v[220:223], v[224:227], v[2:17]
	v_mfma_f32_32x32x16_bf16 v[18:33], v[220:223], v[232:235], v[18:33]
	v_mfma_f32_32x32x16_bf16 v[34:49], v[236:239], v[224:227], v[34:49]
	v_mfma_f32_32x32x16_bf16 v[50:65], v[236:239], v[232:235], v[50:65]
	ds_read_b128 v[212:215], v66
	ds_read_b128 v[216:219], v67 offset:36864
	ds_read_b128 v[220:223], v66 offset:32
	ds_read_b128 v[224:227], v67 offset:36896
	ds_read_b128 v[228:231], v67 offset:41472
	ds_read_b128 v[232:235], v67 offset:41504
	s_waitcnt lgkmcnt(4)
	v_mfma_f32_32x32x16_bf16 v[2:17], v[212:215], v[216:219], v[2:17]
	s_waitcnt lgkmcnt(1)
	v_mfma_f32_32x32x16_bf16 v[18:33], v[212:215], v[228:231], v[18:33]
	ds_read_b128 v[212:215], v66 offset:4608
	ds_read_b128 v[236:239], v66 offset:4640
	s_waitcnt lgkmcnt(1)
	v_mfma_f32_32x32x16_bf16 v[34:49], v[212:215], v[216:219], v[34:49]
	v_mfma_f32_32x32x16_bf16 v[50:65], v[212:215], v[228:231], v[50:65]
	v_mfma_f32_32x32x16_bf16 v[2:17], v[220:223], v[224:227], v[2:17]
	v_mfma_f32_32x32x16_bf16 v[18:33], v[220:223], v[232:235], v[18:33]
	s_waitcnt lgkmcnt(0)
	v_mfma_f32_32x32x16_bf16 v[34:49], v[236:239], v[224:227], v[34:49]
	ds_read_b128 v[212:215], v66 offset:64
	ds_read_b128 v[216:219], v67 offset:36928
	ds_read_b128 v[220:223], v66 offset:96
	ds_read_b128 v[224:227], v67 offset:36960
	v_mfma_f32_32x32x16_bf16 v[50:65], v[236:239], v[232:235], v[50:65]
	ds_read_b128 v[228:231], v67 offset:41536
	ds_read_b128 v[232:235], v67 offset:41568
	s_waitcnt lgkmcnt(4)
	v_mfma_f32_32x32x16_bf16 v[2:17], v[212:215], v[216:219], v[2:17]
	s_waitcnt lgkmcnt(1)
	v_mfma_f32_32x32x16_bf16 v[18:33], v[212:215], v[228:231], v[18:33]
	ds_read_b128 v[212:215], v66 offset:4672
	ds_read_b128 v[236:239], v66 offset:4704
	s_waitcnt vmcnt(16)
	ds_write_b128 v1, v[164:167] offset:18432
	ds_write_b128 v1, v[168:171] offset:23040
	ds_write_b128 v1, v[172:175] offset:27648
	ds_write_b128 v1, v[176:179] offset:32256
	ds_write_b128 v1, v[148:151] offset:55296
	ds_write_b128 v1, v[152:155] offset:59904
	ds_write_b128 v1, v[156:159] offset:64512
	ds_write_b128 v92, v[160:163] offset:32256
	global_load_dwordx4 v[168:171], v[80:81], off offset:1280
	global_load_dwordx4 v[172:175], v[82:83], off offset:1280
	global_load_dwordx4 v[164:167], v[78:79], off offset:1280
	global_load_dwordx4 v[148:151], v[76:77], off offset:1280
	global_load_dwordx4 v[176:179], v[90:91], off offset:1280
	global_load_dwordx4 v[152:155], v[84:85], off offset:1280
	global_load_dwordx4 v[156:159], v[86:87], off offset:1280
	global_load_dwordx4 v[160:163], v[88:89], off offset:1280
	s_waitcnt lgkmcnt(0)
	s_barrier
	v_mfma_f32_32x32x16_bf16 v[34:49], v[212:215], v[216:219], v[34:49]
	v_mfma_f32_32x32x16_bf16 v[50:65], v[212:215], v[228:231], v[50:65]
	v_mfma_f32_32x32x16_bf16 v[2:17], v[220:223], v[224:227], v[2:17]
	v_mfma_f32_32x32x16_bf16 v[18:33], v[220:223], v[232:235], v[18:33]
	v_mfma_f32_32x32x16_bf16 v[34:49], v[236:239], v[224:227], v[34:49]
	v_mfma_f32_32x32x16_bf16 v[50:65], v[236:239], v[232:235], v[50:65]
	ds_read_b128 v[212:215], v66 offset:18432
	ds_read_b128 v[216:219], v67 offset:55296
	ds_read_b128 v[220:223], v66 offset:18464
	ds_read_b128 v[224:227], v67 offset:55328
	ds_read_b128 v[228:231], v67 offset:59904
	ds_read_b128 v[232:235], v67 offset:59936
	s_waitcnt lgkmcnt(4)
	v_mfma_f32_32x32x16_bf16 v[2:17], v[212:215], v[216:219], v[2:17]
	s_waitcnt lgkmcnt(1)
	v_mfma_f32_32x32x16_bf16 v[18:33], v[212:215], v[228:231], v[18:33]
	ds_read_b128 v[212:215], v66 offset:23040
	ds_read_b128 v[236:239], v66 offset:23072
	s_waitcnt lgkmcnt(1)
	v_mfma_f32_32x32x16_bf16 v[34:49], v[212:215], v[216:219], v[34:49]
	v_mfma_f32_32x32x16_bf16 v[50:65], v[212:215], v[228:231], v[50:65]
	v_mfma_f32_32x32x16_bf16 v[2:17], v[220:223], v[224:227], v[2:17]
	v_mfma_f32_32x32x16_bf16 v[18:33], v[220:223], v[232:235], v[18:33]
	s_waitcnt lgkmcnt(0)
	v_mfma_f32_32x32x16_bf16 v[34:49], v[236:239], v[224:227], v[34:49]
	ds_read_b128 v[212:215], v66 offset:18496
	ds_read_b128 v[216:219], v67 offset:55360
	ds_read_b128 v[220:223], v66 offset:18528
	ds_read_b128 v[224:227], v67 offset:55392
	v_mfma_f32_32x32x16_bf16 v[50:65], v[236:239], v[232:235], v[50:65]
	ds_read_b128 v[228:231], v67 offset:59968
	ds_read_b128 v[232:235], v67 offset:60000
	s_waitcnt lgkmcnt(4)
	v_mfma_f32_32x32x16_bf16 v[2:17], v[212:215], v[216:219], v[2:17]
	s_waitcnt lgkmcnt(1)
	v_mfma_f32_32x32x16_bf16 v[18:33], v[212:215], v[228:231], v[18:33]
	ds_read_b128 v[212:215], v66 offset:23104
	ds_read_b128 v[236:239], v66 offset:23136
	s_waitcnt vmcnt(16)
	ds_write_b128 v1, v[196:199]
	ds_write_b128 v1, v[200:203] offset:4608
	ds_write_b128 v1, v[204:207] offset:9216
	ds_write_b128 v1, v[208:211] offset:13824
	ds_write_b128 v1, v[180:183] offset:36864
	ds_write_b128 v1, v[184:187] offset:41472
	ds_write_b128 v1, v[188:191] offset:46080
	ds_write_b128 v1, v[192:195] offset:50688
	global_load_dwordx4 v[200:203], v[80:81], off offset:1408
	global_load_dwordx4 v[204:207], v[82:83], off offset:1408
	global_load_dwordx4 v[196:199], v[78:79], off offset:1408
	global_load_dwordx4 v[180:183], v[76:77], off offset:1408
	global_load_dwordx4 v[208:211], v[90:91], off offset:1408
	global_load_dwordx4 v[184:187], v[84:85], off offset:1408
	global_load_dwordx4 v[188:191], v[86:87], off offset:1408
	global_load_dwordx4 v[192:195], v[88:89], off offset:1408
	s_waitcnt lgkmcnt(0)
	s_barrier
	v_mfma_f32_32x32x16_bf16 v[34:49], v[212:215], v[216:219], v[34:49]
	v_mfma_f32_32x32x16_bf16 v[50:65], v[212:215], v[228:231], v[50:65]
	v_mfma_f32_32x32x16_bf16 v[2:17], v[220:223], v[224:227], v[2:17]
	v_mfma_f32_32x32x16_bf16 v[18:33], v[220:223], v[232:235], v[18:33]
	v_mfma_f32_32x32x16_bf16 v[34:49], v[236:239], v[224:227], v[34:49]
	v_mfma_f32_32x32x16_bf16 v[50:65], v[236:239], v[232:235], v[50:65]
	ds_read_b128 v[212:215], v66
	ds_read_b128 v[216:219], v67 offset:36864
	ds_read_b128 v[220:223], v66 offset:32
	ds_read_b128 v[224:227], v67 offset:36896
	ds_read_b128 v[228:231], v67 offset:41472
	ds_read_b128 v[232:235], v67 offset:41504
	s_waitcnt lgkmcnt(4)
	v_mfma_f32_32x32x16_bf16 v[2:17], v[212:215], v[216:219], v[2:17]
	s_waitcnt lgkmcnt(1)
	v_mfma_f32_32x32x16_bf16 v[18:33], v[212:215], v[228:231], v[18:33]
	ds_read_b128 v[212:215], v66 offset:4608
	ds_read_b128 v[236:239], v66 offset:4640
	s_waitcnt lgkmcnt(1)
	v_mfma_f32_32x32x16_bf16 v[34:49], v[212:215], v[216:219], v[34:49]
	v_mfma_f32_32x32x16_bf16 v[50:65], v[212:215], v[228:231], v[50:65]
	v_mfma_f32_32x32x16_bf16 v[2:17], v[220:223], v[224:227], v[2:17]
	v_mfma_f32_32x32x16_bf16 v[18:33], v[220:223], v[232:235], v[18:33]
	s_waitcnt lgkmcnt(0)
	v_mfma_f32_32x32x16_bf16 v[34:49], v[236:239], v[224:227], v[34:49]
	ds_read_b128 v[212:215], v66 offset:64
	ds_read_b128 v[216:219], v67 offset:36928
	ds_read_b128 v[220:223], v66 offset:96
	ds_read_b128 v[224:227], v67 offset:36960
	v_mfma_f32_32x32x16_bf16 v[50:65], v[236:239], v[232:235], v[50:65]
	ds_read_b128 v[228:231], v67 offset:41536
	ds_read_b128 v[232:235], v67 offset:41568
	s_waitcnt lgkmcnt(4)
	v_mfma_f32_32x32x16_bf16 v[2:17], v[212:215], v[216:219], v[2:17]
	s_waitcnt lgkmcnt(1)
	v_mfma_f32_32x32x16_bf16 v[18:33], v[212:215], v[228:231], v[18:33]
	ds_read_b128 v[212:215], v66 offset:4672
	ds_read_b128 v[236:239], v66 offset:4704
	s_waitcnt vmcnt(16)
	ds_write_b128 v1, v[120:123] offset:18432
	ds_write_b128 v1, v[124:127] offset:23040
	ds_write_b128 v1, v[128:131] offset:27648
	ds_write_b128 v1, v[240:243] offset:32256
	ds_write_b128 v1, v[104:107] offset:55296
	ds_write_b128 v1, v[108:111] offset:59904
	ds_write_b128 v1, v[112:115] offset:64512
	ds_write_b128 v92, v[116:119] offset:32256
	global_load_dwordx4 v[124:127], v[80:81], off offset:1536
	global_load_dwordx4 v[128:131], v[82:83], off offset:1536
	global_load_dwordx4 v[120:123], v[78:79], off offset:1536
	global_load_dwordx4 v[104:107], v[76:77], off offset:1536
	global_load_dwordx4 v[240:243], v[90:91], off offset:1536
	global_load_dwordx4 v[108:111], v[84:85], off offset:1536
	global_load_dwordx4 v[112:115], v[86:87], off offset:1536
	global_load_dwordx4 v[116:119], v[88:89], off offset:1536
	s_waitcnt lgkmcnt(0)
	s_barrier
	v_mfma_f32_32x32x16_bf16 v[34:49], v[212:215], v[216:219], v[34:49]
	v_mfma_f32_32x32x16_bf16 v[50:65], v[212:215], v[228:231], v[50:65]
	v_mfma_f32_32x32x16_bf16 v[2:17], v[220:223], v[224:227], v[2:17]
	v_mfma_f32_32x32x16_bf16 v[18:33], v[220:223], v[232:235], v[18:33]
	v_mfma_f32_32x32x16_bf16 v[34:49], v[236:239], v[224:227], v[34:49]
	v_mfma_f32_32x32x16_bf16 v[50:65], v[236:239], v[232:235], v[50:65]
	ds_read_b128 v[212:215], v66 offset:18432
	ds_read_b128 v[216:219], v67 offset:55296
	ds_read_b128 v[220:223], v66 offset:18464
	ds_read_b128 v[224:227], v67 offset:55328
	ds_read_b128 v[228:231], v67 offset:59904
	ds_read_b128 v[232:235], v67 offset:59936
	s_waitcnt lgkmcnt(4)
	v_mfma_f32_32x32x16_bf16 v[2:17], v[212:215], v[216:219], v[2:17]
	s_waitcnt lgkmcnt(1)
	v_mfma_f32_32x32x16_bf16 v[18:33], v[212:215], v[228:231], v[18:33]
	ds_read_b128 v[212:215], v66 offset:23040
	ds_read_b128 v[236:239], v66 offset:23072
	s_waitcnt lgkmcnt(1)
	v_mfma_f32_32x32x16_bf16 v[34:49], v[212:215], v[216:219], v[34:49]
	v_mfma_f32_32x32x16_bf16 v[50:65], v[212:215], v[228:231], v[50:65]
	v_mfma_f32_32x32x16_bf16 v[2:17], v[220:223], v[224:227], v[2:17]
	v_mfma_f32_32x32x16_bf16 v[18:33], v[220:223], v[232:235], v[18:33]
	s_waitcnt lgkmcnt(0)
	v_mfma_f32_32x32x16_bf16 v[34:49], v[236:239], v[224:227], v[34:49]
	ds_read_b128 v[212:215], v66 offset:18496
	ds_read_b128 v[216:219], v67 offset:55360
	ds_read_b128 v[220:223], v66 offset:18528
	ds_read_b128 v[224:227], v67 offset:55392
	v_mfma_f32_32x32x16_bf16 v[50:65], v[236:239], v[232:235], v[50:65]
	ds_read_b128 v[228:231], v67 offset:59968
	ds_read_b128 v[232:235], v67 offset:60000
	s_waitcnt lgkmcnt(4)
	v_mfma_f32_32x32x16_bf16 v[2:17], v[212:215], v[216:219], v[2:17]
	s_waitcnt lgkmcnt(1)
	v_mfma_f32_32x32x16_bf16 v[18:33], v[212:215], v[228:231], v[18:33]
	ds_read_b128 v[212:215], v66 offset:23104
	ds_read_b128 v[236:239], v66 offset:23136
	s_waitcnt vmcnt(16)
	ds_write_b128 v1, v[164:167]
	ds_write_b128 v1, v[168:171] offset:4608
	ds_write_b128 v1, v[172:175] offset:9216
	ds_write_b128 v1, v[176:179] offset:13824
	ds_write_b128 v1, v[148:151] offset:36864
	ds_write_b128 v1, v[152:155] offset:41472
	ds_write_b128 v1, v[156:159] offset:46080
	ds_write_b128 v1, v[160:163] offset:50688
	global_load_dwordx4 v[168:171], v[80:81], off offset:1664
	global_load_dwordx4 v[172:175], v[82:83], off offset:1664
	global_load_dwordx4 v[164:167], v[78:79], off offset:1664
	global_load_dwordx4 v[148:151], v[76:77], off offset:1664
	global_load_dwordx4 v[176:179], v[90:91], off offset:1664
	global_load_dwordx4 v[152:155], v[84:85], off offset:1664
	global_load_dwordx4 v[156:159], v[86:87], off offset:1664
	global_load_dwordx4 v[160:163], v[88:89], off offset:1664
	s_waitcnt lgkmcnt(0)
	s_barrier
	v_mfma_f32_32x32x16_bf16 v[34:49], v[212:215], v[216:219], v[34:49]
	v_mfma_f32_32x32x16_bf16 v[50:65], v[212:215], v[228:231], v[50:65]
	v_mfma_f32_32x32x16_bf16 v[2:17], v[220:223], v[224:227], v[2:17]
	v_mfma_f32_32x32x16_bf16 v[18:33], v[220:223], v[232:235], v[18:33]
	v_mfma_f32_32x32x16_bf16 v[34:49], v[236:239], v[224:227], v[34:49]
	v_mfma_f32_32x32x16_bf16 v[50:65], v[236:239], v[232:235], v[50:65]
	ds_read_b128 v[212:215], v66
	ds_read_b128 v[216:219], v67 offset:36864
	ds_read_b128 v[220:223], v66 offset:32
	ds_read_b128 v[224:227], v67 offset:36896
	ds_read_b128 v[228:231], v67 offset:41472
	ds_read_b128 v[232:235], v67 offset:41504
	s_waitcnt lgkmcnt(4)
	v_mfma_f32_32x32x16_bf16 v[2:17], v[212:215], v[216:219], v[2:17]
	s_waitcnt lgkmcnt(1)
	v_mfma_f32_32x32x16_bf16 v[18:33], v[212:215], v[228:231], v[18:33]
	ds_read_b128 v[212:215], v66 offset:4608
	ds_read_b128 v[236:239], v66 offset:4640
	s_waitcnt lgkmcnt(1)
	v_mfma_f32_32x32x16_bf16 v[34:49], v[212:215], v[216:219], v[34:49]
	v_mfma_f32_32x32x16_bf16 v[50:65], v[212:215], v[228:231], v[50:65]
	v_mfma_f32_32x32x16_bf16 v[2:17], v[220:223], v[224:227], v[2:17]
	v_mfma_f32_32x32x16_bf16 v[18:33], v[220:223], v[232:235], v[18:33]
	s_waitcnt lgkmcnt(0)
	v_mfma_f32_32x32x16_bf16 v[34:49], v[236:239], v[224:227], v[34:49]
	ds_read_b128 v[212:215], v66 offset:64
	ds_read_b128 v[216:219], v67 offset:36928
	ds_read_b128 v[220:223], v66 offset:96
	ds_read_b128 v[224:227], v67 offset:36960
	v_mfma_f32_32x32x16_bf16 v[50:65], v[236:239], v[232:235], v[50:65]
	ds_read_b128 v[228:231], v67 offset:41536
	ds_read_b128 v[232:235], v67 offset:41568
	s_waitcnt lgkmcnt(4)
	v_mfma_f32_32x32x16_bf16 v[2:17], v[212:215], v[216:219], v[2:17]
	s_waitcnt lgkmcnt(1)
	v_mfma_f32_32x32x16_bf16 v[18:33], v[212:215], v[228:231], v[18:33]
	ds_read_b128 v[212:215], v66 offset:4672
	ds_read_b128 v[236:239], v66 offset:4704
	s_waitcnt vmcnt(16)
	ds_write_b128 v1, v[196:199] offset:18432
	ds_write_b128 v1, v[200:203] offset:23040
	ds_write_b128 v1, v[204:207] offset:27648
	ds_write_b128 v1, v[208:211] offset:32256
	ds_write_b128 v1, v[180:183] offset:55296
	ds_write_b128 v1, v[184:187] offset:59904
	ds_write_b128 v1, v[188:191] offset:64512
	ds_write_b128 v92, v[192:195] offset:32256
	global_load_dwordx4 v[200:203], v[80:81], off offset:1792
	global_load_dwordx4 v[204:207], v[82:83], off offset:1792
	global_load_dwordx4 v[196:199], v[78:79], off offset:1792
	global_load_dwordx4 v[180:183], v[76:77], off offset:1792
	global_load_dwordx4 v[208:211], v[90:91], off offset:1792
	global_load_dwordx4 v[184:187], v[84:85], off offset:1792
	global_load_dwordx4 v[188:191], v[86:87], off offset:1792
	global_load_dwordx4 v[192:195], v[88:89], off offset:1792
	s_waitcnt lgkmcnt(0)
	s_barrier
	v_mfma_f32_32x32x16_bf16 v[34:49], v[212:215], v[216:219], v[34:49]
	v_mfma_f32_32x32x16_bf16 v[50:65], v[212:215], v[228:231], v[50:65]
	v_mfma_f32_32x32x16_bf16 v[2:17], v[220:223], v[224:227], v[2:17]
	v_mfma_f32_32x32x16_bf16 v[18:33], v[220:223], v[232:235], v[18:33]
	v_mfma_f32_32x32x16_bf16 v[34:49], v[236:239], v[224:227], v[34:49]
	v_mfma_f32_32x32x16_bf16 v[50:65], v[236:239], v[232:235], v[50:65]
	ds_read_b128 v[212:215], v66 offset:18432
	ds_read_b128 v[216:219], v67 offset:55296
	ds_read_b128 v[220:223], v66 offset:18464
	ds_read_b128 v[224:227], v67 offset:55328
	ds_read_b128 v[228:231], v67 offset:59904
	ds_read_b128 v[232:235], v67 offset:59936
	s_waitcnt lgkmcnt(4)
	v_mfma_f32_32x32x16_bf16 v[2:17], v[212:215], v[216:219], v[2:17]
	s_waitcnt lgkmcnt(1)
	v_mfma_f32_32x32x16_bf16 v[18:33], v[212:215], v[228:231], v[18:33]
	ds_read_b128 v[212:215], v66 offset:23040
	ds_read_b128 v[236:239], v66 offset:23072
	s_waitcnt lgkmcnt(1)
	v_mfma_f32_32x32x16_bf16 v[34:49], v[212:215], v[216:219], v[34:49]
	v_mfma_f32_32x32x16_bf16 v[50:65], v[212:215], v[228:231], v[50:65]
	v_mfma_f32_32x32x16_bf16 v[2:17], v[220:223], v[224:227], v[2:17]
	v_mfma_f32_32x32x16_bf16 v[18:33], v[220:223], v[232:235], v[18:33]
	s_waitcnt lgkmcnt(0)
	v_mfma_f32_32x32x16_bf16 v[34:49], v[236:239], v[224:227], v[34:49]
	ds_read_b128 v[212:215], v66 offset:18496
	ds_read_b128 v[216:219], v67 offset:55360
	ds_read_b128 v[220:223], v66 offset:18528
	ds_read_b128 v[224:227], v67 offset:55392
	v_mfma_f32_32x32x16_bf16 v[50:65], v[236:239], v[232:235], v[50:65]
	ds_read_b128 v[228:231], v67 offset:59968
	ds_read_b128 v[232:235], v67 offset:60000
	s_waitcnt lgkmcnt(4)
	v_mfma_f32_32x32x16_bf16 v[2:17], v[212:215], v[216:219], v[2:17]
	s_waitcnt lgkmcnt(1)
	v_mfma_f32_32x32x16_bf16 v[18:33], v[212:215], v[228:231], v[18:33]
	ds_read_b128 v[212:215], v66 offset:23104
	ds_read_b128 v[236:239], v66 offset:23136
	s_waitcnt vmcnt(16)
	ds_write_b128 v1, v[120:123]
	ds_write_b128 v1, v[124:127] offset:4608
	ds_write_b128 v1, v[128:131] offset:9216
	ds_write_b128 v1, v[240:243] offset:13824
	ds_write_b128 v1, v[104:107] offset:36864
	ds_write_b128 v1, v[108:111] offset:41472
	ds_write_b128 v1, v[112:115] offset:46080
	ds_write_b128 v1, v[116:119] offset:50688
	global_load_dwordx4 v[124:127], v[80:81], off offset:1920
	global_load_dwordx4 v[128:131], v[82:83], off offset:1920
	global_load_dwordx4 v[120:123], v[78:79], off offset:1920
	global_load_dwordx4 v[104:107], v[76:77], off offset:1920
	global_load_dwordx4 v[240:243], v[90:91], off offset:1920
	global_load_dwordx4 v[108:111], v[84:85], off offset:1920
	global_load_dwordx4 v[112:115], v[86:87], off offset:1920
	global_load_dwordx4 v[116:119], v[88:89], off offset:1920
	s_waitcnt lgkmcnt(0)
	s_barrier
	v_mfma_f32_32x32x16_bf16 v[34:49], v[212:215], v[216:219], v[34:49]
	v_mfma_f32_32x32x16_bf16 v[50:65], v[212:215], v[228:231], v[50:65]
	v_mfma_f32_32x32x16_bf16 v[2:17], v[220:223], v[224:227], v[2:17]
	v_mfma_f32_32x32x16_bf16 v[18:33], v[220:223], v[232:235], v[18:33]
	v_mfma_f32_32x32x16_bf16 v[34:49], v[236:239], v[224:227], v[34:49]
	v_mfma_f32_32x32x16_bf16 v[50:65], v[236:239], v[232:235], v[50:65]
	ds_read_b128 v[212:215], v66
	ds_read_b128 v[216:219], v67 offset:36864
	ds_read_b128 v[220:223], v66 offset:32
	ds_read_b128 v[224:227], v67 offset:36896
	ds_read_b128 v[228:231], v67 offset:41472
	ds_read_b128 v[232:235], v67 offset:41504
	s_waitcnt lgkmcnt(4)
	v_mfma_f32_32x32x16_bf16 v[2:17], v[212:215], v[216:219], v[2:17]
	s_waitcnt lgkmcnt(1)
	v_mfma_f32_32x32x16_bf16 v[18:33], v[212:215], v[228:231], v[18:33]
	ds_read_b128 v[212:215], v66 offset:4608
	ds_read_b128 v[236:239], v66 offset:4640
	s_waitcnt lgkmcnt(1)
	v_mfma_f32_32x32x16_bf16 v[34:49], v[212:215], v[216:219], v[34:49]
	v_mfma_f32_32x32x16_bf16 v[50:65], v[212:215], v[228:231], v[50:65]
	v_mfma_f32_32x32x16_bf16 v[2:17], v[220:223], v[224:227], v[2:17]
	v_mfma_f32_32x32x16_bf16 v[18:33], v[220:223], v[232:235], v[18:33]
	s_waitcnt lgkmcnt(0)
	v_mfma_f32_32x32x16_bf16 v[34:49], v[236:239], v[224:227], v[34:49]
	ds_read_b128 v[212:215], v66 offset:64
	ds_read_b128 v[216:219], v67 offset:36928
	ds_read_b128 v[220:223], v66 offset:96
	ds_read_b128 v[224:227], v67 offset:36960
	v_mfma_f32_32x32x16_bf16 v[50:65], v[236:239], v[232:235], v[50:65]
	ds_read_b128 v[228:231], v67 offset:41536
	ds_read_b128 v[232:235], v67 offset:41568
	s_waitcnt lgkmcnt(4)
	v_mfma_f32_32x32x16_bf16 v[2:17], v[212:215], v[216:219], v[2:17]
	s_waitcnt lgkmcnt(1)
	v_mfma_f32_32x32x16_bf16 v[18:33], v[212:215], v[228:231], v[18:33]
	ds_read_b128 v[212:215], v66 offset:4672
	ds_read_b128 v[236:239], v66 offset:4704
	s_waitcnt vmcnt(16)
	ds_write_b128 v1, v[164:167] offset:18432
	ds_write_b128 v1, v[168:171] offset:23040
	ds_write_b128 v1, v[172:175] offset:27648
	ds_write_b128 v1, v[176:179] offset:32256
	ds_write_b128 v1, v[148:151] offset:55296
	ds_write_b128 v1, v[152:155] offset:59904
	ds_write_b128 v1, v[156:159] offset:64512
	ds_write_b128 v92, v[160:163] offset:32256
	s_waitcnt lgkmcnt(0)
	s_barrier
	v_mfma_f32_32x32x16_bf16 v[34:49], v[212:215], v[216:219], v[34:49]
	v_mfma_f32_32x32x16_bf16 v[50:65], v[212:215], v[228:231], v[50:65]
	v_mfma_f32_32x32x16_bf16 v[2:17], v[220:223], v[224:227], v[2:17]
	v_mfma_f32_32x32x16_bf16 v[18:33], v[220:223], v[232:235], v[18:33]
	v_mfma_f32_32x32x16_bf16 v[34:49], v[236:239], v[224:227], v[34:49]
	v_mfma_f32_32x32x16_bf16 v[50:65], v[236:239], v[232:235], v[50:65]
	ds_read_b128 v[164:167], v66 offset:18432
	ds_read_b128 v[168:171], v67 offset:55296
	ds_read_b128 v[172:175], v66 offset:18464
	ds_read_b128 v[176:179], v67 offset:55328
	ds_read_b128 v[212:215], v67 offset:59904
	ds_read_b128 v[216:219], v67 offset:59936
	s_waitcnt lgkmcnt(4)
	v_mfma_f32_32x32x16_bf16 v[2:17], v[164:167], v[168:171], v[2:17]
	s_waitcnt lgkmcnt(1)
	v_mfma_f32_32x32x16_bf16 v[18:33], v[164:167], v[212:215], v[18:33]
	ds_read_b128 v[164:167], v66 offset:23040
	ds_read_b128 v[220:223], v66 offset:23072
	s_waitcnt lgkmcnt(1)
	v_mfma_f32_32x32x16_bf16 v[34:49], v[164:167], v[168:171], v[34:49]
	v_mfma_f32_32x32x16_bf16 v[50:65], v[164:167], v[212:215], v[50:65]
	v_mfma_f32_32x32x16_bf16 v[2:17], v[172:175], v[176:179], v[2:17]
	v_mfma_f32_32x32x16_bf16 v[18:33], v[172:175], v[216:219], v[18:33]
	s_waitcnt lgkmcnt(0)
	v_mfma_f32_32x32x16_bf16 v[34:49], v[220:223], v[176:179], v[34:49]
	ds_read_b128 v[164:167], v66 offset:18496
	ds_read_b128 v[168:171], v67 offset:55360
	ds_read_b128 v[172:175], v66 offset:18528
	ds_read_b128 v[176:179], v67 offset:55392
	v_mfma_f32_32x32x16_bf16 v[50:65], v[220:223], v[216:219], v[50:65]
	ds_read_b128 v[212:215], v67 offset:59968
	ds_read_b128 v[216:219], v67 offset:60000
	s_waitcnt lgkmcnt(4)
	v_mfma_f32_32x32x16_bf16 v[2:17], v[164:167], v[168:171], v[2:17]
	s_waitcnt lgkmcnt(1)
	v_mfma_f32_32x32x16_bf16 v[18:33], v[164:167], v[212:215], v[18:33]
	ds_read_b128 v[164:167], v66 offset:23104
	ds_read_b128 v[220:223], v66 offset:23136
	s_waitcnt vmcnt(8)
	ds_write_b128 v1, v[196:199]
	ds_write_b128 v1, v[200:203] offset:4608
	ds_write_b128 v1, v[204:207] offset:9216
	ds_write_b128 v1, v[208:211] offset:13824
	ds_write_b128 v1, v[180:183] offset:36864
	ds_write_b128 v1, v[184:187] offset:41472
	ds_write_b128 v1, v[188:191] offset:46080
	ds_write_b128 v1, v[192:195] offset:50688
	s_waitcnt lgkmcnt(0)
	s_barrier
	v_mfma_f32_32x32x16_bf16 v[34:49], v[164:167], v[168:171], v[34:49]
	v_mfma_f32_32x32x16_bf16 v[50:65], v[164:167], v[212:215], v[50:65]
	v_mfma_f32_32x32x16_bf16 v[2:17], v[172:175], v[176:179], v[2:17]
	v_mfma_f32_32x32x16_bf16 v[18:33], v[172:175], v[216:219], v[18:33]
	v_mfma_f32_32x32x16_bf16 v[34:49], v[220:223], v[176:179], v[34:49]
	v_mfma_f32_32x32x16_bf16 v[50:65], v[220:223], v[216:219], v[50:65]
	ds_read_b128 v[164:167], v66
	ds_read_b128 v[168:171], v67 offset:36864
	ds_read_b128 v[172:175], v66 offset:32
	ds_read_b128 v[176:179], v67 offset:36896
	ds_read_b128 v[180:183], v67 offset:41472
	ds_read_b128 v[184:187], v67 offset:41504
	s_waitcnt lgkmcnt(4)
	v_mfma_f32_32x32x16_bf16 v[2:17], v[164:167], v[168:171], v[2:17]
	s_waitcnt lgkmcnt(1)
	v_mfma_f32_32x32x16_bf16 v[18:33], v[164:167], v[180:183], v[18:33]
	ds_read_b128 v[164:167], v66 offset:4608
	ds_read_b128 v[188:191], v66 offset:4640
	s_waitcnt lgkmcnt(1)
	v_mfma_f32_32x32x16_bf16 v[34:49], v[164:167], v[168:171], v[34:49]
	v_mfma_f32_32x32x16_bf16 v[50:65], v[164:167], v[180:183], v[50:65]
	v_mfma_f32_32x32x16_bf16 v[2:17], v[172:175], v[176:179], v[2:17]
	v_mfma_f32_32x32x16_bf16 v[18:33], v[172:175], v[184:187], v[18:33]
	s_waitcnt lgkmcnt(0)
	v_mfma_f32_32x32x16_bf16 v[34:49], v[188:191], v[176:179], v[34:49]
	ds_read_b128 v[164:167], v66 offset:64
	ds_read_b128 v[168:171], v67 offset:36928
	ds_read_b128 v[172:175], v66 offset:96
	ds_read_b128 v[176:179], v67 offset:36960
	v_mfma_f32_32x32x16_bf16 v[50:65], v[188:191], v[184:187], v[50:65]
	ds_read_b128 v[180:183], v67 offset:41536
	ds_read_b128 v[184:187], v67 offset:41568
	s_waitcnt lgkmcnt(4)
	v_mfma_f32_32x32x16_bf16 v[2:17], v[164:167], v[168:171], v[2:17]
	s_waitcnt lgkmcnt(1)
	v_mfma_f32_32x32x16_bf16 v[18:33], v[164:167], v[180:183], v[18:33]
	ds_read_b128 v[164:167], v66 offset:4672
	ds_read_b128 v[188:191], v66 offset:4704
	s_waitcnt vmcnt(0)
	ds_write_b128 v1, v[120:123] offset:18432
	ds_write_b128 v1, v[124:127] offset:23040
	ds_write_b128 v1, v[128:131] offset:27648
	ds_write_b128 v1, v[240:243] offset:32256
	ds_write_b128 v1, v[104:107] offset:55296
	ds_write_b128 v1, v[108:111] offset:59904
	ds_write_b128 v1, v[112:115] offset:64512
	ds_write_b128 v92, v[116:119] offset:32256
	s_waitcnt lgkmcnt(0)
	s_barrier
	v_mfma_f32_32x32x16_bf16 v[34:49], v[164:167], v[168:171], v[34:49]
	v_mfma_f32_32x32x16_bf16 v[50:65], v[164:167], v[180:183], v[50:65]
	v_mfma_f32_32x32x16_bf16 v[2:17], v[172:175], v[176:179], v[2:17]
	v_mfma_f32_32x32x16_bf16 v[18:33], v[172:175], v[184:187], v[18:33]
	v_mfma_f32_32x32x16_bf16 v[34:49], v[188:191], v[176:179], v[34:49]
	v_mfma_f32_32x32x16_bf16 v[50:65], v[188:191], v[184:187], v[50:65]
	ds_read_b128 v[76:79], v66 offset:18432
	ds_read_b128 v[80:83], v67 offset:55296
	ds_read_b128 v[84:87], v66 offset:18464
	ds_read_b128 v[88:91], v67 offset:55328
	ds_read_b128 v[148:151], v67 offset:59904
	ds_read_b128 v[152:155], v67 offset:59936
	v_or_b32_e32 v68, s8, v94
	s_waitcnt lgkmcnt(4)
	v_mfma_f32_32x32x16_bf16 v[2:17], v[76:79], v[80:83], v[2:17]
	s_lshl_b32 s10, s10, 1
	s_mov_b32 s11, s9
	s_add_i32 s12, s12, s13
	s_add_i32 s14, s14, s15
	s_add_i32 s16, s16, s17
	s_cmpk_lt_u32 s12, 0x400
	s_waitcnt lgkmcnt(1)
	v_mfma_f32_32x32x16_bf16 v[18:33], v[76:79], v[148:151], v[18:33]
	ds_read_b128 v[76:79], v66 offset:23040
	ds_read_b128 v[156:159], v66 offset:23072
	s_waitcnt lgkmcnt(1)
	v_mfma_f32_32x32x16_bf16 v[34:49], v[76:79], v[80:83], v[34:49]
	v_mfma_f32_32x32x16_bf16 v[50:65], v[76:79], v[148:151], v[50:65]
	v_mfma_f32_32x32x16_bf16 v[2:17], v[84:87], v[88:91], v[2:17]
	v_mfma_f32_32x32x16_bf16 v[18:33], v[84:87], v[152:155], v[18:33]
	s_waitcnt lgkmcnt(0)
	v_mfma_f32_32x32x16_bf16 v[34:49], v[156:159], v[88:91], v[34:49]
	ds_read_b128 v[76:79], v66 offset:18496
	ds_read_b128 v[80:83], v67 offset:55360
	ds_read_b128 v[84:87], v66 offset:18528
	ds_read_b128 v[88:91], v67 offset:55392
	v_mfma_f32_32x32x16_bf16 v[50:65], v[156:159], v[152:155], v[50:65]
	ds_read_b128 v[148:151], v67 offset:59968
	ds_read_b128 v[152:155], v67 offset:60000
	s_waitcnt lgkmcnt(4)
	v_mfma_f32_32x32x16_bf16 v[2:17], v[76:79], v[80:83], v[2:17]
	s_waitcnt lgkmcnt(1)
	v_mfma_f32_32x32x16_bf16 v[18:33], v[76:79], v[148:151], v[18:33]
	ds_read_b128 v[76:79], v66 offset:23104
	ds_read_b128 v[156:159], v66 offset:23136
	s_waitcnt lgkmcnt(0)
	s_barrier
	v_mfma_f32_32x32x16_bf16 v[34:49], v[76:79], v[80:83], v[34:49]
	v_mfma_f32_32x32x16_bf16 v[50:65], v[76:79], v[148:151], v[50:65]
	v_mfma_f32_32x32x16_bf16 v[2:17], v[84:87], v[88:91], v[2:17]
	v_mfma_f32_32x32x16_bf16 v[18:33], v[84:87], v[152:155], v[18:33]
	v_mfma_f32_32x32x16_bf16 v[34:49], v[156:159], v[88:91], v[34:49]
	s_nop 10
	ds_write2_b32 v93, v2, v18 offset1:32
	v_mfma_f32_32x32x16_bf16 v[50:65], v[156:159], v[152:155], v[50:65]
	s_nop 11
	ds_write2_b32 v132, v34, v50 offset0:32 offset1:64
	ds_write2_b32 v93, v3, v19 offset0:129 offset1:161
	ds_write2_b32 v132, v35, v51 offset0:161 offset1:193
	ds_write2_b32 v133, v4, v20 offset0:2 offset1:34
	ds_write2_b32 v134, v36, v52 offset0:34 offset1:66
	ds_write2_b32 v133, v5, v21 offset0:131 offset1:163
	ds_write2_b32 v134, v37, v53 offset0:163 offset1:195
	ds_write2_b32 v135, v6, v22 offset0:8 offset1:40
	ds_write2_b32 v136, v38, v54 offset0:40 offset1:72
	ds_write2_b32 v135, v7, v23 offset0:137 offset1:169
	ds_write2_b32 v136, v39, v55 offset0:169 offset1:201
	ds_write2_b32 v137, v8, v24 offset0:10 offset1:42
	ds_write2_b32 v138, v40, v56 offset0:42 offset1:74
	ds_write2_b32 v137, v9, v25 offset0:139 offset1:171
	ds_write2_b32 v138, v41, v57 offset0:171 offset1:203
	ds_write2_b32 v139, v10, v26 offset0:16 offset1:48
	ds_write2_b32 v140, v42, v58 offset0:48 offset1:80
	ds_write2_b32 v139, v11, v27 offset0:145 offset1:177
	ds_write2_b32 v140, v43, v59 offset0:177 offset1:209
	ds_write2_b32 v141, v12, v28 offset0:18 offset1:50
	ds_write2_b32 v142, v44, v60 offset0:50 offset1:82
	ds_write2_b32 v141, v13, v29 offset0:147 offset1:179
	ds_write2_b32 v142, v45, v61 offset0:179 offset1:211
	ds_write2_b32 v143, v14, v30 offset0:24 offset1:56
	ds_write2_b32 v144, v46, v62 offset0:56 offset1:88
	ds_write2_b32 v143, v15, v31 offset0:153 offset1:185
	ds_write2_b32 v144, v47, v63 offset0:185 offset1:217
	ds_write2_b32 v145, v16, v32 offset0:26 offset1:58
	ds_write2_b32 v146, v48, v64 offset0:58 offset1:90
	ds_write2_b32 v145, v17, v33 offset0:155 offset1:187
	ds_write2_b32 v146, v49, v65 offset0:187 offset1:219
	v_lshl_add_u64 v[2:3], v[68:69], 2, s[6:7]
	s_waitcnt lgkmcnt(0)
	s_barrier
	v_mov_b32_e32 v2, v68
	v_lshlrev_b32_e32 v3, 2, v2
	global_load_dword v5, v3, s[6:7]
	global_load_dword v6, v3, s[6:7] offset:64
	global_load_dword v7, v3, s[6:7] offset:128
	global_load_dword v8, v3, s[6:7] offset:192
	global_load_dword v9, v3, s[6:7] offset:256
	global_load_dword v10, v3, s[6:7] offset:320
	global_load_dword v11, v3, s[6:7] offset:384
	global_load_dword v12, v3, s[6:7] offset:448
	v_lshlrev_b32_e32 v4, 13, v2
	v_add3_u32 v4, v4, v74, s10
	s_movk_i32 s24, 0x7fff
	v_mov_b32_e32 v59, 1
	v_mov_b32_e32 v13, 0x358637bd
	ds_read2_b32 v[14:15], v103 offset0:0 offset1:1
	ds_read2_b32 v[16:17], v103 offset0:2 offset1:3
	ds_read2_b32 v[18:19], v103 offset0:4 offset1:5
	ds_read2_b32 v[20:21], v103 offset0:6 offset1:7
	v_add_u32_e32 v56, 0x2040, v103
	ds_read2_b32 v[22:23], v56 offset0:0 offset1:1
	ds_read2_b32 v[24:25], v56 offset0:2 offset1:3
	ds_read2_b32 v[26:27], v56 offset0:4 offset1:5
	ds_read2_b32 v[28:29], v56 offset0:6 offset1:7
	s_waitcnt vmcnt(7) lgkmcnt(4)
	v_fmamk_f32 v54, v5, 0x3a800000, v13
	v_rsq_f32_e32 v54, v54
	s_nop 0
	v_mul_f32_e32 v14, v14, v54
	v_mul_f32_e32 v15, v15, v54
	v_mul_f32_e32 v16, v16, v54
	v_mul_f32_e32 v17, v17, v54
	v_mul_f32_e32 v18, v18, v54
	v_mul_f32_e32 v19, v19, v54
	v_mul_f32_e32 v20, v20, v54
	v_mul_f32_e32 v21, v21, v54
	v_max_f32_e32 v14, 0, v14
	v_max_f32_e32 v15, 0, v15
	v_max_f32_e32 v16, 0, v16
	v_max_f32_e32 v17, 0, v17
	v_max_f32_e32 v18, 0, v18
	v_max_f32_e32 v19, 0, v19
	v_max_f32_e32 v20, 0, v20
	v_max_f32_e32 v21, 0, v21
	v_pk_mul_f32 v[14:15], v[14:15], v[14:15]
	v_pk_mul_f32 v[16:17], v[16:17], v[16:17]
	v_pk_mul_f32 v[18:19], v[18:19], v[18:19]
	v_pk_mul_f32 v[20:21], v[20:21], v[20:21]
	v_and_b32_sdwa v46, v14, v59 dst_sel:DWORD dst_unused:UNUSED_PAD src0_sel:WORD_1 src1_sel:DWORD
	v_and_b32_sdwa v47, v15, v59 dst_sel:DWORD dst_unused:UNUSED_PAD src0_sel:WORD_1 src1_sel:DWORD
	v_and_b32_sdwa v48, v16, v59 dst_sel:DWORD dst_unused:UNUSED_PAD src0_sel:WORD_1 src1_sel:DWORD
	v_and_b32_sdwa v49, v17, v59 dst_sel:DWORD dst_unused:UNUSED_PAD src0_sel:WORD_1 src1_sel:DWORD
	v_and_b32_sdwa v50, v18, v59 dst_sel:DWORD dst_unused:UNUSED_PAD src0_sel:WORD_1 src1_sel:DWORD
	v_and_b32_sdwa v51, v19, v59 dst_sel:DWORD dst_unused:UNUSED_PAD src0_sel:WORD_1 src1_sel:DWORD
	v_and_b32_sdwa v52, v20, v59 dst_sel:DWORD dst_unused:UNUSED_PAD src0_sel:WORD_1 src1_sel:DWORD
	v_and_b32_sdwa v53, v21, v59 dst_sel:DWORD dst_unused:UNUSED_PAD src0_sel:WORD_1 src1_sel:DWORD
	v_add3_u32 v14, v14, v46, s24
	v_add3_u32 v15, v15, v47, s24
	v_add3_u32 v16, v16, v48, s24
	v_add3_u32 v17, v17, v49, s24
	v_add3_u32 v18, v18, v50, s24
	v_add3_u32 v19, v19, v51, s24
	v_add3_u32 v20, v20, v52, s24
	v_add3_u32 v21, v21, v53, s24
	v_and_b32_e32 v15, 0xffff0000, v15
	v_and_b32_e32 v17, 0xffff0000, v17
	v_and_b32_e32 v19, 0xffff0000, v19
	v_and_b32_e32 v21, 0xffff0000, v21
	v_or_b32_sdwa v60, v15, v14 dst_sel:DWORD dst_unused:UNUSED_PAD src0_sel:DWORD src1_sel:WORD_1
	v_or_b32_sdwa v61, v17, v16 dst_sel:DWORD dst_unused:UNUSED_PAD src0_sel:DWORD src1_sel:WORD_1
	v_or_b32_sdwa v62, v19, v18 dst_sel:DWORD dst_unused:UNUSED_PAD src0_sel:DWORD src1_sel:WORD_1
	v_or_b32_sdwa v63, v21, v20 dst_sel:DWORD dst_unused:UNUSED_PAD src0_sel:DWORD src1_sel:WORD_1
	global_store_dwordx4 v4, v[60:63], s[56:57]
	v_add_u32_e32 v55, 0x4080, v103
	ds_read2_b32 v[30:31], v55 offset0:0 offset1:1
	ds_read2_b32 v[32:33], v55 offset0:2 offset1:3
	ds_read2_b32 v[34:35], v55 offset0:4 offset1:5
	ds_read2_b32 v[36:37], v55 offset0:6 offset1:7
	v_add_u32_e32 v56, 0x60c0, v103
	ds_read2_b32 v[38:39], v56 offset0:0 offset1:1
	ds_read2_b32 v[40:41], v56 offset0:2 offset1:3
	ds_read2_b32 v[42:43], v56 offset0:4 offset1:5
	ds_read2_b32 v[44:45], v56 offset0:6 offset1:7
	s_waitcnt vmcnt(7) lgkmcnt(8)
	v_fmamk_f32 v54, v6, 0x3a800000, v13
	v_rsq_f32_e32 v54, v54
	v_add_u32_e32 v58, 0x20000, v4
	v_mul_f32_e32 v22, v22, v54
	v_mul_f32_e32 v23, v23, v54
	v_mul_f32_e32 v24, v24, v54
	v_mul_f32_e32 v25, v25, v54
	v_mul_f32_e32 v26, v26, v54
	v_mul_f32_e32 v27, v27, v54
	v_mul_f32_e32 v28, v28, v54
	v_mul_f32_e32 v29, v29, v54
	v_max_f32_e32 v22, 0, v22
	v_max_f32_e32 v23, 0, v23
	v_max_f32_e32 v24, 0, v24
	v_max_f32_e32 v25, 0, v25
	v_max_f32_e32 v26, 0, v26
	v_max_f32_e32 v27, 0, v27
	v_max_f32_e32 v28, 0, v28
	v_max_f32_e32 v29, 0, v29
	v_pk_mul_f32 v[22:23], v[22:23], v[22:23]
	v_pk_mul_f32 v[24:25], v[24:25], v[24:25]
	v_pk_mul_f32 v[26:27], v[26:27], v[26:27]
	v_pk_mul_f32 v[28:29], v[28:29], v[28:29]
	v_and_b32_sdwa v46, v22, v59 dst_sel:DWORD dst_unused:UNUSED_PAD src0_sel:WORD_1 src1_sel:DWORD
	v_and_b32_sdwa v47, v23, v59 dst_sel:DWORD dst_unused:UNUSED_PAD src0_sel:WORD_1 src1_sel:DWORD
	v_and_b32_sdwa v48, v24, v59 dst_sel:DWORD dst_unused:UNUSED_PAD src0_sel:WORD_1 src1_sel:DWORD
	v_and_b32_sdwa v49, v25, v59 dst_sel:DWORD dst_unused:UNUSED_PAD src0_sel:WORD_1 src1_sel:DWORD
	v_and_b32_sdwa v50, v26, v59 dst_sel:DWORD dst_unused:UNUSED_PAD src0_sel:WORD_1 src1_sel:DWORD
	v_and_b32_sdwa v51, v27, v59 dst_sel:DWORD dst_unused:UNUSED_PAD src0_sel:WORD_1 src1_sel:DWORD
	v_and_b32_sdwa v52, v28, v59 dst_sel:DWORD dst_unused:UNUSED_PAD src0_sel:WORD_1 src1_sel:DWORD
	v_and_b32_sdwa v53, v29, v59 dst_sel:DWORD dst_unused:UNUSED_PAD src0_sel:WORD_1 src1_sel:DWORD
	v_add3_u32 v22, v22, v46, s24
	v_add3_u32 v23, v23, v47, s24
	v_add3_u32 v24, v24, v48, s24
	v_add3_u32 v25, v25, v49, s24
	v_add3_u32 v26, v26, v50, s24
	v_add3_u32 v27, v27, v51, s24
	v_add3_u32 v28, v28, v52, s24
	v_add3_u32 v29, v29, v53, s24
	v_and_b32_e32 v23, 0xffff0000, v23
	v_and_b32_e32 v25, 0xffff0000, v25
	v_and_b32_e32 v27, 0xffff0000, v27
	v_and_b32_e32 v29, 0xffff0000, v29
	v_or_b32_sdwa v76, v23, v22 dst_sel:DWORD dst_unused:UNUSED_PAD src0_sel:DWORD src1_sel:WORD_1
	v_or_b32_sdwa v77, v25, v24 dst_sel:DWORD dst_unused:UNUSED_PAD src0_sel:DWORD src1_sel:WORD_1
	v_or_b32_sdwa v78, v27, v26 dst_sel:DWORD dst_unused:UNUSED_PAD src0_sel:DWORD src1_sel:WORD_1
	v_or_b32_sdwa v79, v29, v28 dst_sel:DWORD dst_unused:UNUSED_PAD src0_sel:DWORD src1_sel:WORD_1
	global_store_dwordx4 v58, v[76:79], s[56:57]
	s_waitcnt vmcnt(7) lgkmcnt(4)
	v_fmamk_f32 v54, v7, 0x3a800000, v13
	v_rsq_f32_e32 v54, v54
	v_add_u32_e32 v57, 0x40000, v4
	v_mul_f32_e32 v30, v30, v54
	v_mul_f32_e32 v31, v31, v54
	v_mul_f32_e32 v32, v32, v54
	v_mul_f32_e32 v33, v33, v54
	v_mul_f32_e32 v34, v34, v54
	v_mul_f32_e32 v35, v35, v54
	v_mul_f32_e32 v36, v36, v54
	v_mul_f32_e32 v37, v37, v54
	v_max_f32_e32 v30, 0, v30
	v_max_f32_e32 v31, 0, v31
	v_max_f32_e32 v32, 0, v32
	v_max_f32_e32 v33, 0, v33
	v_max_f32_e32 v34, 0, v34
	v_max_f32_e32 v35, 0, v35
	v_max_f32_e32 v36, 0, v36
	v_max_f32_e32 v37, 0, v37
	v_pk_mul_f32 v[30:31], v[30:31], v[30:31]
	v_pk_mul_f32 v[32:33], v[32:33], v[32:33]
	v_pk_mul_f32 v[34:35], v[34:35], v[34:35]
	v_pk_mul_f32 v[36:37], v[36:37], v[36:37]
	v_and_b32_sdwa v46, v30, v59 dst_sel:DWORD dst_unused:UNUSED_PAD src0_sel:WORD_1 src1_sel:DWORD
	v_and_b32_sdwa v47, v31, v59 dst_sel:DWORD dst_unused:UNUSED_PAD src0_sel:WORD_1 src1_sel:DWORD
	v_and_b32_sdwa v48, v32, v59 dst_sel:DWORD dst_unused:UNUSED_PAD src0_sel:WORD_1 src1_sel:DWORD
	v_and_b32_sdwa v49, v33, v59 dst_sel:DWORD dst_unused:UNUSED_PAD src0_sel:WORD_1 src1_sel:DWORD
	v_and_b32_sdwa v50, v34, v59 dst_sel:DWORD dst_unused:UNUSED_PAD src0_sel:WORD_1 src1_sel:DWORD
	v_and_b32_sdwa v51, v35, v59 dst_sel:DWORD dst_unused:UNUSED_PAD src0_sel:WORD_1 src1_sel:DWORD
	v_and_b32_sdwa v52, v36, v59 dst_sel:DWORD dst_unused:UNUSED_PAD src0_sel:WORD_1 src1_sel:DWORD
	v_and_b32_sdwa v53, v37, v59 dst_sel:DWORD dst_unused:UNUSED_PAD src0_sel:WORD_1 src1_sel:DWORD
	v_add3_u32 v30, v30, v46, s24
	v_add3_u32 v31, v31, v47, s24
	v_add3_u32 v32, v32, v48, s24
	v_add3_u32 v33, v33, v49, s24
	v_add3_u32 v34, v34, v50, s24
	v_add3_u32 v35, v35, v51, s24
	v_add3_u32 v36, v36, v52, s24
	v_add3_u32 v37, v37, v53, s24
	v_and_b32_e32 v31, 0xffff0000, v31
	v_and_b32_e32 v33, 0xffff0000, v33
	v_and_b32_e32 v35, 0xffff0000, v35
	v_and_b32_e32 v37, 0xffff0000, v37
	v_or_b32_sdwa v60, v31, v30 dst_sel:DWORD dst_unused:UNUSED_PAD src0_sel:DWORD src1_sel:WORD_1
	v_or_b32_sdwa v61, v33, v32 dst_sel:DWORD dst_unused:UNUSED_PAD src0_sel:DWORD src1_sel:WORD_1
	v_or_b32_sdwa v62, v35, v34 dst_sel:DWORD dst_unused:UNUSED_PAD src0_sel:DWORD src1_sel:WORD_1
	v_or_b32_sdwa v63, v37, v36 dst_sel:DWORD dst_unused:UNUSED_PAD src0_sel:DWORD src1_sel:WORD_1
	global_store_dwordx4 v57, v[60:63], s[56:57]
	v_add_u32_e32 v55, 0x8100, v103
	ds_read2_b32 v[14:15], v55 offset0:0 offset1:1
	ds_read2_b32 v[16:17], v55 offset0:2 offset1:3
	ds_read2_b32 v[18:19], v55 offset0:4 offset1:5
	ds_read2_b32 v[20:21], v55 offset0:6 offset1:7
	v_add_u32_e32 v56, 0xa140, v103
	ds_read2_b32 v[22:23], v56 offset0:0 offset1:1
	ds_read2_b32 v[24:25], v56 offset0:2 offset1:3
	ds_read2_b32 v[26:27], v56 offset0:4 offset1:5
	ds_read2_b32 v[28:29], v56 offset0:6 offset1:7
	s_waitcnt vmcnt(7) lgkmcnt(8)
	v_fmamk_f32 v54, v8, 0x3a800000, v13
	v_rsq_f32_e32 v54, v54
	v_add_u32_e32 v58, 0x60000, v4
	v_mul_f32_e32 v38, v38, v54
	v_mul_f32_e32 v39, v39, v54
	v_mul_f32_e32 v40, v40, v54
	v_mul_f32_e32 v41, v41, v54
	v_mul_f32_e32 v42, v42, v54
	v_mul_f32_e32 v43, v43, v54
	v_mul_f32_e32 v44, v44, v54
	v_mul_f32_e32 v45, v45, v54
	v_max_f32_e32 v38, 0, v38
	v_max_f32_e32 v39, 0, v39
	v_max_f32_e32 v40, 0, v40
	v_max_f32_e32 v41, 0, v41
	v_max_f32_e32 v42, 0, v42
	v_max_f32_e32 v43, 0, v43
	v_max_f32_e32 v44, 0, v44
	v_max_f32_e32 v45, 0, v45
	v_pk_mul_f32 v[38:39], v[38:39], v[38:39]
	v_pk_mul_f32 v[40:41], v[40:41], v[40:41]
	v_pk_mul_f32 v[42:43], v[42:43], v[42:43]
	v_pk_mul_f32 v[44:45], v[44:45], v[44:45]
	v_and_b32_sdwa v46, v38, v59 dst_sel:DWORD dst_unused:UNUSED_PAD src0_sel:WORD_1 src1_sel:DWORD
	v_and_b32_sdwa v47, v39, v59 dst_sel:DWORD dst_unused:UNUSED_PAD src0_sel:WORD_1 src1_sel:DWORD
	v_and_b32_sdwa v48, v40, v59 dst_sel:DWORD dst_unused:UNUSED_PAD src0_sel:WORD_1 src1_sel:DWORD
	v_and_b32_sdwa v49, v41, v59 dst_sel:DWORD dst_unused:UNUSED_PAD src0_sel:WORD_1 src1_sel:DWORD
	v_and_b32_sdwa v50, v42, v59 dst_sel:DWORD dst_unused:UNUSED_PAD src0_sel:WORD_1 src1_sel:DWORD
	v_and_b32_sdwa v51, v43, v59 dst_sel:DWORD dst_unused:UNUSED_PAD src0_sel:WORD_1 src1_sel:DWORD
	v_and_b32_sdwa v52, v44, v59 dst_sel:DWORD dst_unused:UNUSED_PAD src0_sel:WORD_1 src1_sel:DWORD
	v_and_b32_sdwa v53, v45, v59 dst_sel:DWORD dst_unused:UNUSED_PAD src0_sel:WORD_1 src1_sel:DWORD
	v_add3_u32 v38, v38, v46, s24
	v_add3_u32 v39, v39, v47, s24
	v_add3_u32 v40, v40, v48, s24
	v_add3_u32 v41, v41, v49, s24
	v_add3_u32 v42, v42, v50, s24
	v_add3_u32 v43, v43, v51, s24
	v_add3_u32 v44, v44, v52, s24
	v_add3_u32 v45, v45, v53, s24
	v_and_b32_e32 v39, 0xffff0000, v39
	v_and_b32_e32 v41, 0xffff0000, v41
	v_and_b32_e32 v43, 0xffff0000, v43
	v_and_b32_e32 v45, 0xffff0000, v45
	v_or_b32_sdwa v76, v39, v38 dst_sel:DWORD dst_unused:UNUSED_PAD src0_sel:DWORD src1_sel:WORD_1
	v_or_b32_sdwa v77, v41, v40 dst_sel:DWORD dst_unused:UNUSED_PAD src0_sel:DWORD src1_sel:WORD_1
	v_or_b32_sdwa v78, v43, v42 dst_sel:DWORD dst_unused:UNUSED_PAD src0_sel:DWORD src1_sel:WORD_1
	v_or_b32_sdwa v79, v45, v44 dst_sel:DWORD dst_unused:UNUSED_PAD src0_sel:DWORD src1_sel:WORD_1
	global_store_dwordx4 v58, v[76:79], s[56:57]
	s_waitcnt vmcnt(7) lgkmcnt(4)
	v_fmamk_f32 v54, v9, 0x3a800000, v13
	v_rsq_f32_e32 v54, v54
	v_add_u32_e32 v57, 0x80000, v4
	v_mul_f32_e32 v14, v14, v54
	v_mul_f32_e32 v15, v15, v54
	v_mul_f32_e32 v16, v16, v54
	v_mul_f32_e32 v17, v17, v54
	v_mul_f32_e32 v18, v18, v54
	v_mul_f32_e32 v19, v19, v54
	v_mul_f32_e32 v20, v20, v54
	v_mul_f32_e32 v21, v21, v54
	v_max_f32_e32 v14, 0, v14
	v_max_f32_e32 v15, 0, v15
	v_max_f32_e32 v16, 0, v16
	v_max_f32_e32 v17, 0, v17
	v_max_f32_e32 v18, 0, v18
	v_max_f32_e32 v19, 0, v19
	v_max_f32_e32 v20, 0, v20
	v_max_f32_e32 v21, 0, v21
	v_pk_mul_f32 v[14:15], v[14:15], v[14:15]
	v_pk_mul_f32 v[16:17], v[16:17], v[16:17]
	v_pk_mul_f32 v[18:19], v[18:19], v[18:19]
	v_pk_mul_f32 v[20:21], v[20:21], v[20:21]
	v_and_b32_sdwa v46, v14, v59 dst_sel:DWORD dst_unused:UNUSED_PAD src0_sel:WORD_1 src1_sel:DWORD
	v_and_b32_sdwa v47, v15, v59 dst_sel:DWORD dst_unused:UNUSED_PAD src0_sel:WORD_1 src1_sel:DWORD
	v_and_b32_sdwa v48, v16, v59 dst_sel:DWORD dst_unused:UNUSED_PAD src0_sel:WORD_1 src1_sel:DWORD
	v_and_b32_sdwa v49, v17, v59 dst_sel:DWORD dst_unused:UNUSED_PAD src0_sel:WORD_1 src1_sel:DWORD
	v_and_b32_sdwa v50, v18, v59 dst_sel:DWORD dst_unused:UNUSED_PAD src0_sel:WORD_1 src1_sel:DWORD
	v_and_b32_sdwa v51, v19, v59 dst_sel:DWORD dst_unused:UNUSED_PAD src0_sel:WORD_1 src1_sel:DWORD
	v_and_b32_sdwa v52, v20, v59 dst_sel:DWORD dst_unused:UNUSED_PAD src0_sel:WORD_1 src1_sel:DWORD
	v_and_b32_sdwa v53, v21, v59 dst_sel:DWORD dst_unused:UNUSED_PAD src0_sel:WORD_1 src1_sel:DWORD
	v_add3_u32 v14, v14, v46, s24
	v_add3_u32 v15, v15, v47, s24
	v_add3_u32 v16, v16, v48, s24
	v_add3_u32 v17, v17, v49, s24
	v_add3_u32 v18, v18, v50, s24
	v_add3_u32 v19, v19, v51, s24
	v_add3_u32 v20, v20, v52, s24
	v_add3_u32 v21, v21, v53, s24
	v_and_b32_e32 v15, 0xffff0000, v15
	v_and_b32_e32 v17, 0xffff0000, v17
	v_and_b32_e32 v19, 0xffff0000, v19
	v_and_b32_e32 v21, 0xffff0000, v21
	v_or_b32_sdwa v60, v15, v14 dst_sel:DWORD dst_unused:UNUSED_PAD src0_sel:DWORD src1_sel:WORD_1
	v_or_b32_sdwa v61, v17, v16 dst_sel:DWORD dst_unused:UNUSED_PAD src0_sel:DWORD src1_sel:WORD_1
	v_or_b32_sdwa v62, v19, v18 dst_sel:DWORD dst_unused:UNUSED_PAD src0_sel:DWORD src1_sel:WORD_1
	v_or_b32_sdwa v63, v21, v20 dst_sel:DWORD dst_unused:UNUSED_PAD src0_sel:DWORD src1_sel:WORD_1
	global_store_dwordx4 v57, v[60:63], s[56:57]
	v_add_u32_e32 v55, 0xc180, v103
	ds_read2_b32 v[30:31], v55 offset0:0 offset1:1
	ds_read2_b32 v[32:33], v55 offset0:2 offset1:3
	ds_read2_b32 v[34:35], v55 offset0:4 offset1:5
	ds_read2_b32 v[36:37], v55 offset0:6 offset1:7
	v_add_u32_e32 v56, 0xe1c0, v103
	ds_read2_b32 v[38:39], v56 offset0:0 offset1:1
	ds_read2_b32 v[40:41], v56 offset0:2 offset1:3
	ds_read2_b32 v[42:43], v56 offset0:4 offset1:5
	ds_read2_b32 v[44:45], v56 offset0:6 offset1:7
	s_waitcnt vmcnt(7) lgkmcnt(8)
	v_fmamk_f32 v54, v10, 0x3a800000, v13
	v_rsq_f32_e32 v54, v54
	v_add_u32_e32 v58, 0xa0000, v4
	v_mul_f32_e32 v22, v22, v54
	v_mul_f32_e32 v23, v23, v54
	v_mul_f32_e32 v24, v24, v54
	v_mul_f32_e32 v25, v25, v54
	v_mul_f32_e32 v26, v26, v54
	v_mul_f32_e32 v27, v27, v54
	v_mul_f32_e32 v28, v28, v54
	v_mul_f32_e32 v29, v29, v54
	v_max_f32_e32 v22, 0, v22
	v_max_f32_e32 v23, 0, v23
	v_max_f32_e32 v24, 0, v24
	v_max_f32_e32 v25, 0, v25
	v_max_f32_e32 v26, 0, v26
	v_max_f32_e32 v27, 0, v27
	v_max_f32_e32 v28, 0, v28
	v_max_f32_e32 v29, 0, v29
	v_pk_mul_f32 v[22:23], v[22:23], v[22:23]
	v_pk_mul_f32 v[24:25], v[24:25], v[24:25]
	v_pk_mul_f32 v[26:27], v[26:27], v[26:27]
	v_pk_mul_f32 v[28:29], v[28:29], v[28:29]
	v_and_b32_sdwa v46, v22, v59 dst_sel:DWORD dst_unused:UNUSED_PAD src0_sel:WORD_1 src1_sel:DWORD
	v_and_b32_sdwa v47, v23, v59 dst_sel:DWORD dst_unused:UNUSED_PAD src0_sel:WORD_1 src1_sel:DWORD
	v_and_b32_sdwa v48, v24, v59 dst_sel:DWORD dst_unused:UNUSED_PAD src0_sel:WORD_1 src1_sel:DWORD
	v_and_b32_sdwa v49, v25, v59 dst_sel:DWORD dst_unused:UNUSED_PAD src0_sel:WORD_1 src1_sel:DWORD
	v_and_b32_sdwa v50, v26, v59 dst_sel:DWORD dst_unused:UNUSED_PAD src0_sel:WORD_1 src1_sel:DWORD
	v_and_b32_sdwa v51, v27, v59 dst_sel:DWORD dst_unused:UNUSED_PAD src0_sel:WORD_1 src1_sel:DWORD
	v_and_b32_sdwa v52, v28, v59 dst_sel:DWORD dst_unused:UNUSED_PAD src0_sel:WORD_1 src1_sel:DWORD
	v_and_b32_sdwa v53, v29, v59 dst_sel:DWORD dst_unused:UNUSED_PAD src0_sel:WORD_1 src1_sel:DWORD
	v_add3_u32 v22, v22, v46, s24
	v_add3_u32 v23, v23, v47, s24
	v_add3_u32 v24, v24, v48, s24
	v_add3_u32 v25, v25, v49, s24
	v_add3_u32 v26, v26, v50, s24
	v_add3_u32 v27, v27, v51, s24
	v_add3_u32 v28, v28, v52, s24
	v_add3_u32 v29, v29, v53, s24
	v_and_b32_e32 v23, 0xffff0000, v23
	v_and_b32_e32 v25, 0xffff0000, v25
	v_and_b32_e32 v27, 0xffff0000, v27
	v_and_b32_e32 v29, 0xffff0000, v29
	v_or_b32_sdwa v76, v23, v22 dst_sel:DWORD dst_unused:UNUSED_PAD src0_sel:DWORD src1_sel:WORD_1
	v_or_b32_sdwa v77, v25, v24 dst_sel:DWORD dst_unused:UNUSED_PAD src0_sel:DWORD src1_sel:WORD_1
	v_or_b32_sdwa v78, v27, v26 dst_sel:DWORD dst_unused:UNUSED_PAD src0_sel:DWORD src1_sel:WORD_1
	v_or_b32_sdwa v79, v29, v28 dst_sel:DWORD dst_unused:UNUSED_PAD src0_sel:DWORD src1_sel:WORD_1
	global_store_dwordx4 v58, v[76:79], s[56:57]
	s_waitcnt vmcnt(7) lgkmcnt(4)
	v_fmamk_f32 v54, v11, 0x3a800000, v13
	v_rsq_f32_e32 v54, v54
	v_add_u32_e32 v57, 0xc0000, v4
	v_mul_f32_e32 v30, v30, v54
	v_mul_f32_e32 v31, v31, v54
	v_mul_f32_e32 v32, v32, v54
	v_mul_f32_e32 v33, v33, v54
	v_mul_f32_e32 v34, v34, v54
	v_mul_f32_e32 v35, v35, v54
	v_mul_f32_e32 v36, v36, v54
	v_mul_f32_e32 v37, v37, v54
	v_max_f32_e32 v30, 0, v30
	v_max_f32_e32 v31, 0, v31
	v_max_f32_e32 v32, 0, v32
	v_max_f32_e32 v33, 0, v33
	v_max_f32_e32 v34, 0, v34
	v_max_f32_e32 v35, 0, v35
	v_max_f32_e32 v36, 0, v36
	v_max_f32_e32 v37, 0, v37
	v_pk_mul_f32 v[30:31], v[30:31], v[30:31]
	v_pk_mul_f32 v[32:33], v[32:33], v[32:33]
	v_pk_mul_f32 v[34:35], v[34:35], v[34:35]
	v_pk_mul_f32 v[36:37], v[36:37], v[36:37]
	v_and_b32_sdwa v46, v30, v59 dst_sel:DWORD dst_unused:UNUSED_PAD src0_sel:WORD_1 src1_sel:DWORD
	v_and_b32_sdwa v47, v31, v59 dst_sel:DWORD dst_unused:UNUSED_PAD src0_sel:WORD_1 src1_sel:DWORD
	v_and_b32_sdwa v48, v32, v59 dst_sel:DWORD dst_unused:UNUSED_PAD src0_sel:WORD_1 src1_sel:DWORD
	v_and_b32_sdwa v49, v33, v59 dst_sel:DWORD dst_unused:UNUSED_PAD src0_sel:WORD_1 src1_sel:DWORD
	v_and_b32_sdwa v50, v34, v59 dst_sel:DWORD dst_unused:UNUSED_PAD src0_sel:WORD_1 src1_sel:DWORD
	v_and_b32_sdwa v51, v35, v59 dst_sel:DWORD dst_unused:UNUSED_PAD src0_sel:WORD_1 src1_sel:DWORD
	v_and_b32_sdwa v52, v36, v59 dst_sel:DWORD dst_unused:UNUSED_PAD src0_sel:WORD_1 src1_sel:DWORD
	v_and_b32_sdwa v53, v37, v59 dst_sel:DWORD dst_unused:UNUSED_PAD src0_sel:WORD_1 src1_sel:DWORD
	v_add3_u32 v30, v30, v46, s24
	v_add3_u32 v31, v31, v47, s24
	v_add3_u32 v32, v32, v48, s24
	v_add3_u32 v33, v33, v49, s24
	v_add3_u32 v34, v34, v50, s24
	v_add3_u32 v35, v35, v51, s24
	v_add3_u32 v36, v36, v52, s24
	v_add3_u32 v37, v37, v53, s24
	v_and_b32_e32 v31, 0xffff0000, v31
	v_and_b32_e32 v33, 0xffff0000, v33
	v_and_b32_e32 v35, 0xffff0000, v35
	v_and_b32_e32 v37, 0xffff0000, v37
	v_or_b32_sdwa v60, v31, v30 dst_sel:DWORD dst_unused:UNUSED_PAD src0_sel:DWORD src1_sel:WORD_1
	v_or_b32_sdwa v61, v33, v32 dst_sel:DWORD dst_unused:UNUSED_PAD src0_sel:DWORD src1_sel:WORD_1
	v_or_b32_sdwa v62, v35, v34 dst_sel:DWORD dst_unused:UNUSED_PAD src0_sel:DWORD src1_sel:WORD_1
	v_or_b32_sdwa v63, v37, v36 dst_sel:DWORD dst_unused:UNUSED_PAD src0_sel:DWORD src1_sel:WORD_1
	global_store_dwordx4 v57, v[60:63], s[56:57]
	s_waitcnt vmcnt(7) lgkmcnt(0)
	v_fmamk_f32 v54, v12, 0x3a800000, v13
	v_rsq_f32_e32 v54, v54
	v_add_u32_e32 v58, 0xe0000, v4
	v_mul_f32_e32 v38, v38, v54
	v_mul_f32_e32 v39, v39, v54
	v_mul_f32_e32 v40, v40, v54
	v_mul_f32_e32 v41, v41, v54
	v_mul_f32_e32 v42, v42, v54
	v_mul_f32_e32 v43, v43, v54
	v_mul_f32_e32 v44, v44, v54
	v_mul_f32_e32 v45, v45, v54
	v_max_f32_e32 v38, 0, v38
	v_max_f32_e32 v39, 0, v39
	v_max_f32_e32 v40, 0, v40
	v_max_f32_e32 v41, 0, v41
	v_max_f32_e32 v42, 0, v42
	v_max_f32_e32 v43, 0, v43
	v_max_f32_e32 v44, 0, v44
	v_max_f32_e32 v45, 0, v45
	v_pk_mul_f32 v[38:39], v[38:39], v[38:39]
	v_pk_mul_f32 v[40:41], v[40:41], v[40:41]
	v_pk_mul_f32 v[42:43], v[42:43], v[42:43]
	v_pk_mul_f32 v[44:45], v[44:45], v[44:45]
	v_and_b32_sdwa v46, v38, v59 dst_sel:DWORD dst_unused:UNUSED_PAD src0_sel:WORD_1 src1_sel:DWORD
	v_and_b32_sdwa v47, v39, v59 dst_sel:DWORD dst_unused:UNUSED_PAD src0_sel:WORD_1 src1_sel:DWORD
	v_and_b32_sdwa v48, v40, v59 dst_sel:DWORD dst_unused:UNUSED_PAD src0_sel:WORD_1 src1_sel:DWORD
	v_and_b32_sdwa v49, v41, v59 dst_sel:DWORD dst_unused:UNUSED_PAD src0_sel:WORD_1 src1_sel:DWORD
	v_and_b32_sdwa v50, v42, v59 dst_sel:DWORD dst_unused:UNUSED_PAD src0_sel:WORD_1 src1_sel:DWORD
	v_and_b32_sdwa v51, v43, v59 dst_sel:DWORD dst_unused:UNUSED_PAD src0_sel:WORD_1 src1_sel:DWORD
	v_and_b32_sdwa v52, v44, v59 dst_sel:DWORD dst_unused:UNUSED_PAD src0_sel:WORD_1 src1_sel:DWORD
	v_and_b32_sdwa v53, v45, v59 dst_sel:DWORD dst_unused:UNUSED_PAD src0_sel:WORD_1 src1_sel:DWORD
	v_add3_u32 v38, v38, v46, s24
	v_add3_u32 v39, v39, v47, s24
	v_add3_u32 v40, v40, v48, s24
	v_add3_u32 v41, v41, v49, s24
	v_add3_u32 v42, v42, v50, s24
	v_add3_u32 v43, v43, v51, s24
	v_add3_u32 v44, v44, v52, s24
	v_add3_u32 v45, v45, v53, s24
	v_and_b32_e32 v39, 0xffff0000, v39
	v_and_b32_e32 v41, 0xffff0000, v41
	v_and_b32_e32 v43, 0xffff0000, v43
	v_and_b32_e32 v45, 0xffff0000, v45
	v_or_b32_sdwa v76, v39, v38 dst_sel:DWORD dst_unused:UNUSED_PAD src0_sel:DWORD src1_sel:WORD_1
	v_or_b32_sdwa v77, v41, v40 dst_sel:DWORD dst_unused:UNUSED_PAD src0_sel:DWORD src1_sel:WORD_1
	v_or_b32_sdwa v78, v43, v42 dst_sel:DWORD dst_unused:UNUSED_PAD src0_sel:DWORD src1_sel:WORD_1
	v_or_b32_sdwa v79, v45, v44 dst_sel:DWORD dst_unused:UNUSED_PAD src0_sel:DWORD src1_sel:WORD_1
	global_store_dwordx4 v58, v[76:79], s[56:57]
	s_cmpk_lt_u32 s12, 0x400
	s_barrier
	s_cbranch_scc1 .LBB0_590
